# GEMM K-loops: removed the redundant s_setprio 0/1 pair inside each 32-MFMA segment
# baseline (speedup 1.0000x reference)
; #define PG8_STAGE(bufoff, gbase, voff) do { _Pragma("unroll") for (int _i = 0; _i < 2; ++_i) \
;         __builtin_amdgcn_global_load_lds((const unsigned*)((const char*)(gbase) + (voff)[_i]), (PG8_LAS unsigned*)(lds + (bufoff) + ldsw + _i * 8192), 16, 0, 0); } while (0)
; #define PG8_LDA(dst, b, h) do { _Pragma("unroll") for (int m = 0; m < 4; ++m) _Pragma("unroll") for (int k = 0; k < 2; ++k) dst[m][k] = *(const PG8_LAS bf16x8*)(lds + PG8_SA(b, h) + aoff + m * 2048 + k * 1024); } while (0)
; #define PG8_LDB(dst, b, h) do { _Pragma("unroll") for (int n = 0; n < 2; ++n) _Pragma("unroll") for (int k = 0; k < 2; ++k) dst[n][k] = *(const PG8_LAS bf16x8*)(lds + PG8_SB(b, h) + boff + n * 2048 + k * 1024); } while (0)
; #define PG8_MMA(ai, bj, At, Bt) do { __builtin_amdgcn_s_setprio(1); _Pragma("unroll") for (int m = 0; m < 4; ++m) _Pragma("unroll") for (int n = 0; n < 2; ++n) _Pragma("unroll") for (int k = 0; k < 2; ++k) \
;         acc[ai][bj][m][n] = __builtin_amdgcn_mfma_f32_16x16x32_bf16(Bt[n][k], At[m][k], acc[ai][bj][m][n], 0, 0, 0); __builtin_amdgcn_s_setprio(0); } while (0)
; #define PG8_WAIT_V(n) asm volatile("s_waitcnt vmcnt(" #n ")" ::: "memory")
; #define PG8_WAIT_L(n) asm volatile("s_waitcnt lgkmcnt(" #n ")" ::: "memory")
; #define PG8_BAR __builtin_amdgcn_s_barrier()
; #define PG8_SCHED __builtin_amdgcn_sched_barrier(0)
; template <class Epi, class Sched, bool ALIGN_EPI = false, bool SP2 = false>
; __device__ __forceinline__ void gemm_phase(PG8_LAS unsigned char* lds, const Gemm g, const Sched& S, const Epi& E) {
;     ...
;         for (int t = 0; t < nt; t += 2) {
;             const bool last = (t == nt - 2);
;             const char* a1 = cA + (size_t)(t + 1) * kstep;
;             const char* a2 = last ? nA : cA + (size_t)(t + 2) * kstep; const char* b2 = last ? nB : cB + (size_t)(t + 2) * kstep;
;             const char* a3 = a2 + kstep; const char* b3 = b2 + kstep;
;             if (last && has_next) S.a_ready(nxt);
;             if constexpr (SP2) {
;             PG8_LDB(B0, 0, 0); PG8_LDB(B1, 0, 1); PG8_SCHED; PG8_LDA(At, 0, 0); PG8_STAGE(PG8_SA(1, 1), a1 + hstep, voffA);
;             PG8_WAIT_V(8); PG8_WAIT_L(0); PG8_BAR; PG8_MMA(0, 0, At, B0); PG8_MMA(0, 1, At, B1); PG8_BAR; PG8_SCHED;
;             PG8_LDA(At, 0, 1); PG8_STAGE(PG8_SB(0, 0), b2, voffB); PG8_STAGE(PG8_SB(0, 1), b2 + hstep, voffB); PG8_STAGE(PG8_SA(0, 0), a2, voffA);
.LBB0_117:
	ds_read_b128 v[66:69], v220
	ds_read_b128 v[78:81], v220 offset:1024
	ds_read_b128 v[82:85], v220 offset:2048
	ds_read_b128 v[86:89], v220 offset:3072
	ds_read_b128 v[146:149], v221
	ds_read_b128 v[150:153], v221 offset:1024
	ds_read_b128 v[154:157], v221 offset:2048
	ds_read_b128 v[158:161], v221 offset:3072
	s_add_u32 s34, s12, 0xfff50080
	s_addc_u32 s35, s13, -1
	s_cmp_eq_u32 s86, 40
	s_cselect_b32 s61, s55, s35
	s_cselect_b32 s60, s54, s34
	s_cselect_b32 s59, s57, s85
	s_cselect_b32 s58, s56, s84
	v_lshl_add_u64 v[182:183], s[12:13], 0, v[190:191]
	s_add_i32 m0, s19, 0xc000
	ds_read_b128 v[162:165], v222
	ds_read_b128 v[166:169], v222 offset:1024
	ds_read_b128 v[170:173], v222 offset:2048
	ds_read_b128 v[174:177], v222 offset:3072
	ds_read_b128 v[178:181], v222 offset:4096
	ds_read_b128 v[198:201], v222 offset:5120
	ds_read_b128 v[202:205], v222 offset:6144
	ds_read_b128 v[206:209], v222 offset:7168
	global_load_lds_dwordx4 v[182:183], off
	v_lshl_add_u64 v[182:183], s[12:13], 0, v[192:193]
	s_add_i32 m0, s19, 0xe000
	s_nop 0
	global_load_lds_dwordx4 v[182:183], off
	s_waitcnt vmcnt(8)
	s_waitcnt lgkmcnt(0)
	s_barrier
	s_setprio 1
	s_waitcnt lgkmcnt(0)
	v_mfma_f32_16x16x32_bf16 v[142:145], v[66:69], v[162:165], v[142:145]
	v_mfma_f32_16x16x32_bf16 v[138:141], v[82:85], v[162:165], v[138:141]
	v_mfma_f32_16x16x32_bf16 v[130:133], v[66:69], v[170:173], v[130:133]
	v_mfma_f32_16x16x32_bf16 v[122:125], v[82:85], v[170:173], v[122:125]
	v_mfma_f32_16x16x32_bf16 v[110:113], v[66:69], v[178:181], v[110:113]
	v_mfma_f32_16x16x32_bf16 v[106:109], v[82:85], v[178:181], v[106:109]
	v_mfma_f32_16x16x32_bf16 v[98:101], v[66:69], v[202:205], v[98:101]
	v_mfma_f32_16x16x32_bf16 v[90:93], v[82:85], v[202:205], v[90:93]
	v_mfma_f32_16x16x32_bf16 v[142:145], v[78:81], v[166:169], v[142:145]
	v_mfma_f32_16x16x32_bf16 v[138:141], v[86:89], v[166:169], v[138:141]
	v_mfma_f32_16x16x32_bf16 v[130:133], v[78:81], v[174:177], v[130:133]
	v_mfma_f32_16x16x32_bf16 v[122:125], v[86:89], v[174:177], v[122:125]
	v_mfma_f32_16x16x32_bf16 v[110:113], v[78:81], v[198:201], v[110:113]
	v_mfma_f32_16x16x32_bf16 v[106:109], v[86:89], v[198:201], v[106:109]
	v_mfma_f32_16x16x32_bf16 v[98:101], v[78:81], v[206:209], v[98:101]
	v_mfma_f32_16x16x32_bf16 v[90:93], v[86:89], v[206:209], v[90:93]
	v_mfma_f32_16x16x32_bf16 v[134:137], v[146:149], v[162:165], v[134:137]
	v_mfma_f32_16x16x32_bf16 v[126:129], v[154:157], v[162:165], v[126:129]
	v_mfma_f32_16x16x32_bf16 v[118:121], v[146:149], v[170:173], v[118:121]
	v_mfma_f32_16x16x32_bf16 v[114:117], v[154:157], v[170:173], v[114:117]
	v_mfma_f32_16x16x32_bf16 v[102:105], v[146:149], v[178:181], v[102:105]
	v_mfma_f32_16x16x32_bf16 v[94:97], v[154:157], v[178:181], v[94:97]
	v_mfma_f32_16x16x32_bf16 v[74:77], v[146:149], v[202:205], v[74:77]
	v_mfma_f32_16x16x32_bf16 v[70:73], v[154:157], v[202:205], v[70:73]
	v_mfma_f32_16x16x32_bf16 v[134:137], v[150:153], v[166:169], v[134:137]
	v_mfma_f32_16x16x32_bf16 v[126:129], v[158:161], v[166:169], v[126:129]
	v_mfma_f32_16x16x32_bf16 v[118:121], v[150:153], v[174:177], v[118:121]
	v_mfma_f32_16x16x32_bf16 v[114:117], v[158:161], v[174:177], v[114:117]
	v_mfma_f32_16x16x32_bf16 v[102:105], v[150:153], v[198:201], v[102:105]
	v_mfma_f32_16x16x32_bf16 v[94:97], v[158:161], v[198:201], v[94:97]
	v_mfma_f32_16x16x32_bf16 v[74:77], v[150:153], v[206:209], v[74:77]
	v_mfma_f32_16x16x32_bf16 v[70:73], v[158:161], v[206:209], v[70:73]
	s_setprio 0
	s_barrier
	s_add_i32 s34, s73, s3
	v_lshl_add_u64 v[182:183], s[58:59], 0, v[184:185]
	s_mov_b32 m0, s34
	ds_read_b128 v[162:165], v222 offset:16384
	ds_read_b128 v[166:169], v222 offset:17408
	ds_read_b128 v[170:173], v222 offset:18432
	ds_read_b128 v[174:177], v222 offset:19456
	ds_read_b128 v[178:181], v222 offset:20480
	ds_read_b128 v[198:201], v222 offset:21504
	ds_read_b128 v[202:205], v222 offset:22528
	ds_read_b128 v[206:209], v222 offset:23552
	global_load_lds_dwordx4 v[182:183], off
	s_add_i32 m0, s34, 0x2000
	s_add_u32 s88, s58, 0xb0000
	v_lshl_add_u64 v[210:211], s[58:59], 0, v[186:187]
	s_addc_u32 s89, s59, 0
	s_add_i32 s34, s77, s3
	global_load_lds_dwordx4 v[210:211], off
	v_lshl_add_u64 v[212:213], s[88:89], 0, v[184:185]
	s_mov_b32 m0, s34
	v_lshl_add_u64 v[214:215], s[60:61], 0, v[186:187]
	global_load_lds_dwordx4 v[212:213], off
	v_lshl_add_u64 v[212:213], s[88:89], 0, v[186:187]
	s_add_i32 m0, s34, 0x2000
	s_nop 0
	global_load_lds_dwordx4 v[212:213], off
	v_lshl_add_u64 v[212:213], s[60:61], 0, v[184:185]
	s_mov_b32 m0, s19
	s_nop 0
	global_load_lds_dwordx4 v[212:213], off
	s_mov_b32 m0, s62
	s_nop 0
	global_load_lds_dwordx4 v[214:215], off
	s_waitcnt vmcnt(8)
	s_waitcnt lgkmcnt(0)
	s_barrier
; #define PG8_STAGE(bufoff, gbase, voff) do { _Pragma("unroll") for (int _i = 0; _i < 2; ++_i) \
;         __builtin_amdgcn_global_load_lds((const unsigned*)((const char*)(gbase) + (voff)[_i]), (PG8_LAS unsigned*)(lds + (bufoff) + ldsw + _i * 8192), 16, 0, 0); } while (0)
; #define PG8_LDA(dst, b, h) do { _Pragma("unroll") for (int m = 0; m < 4; ++m) _Pragma("unroll") for (int k = 0; k < 2; ++k) dst[m][k] = *(const PG8_LAS bf16x8*)(lds + PG8_SA(b, h) + aoff + m * 2048 + k * 1024); } while (0)
; #define PG8_LDB(dst, b, h) do { _Pragma("unroll") for (int n = 0; n < 2; ++n) _Pragma("unroll") for (int k = 0; k < 2; ++k) dst[n][k] = *(const PG8_LAS bf16x8*)(lds + PG8_SB(b, h) + boff + n * 2048 + k * 1024); } while (0)
; #define PG8_MMA(ai, bj, At, Bt) do { __builtin_amdgcn_s_setprio(1); _Pragma("unroll") for (int m = 0; m < 4; ++m) _Pragma("unroll") for (int n = 0; n < 2; ++n) _Pragma("unroll") for (int k = 0; k < 2; ++k) \
;         acc[ai][bj][m][n] = __builtin_amdgcn_mfma_f32_16x16x32_bf16(Bt[n][k], At[m][k], acc[ai][bj][m][n], 0, 0, 0); __builtin_amdgcn_s_setprio(0); } while (0)
; #define PG8_WAIT_V(n) asm volatile("s_waitcnt vmcnt(" #n ")" ::: "memory")
; #define PG8_WAIT_L(n) asm volatile("s_waitcnt lgkmcnt(" #n ")" ::: "memory")
; #define PG8_BAR __builtin_amdgcn_s_barrier()
; #define PG8_SCHED __builtin_amdgcn_sched_barrier(0)
; template <class Epi, class Sched, bool ALIGN_EPI = false, bool SP2 = false>
; __device__ __forceinline__ void gemm_phase(PG8_LAS unsigned char* lds, const Gemm g, const Sched& S, const Epi& E) {
;     ...
;             PG8_WAIT_V(8); PG8_WAIT_L(0); PG8_BAR; PG8_MMA(1, 0, At, B0); PG8_MMA(1, 1, At, B1); PG8_BAR; PG8_SCHED;
;             PG8_LDB(B0, 1, 0); PG8_LDB(B1, 1, 1); PG8_SCHED; PG8_LDA(At, 1, 0); PG8_STAGE(PG8_SA(0, 1), a2 + hstep, voffA);
;             PG8_WAIT_V(8); PG8_WAIT_L(0); PG8_BAR; PG8_MMA(0, 0, At, B0); PG8_MMA(0, 1, At, B1); PG8_BAR; PG8_SCHED;
	s_setprio 1
	s_waitcnt lgkmcnt(0)
	v_mfma_f32_16x16x32_bf16 v[62:65], v[66:69], v[162:165], v[62:65]
	v_mfma_f32_16x16x32_bf16 v[58:61], v[82:85], v[162:165], v[58:61]
	v_mfma_f32_16x16x32_bf16 v[50:53], v[66:69], v[170:173], v[50:53]
	v_mfma_f32_16x16x32_bf16 v[42:45], v[82:85], v[170:173], v[42:45]
	v_mfma_f32_16x16x32_bf16 v[30:33], v[66:69], v[178:181], v[30:33]
	v_mfma_f32_16x16x32_bf16 v[26:29], v[82:85], v[178:181], v[26:29]
	v_mfma_f32_16x16x32_bf16 v[18:21], v[66:69], v[202:205], v[18:21]
	v_mfma_f32_16x16x32_bf16 v[10:13], v[82:85], v[202:205], v[10:13]
	v_mfma_f32_16x16x32_bf16 v[62:65], v[78:81], v[166:169], v[62:65]
	v_mfma_f32_16x16x32_bf16 v[58:61], v[86:89], v[166:169], v[58:61]
	v_mfma_f32_16x16x32_bf16 v[50:53], v[78:81], v[174:177], v[50:53]
	v_mfma_f32_16x16x32_bf16 v[42:45], v[86:89], v[174:177], v[42:45]
	v_mfma_f32_16x16x32_bf16 v[30:33], v[78:81], v[198:201], v[30:33]
	v_mfma_f32_16x16x32_bf16 v[26:29], v[86:89], v[198:201], v[26:29]
	v_mfma_f32_16x16x32_bf16 v[18:21], v[78:81], v[206:209], v[18:21]
	v_mfma_f32_16x16x32_bf16 v[10:13], v[86:89], v[206:209], v[10:13]
	v_mfma_f32_16x16x32_bf16 v[54:57], v[146:149], v[162:165], v[54:57]
	v_mfma_f32_16x16x32_bf16 v[46:49], v[154:157], v[162:165], v[46:49]
	v_mfma_f32_16x16x32_bf16 v[38:41], v[146:149], v[170:173], v[38:41]
	v_mfma_f32_16x16x32_bf16 v[34:37], v[154:157], v[170:173], v[34:37]
	v_mfma_f32_16x16x32_bf16 v[22:25], v[146:149], v[178:181], v[22:25]
	v_mfma_f32_16x16x32_bf16 v[14:17], v[154:157], v[178:181], v[14:17]
	v_mfma_f32_16x16x32_bf16 v[6:9], v[146:149], v[202:205], v[6:9]
	v_mfma_f32_16x16x32_bf16 v[2:5], v[154:157], v[202:205], v[2:5]
	v_mfma_f32_16x16x32_bf16 v[54:57], v[150:153], v[166:169], v[54:57]
	v_mfma_f32_16x16x32_bf16 v[46:49], v[158:161], v[166:169], v[46:49]
	v_mfma_f32_16x16x32_bf16 v[38:41], v[150:153], v[174:177], v[38:41]
	v_mfma_f32_16x16x32_bf16 v[34:37], v[158:161], v[174:177], v[34:37]
	v_mfma_f32_16x16x32_bf16 v[22:25], v[150:153], v[198:201], v[22:25]
	v_mfma_f32_16x16x32_bf16 v[14:17], v[158:161], v[198:201], v[14:17]
	v_mfma_f32_16x16x32_bf16 v[6:9], v[150:153], v[206:209], v[6:9]
	v_mfma_f32_16x16x32_bf16 v[2:5], v[158:161], v[206:209], v[2:5]
	s_setprio 0
	s_barrier
	s_add_i32 s34, 0, 0x18000
	s_add_i32 s35, 0, 0x1c000
	v_add_u32_e32 v86, s34, v216
	v_add_u32_e32 v158, s35, v216
	ds_read_b128 v[66:69], v86
	ds_read_b128 v[78:81], v86 offset:1024
	ds_read_b128 v[82:85], v86 offset:2048
	ds_read_b128 v[86:89], v86 offset:3072
	ds_read_b128 v[146:149], v158
	ds_read_b128 v[150:153], v158 offset:1024
	ds_read_b128 v[154:157], v158 offset:2048
	ds_read_b128 v[158:161], v158 offset:3072
	s_add_u32 s60, s60, 0xb0000
	s_addc_u32 s61, s61, 0
	s_mov_b32 m0, s63
	v_lshl_add_u64 v[224:225], s[60:61], 0, v[184:185]
	ds_read_b128 v[162:165], v222 offset:32768
	ds_read_b128 v[166:169], v222 offset:33792
	ds_read_b128 v[170:173], v222 offset:34816
	ds_read_b128 v[174:177], v222 offset:35840
	ds_read_b128 v[178:181], v222 offset:36864
	ds_read_b128 v[198:201], v222 offset:37888
	ds_read_b128 v[202:205], v222 offset:38912
	ds_read_b128 v[206:209], v222 offset:39936
	global_load_lds_dwordx4 v[224:225], off
	v_lshl_add_u64 v[224:225], s[60:61], 0, v[186:187]
	s_mov_b32 m0, s64
	s_nop 0
	global_load_lds_dwordx4 v[224:225], off
	s_waitcnt vmcnt(8)
	s_waitcnt lgkmcnt(0)
	s_barrier
	s_setprio 1
	s_waitcnt lgkmcnt(0)
	v_mfma_f32_16x16x32_bf16 v[142:145], v[66:69], v[162:165], v[142:145]
	v_mfma_f32_16x16x32_bf16 v[138:141], v[82:85], v[162:165], v[138:141]
	v_mfma_f32_16x16x32_bf16 v[130:133], v[66:69], v[170:173], v[130:133]
	v_mfma_f32_16x16x32_bf16 v[122:125], v[82:85], v[170:173], v[122:125]
	v_mfma_f32_16x16x32_bf16 v[110:113], v[66:69], v[178:181], v[110:113]
	v_mfma_f32_16x16x32_bf16 v[106:109], v[82:85], v[178:181], v[106:109]
	v_mfma_f32_16x16x32_bf16 v[98:101], v[66:69], v[202:205], v[98:101]
	v_mfma_f32_16x16x32_bf16 v[90:93], v[82:85], v[202:205], v[90:93]
	v_mfma_f32_16x16x32_bf16 v[142:145], v[78:81], v[166:169], v[142:145]
	v_mfma_f32_16x16x32_bf16 v[138:141], v[86:89], v[166:169], v[138:141]
	v_mfma_f32_16x16x32_bf16 v[130:133], v[78:81], v[174:177], v[130:133]
	v_mfma_f32_16x16x32_bf16 v[122:125], v[86:89], v[174:177], v[122:125]
	v_mfma_f32_16x16x32_bf16 v[110:113], v[78:81], v[198:201], v[110:113]
	v_mfma_f32_16x16x32_bf16 v[106:109], v[86:89], v[198:201], v[106:109]
	v_mfma_f32_16x16x32_bf16 v[98:101], v[78:81], v[206:209], v[98:101]
	v_mfma_f32_16x16x32_bf16 v[90:93], v[86:89], v[206:209], v[90:93]
	v_mfma_f32_16x16x32_bf16 v[134:137], v[146:149], v[162:165], v[134:137]
	v_mfma_f32_16x16x32_bf16 v[126:129], v[154:157], v[162:165], v[126:129]
	v_mfma_f32_16x16x32_bf16 v[118:121], v[146:149], v[170:173], v[118:121]
	v_mfma_f32_16x16x32_bf16 v[114:117], v[154:157], v[170:173], v[114:117]
	v_mfma_f32_16x16x32_bf16 v[102:105], v[146:149], v[178:181], v[102:105]
	v_mfma_f32_16x16x32_bf16 v[94:97], v[154:157], v[178:181], v[94:97]
	v_mfma_f32_16x16x32_bf16 v[74:77], v[146:149], v[202:205], v[74:77]
	v_mfma_f32_16x16x32_bf16 v[70:73], v[154:157], v[202:205], v[70:73]
	v_mfma_f32_16x16x32_bf16 v[134:137], v[150:153], v[166:169], v[134:137]
	v_mfma_f32_16x16x32_bf16 v[126:129], v[158:161], v[166:169], v[126:129]
	v_mfma_f32_16x16x32_bf16 v[118:121], v[150:153], v[174:177], v[118:121]
	v_mfma_f32_16x16x32_bf16 v[114:117], v[158:161], v[174:177], v[114:117]
	v_mfma_f32_16x16x32_bf16 v[102:105], v[150:153], v[198:201], v[102:105]
	v_mfma_f32_16x16x32_bf16 v[94:97], v[158:161], v[198:201], v[94:97]
	v_mfma_f32_16x16x32_bf16 v[74:77], v[150:153], v[206:209], v[74:77]
	v_mfma_f32_16x16x32_bf16 v[70:73], v[158:161], v[206:209], v[70:73]
	s_setprio 0
	s_barrier
; #define PG8_STAGE(bufoff, gbase, voff) do { _Pragma("unroll") for (int _i = 0; _i < 2; ++_i) \
;         __builtin_amdgcn_global_load_lds((const unsigned*)((const char*)(gbase) + (voff)[_i]), (PG8_LAS unsigned*)(lds + (bufoff) + ldsw + _i * 8192), 16, 0, 0); } while (0)
; #define PG8_LDA(dst, b, h) do { _Pragma("unroll") for (int m = 0; m < 4; ++m) _Pragma("unroll") for (int k = 0; k < 2; ++k) dst[m][k] = *(const PG8_LAS bf16x8*)(lds + PG8_SA(b, h) + aoff + m * 2048 + k * 1024); } while (0)
; #define PG8_MMA(ai, bj, At, Bt) do { __builtin_amdgcn_s_setprio(1); _Pragma("unroll") for (int m = 0; m < 4; ++m) _Pragma("unroll") for (int n = 0; n < 2; ++n) _Pragma("unroll") for (int k = 0; k < 2; ++k) \
;         acc[ai][bj][m][n] = __builtin_amdgcn_mfma_f32_16x16x32_bf16(Bt[n][k], At[m][k], acc[ai][bj][m][n], 0, 0, 0); __builtin_amdgcn_s_setprio(0); } while (0)
; #define PG8_WAIT_V(n) asm volatile("s_waitcnt vmcnt(" #n ")" ::: "memory")
; #define PG8_WAIT_L(n) asm volatile("s_waitcnt lgkmcnt(" #n ")" ::: "memory")
; #define PG8_BAR __builtin_amdgcn_s_barrier()
; #define PG8_SCHED __builtin_amdgcn_sched_barrier(0)
; template <class Epi, class Sched, bool ALIGN_EPI = false, bool SP2 = false>
; __device__ __forceinline__ void gemm_phase(PG8_LAS unsigned char* lds, const Gemm g, const Sched& S, const Epi& E) {
;     ...
;             PG8_LDA(At, 1, 1); PG8_STAGE(PG8_SB(1, 0), b3, voffB); PG8_STAGE(PG8_SB(1, 1), b3 + hstep, voffB); PG8_STAGE(PG8_SA(1, 0), a3, voffA);
;             PG8_WAIT_V(8); PG8_WAIT_L(0); PG8_BAR; PG8_MMA(1, 0, At, B0); PG8_MMA(1, 1, At, B1); PG8_BAR; PG8_SCHED;
;     ...
;         if constexpr (ALIGN_EPI) { if (wr == 0) PG8_BAR; }
	s_add_i32 s34, s34, s3
	v_lshl_add_u64 v[182:183], v[182:183], 0, s[48:49]
	s_mov_b32 m0, s34
	ds_read_b128 v[162:165], v222 offset:49152
	ds_read_b128 v[166:169], v222 offset:50176
	ds_read_b128 v[170:173], v222 offset:51200
	ds_read_b128 v[174:177], v222 offset:52224
	ds_read_b128 v[178:181], v222 offset:53248
	ds_read_b128 v[198:201], v222 offset:54272
	ds_read_b128 v[202:205], v222 offset:55296
	ds_read_b128 v[206:209], v222 offset:56320
	global_load_lds_dwordx4 v[182:183], off
	s_add_i32 m0, s34, 0x2000
	s_add_u32 s58, s58, 0xb0080
	v_lshl_add_u64 v[182:183], v[210:211], 0, s[48:49]
	s_addc_u32 s59, s59, 0
	s_add_i32 s34, s35, s3
	global_load_lds_dwordx4 v[182:183], off
	v_lshl_add_u64 v[182:183], s[58:59], 0, v[184:185]
	s_mov_b32 m0, s34
	s_nop 0
	global_load_lds_dwordx4 v[182:183], off
	v_lshl_add_u64 v[182:183], s[58:59], 0, v[186:187]
	s_add_i32 m0, s34, 0x2000
	s_nop 0
	global_load_lds_dwordx4 v[182:183], off
	v_lshl_add_u64 v[182:183], v[212:213], 0, s[48:49]
	s_mov_b32 m0, s67
	s_nop 0
	global_load_lds_dwordx4 v[182:183], off
	v_lshl_add_u64 v[182:183], v[214:215], 0, s[48:49]
	s_mov_b32 m0, s68
	s_nop 0
	global_load_lds_dwordx4 v[182:183], off
	s_waitcnt vmcnt(8)
	s_waitcnt lgkmcnt(0)
	s_barrier
	s_setprio 1
	s_waitcnt lgkmcnt(0)
	v_mfma_f32_16x16x32_bf16 v[62:65], v[66:69], v[162:165], v[62:65]
	v_mfma_f32_16x16x32_bf16 v[58:61], v[82:85], v[162:165], v[58:61]
	v_mfma_f32_16x16x32_bf16 v[50:53], v[66:69], v[170:173], v[50:53]
	v_mfma_f32_16x16x32_bf16 v[42:45], v[82:85], v[170:173], v[42:45]
	v_mfma_f32_16x16x32_bf16 v[30:33], v[66:69], v[178:181], v[30:33]
	v_mfma_f32_16x16x32_bf16 v[26:29], v[82:85], v[178:181], v[26:29]
	v_mfma_f32_16x16x32_bf16 v[18:21], v[66:69], v[202:205], v[18:21]
	v_mfma_f32_16x16x32_bf16 v[10:13], v[82:85], v[202:205], v[10:13]
	v_mfma_f32_16x16x32_bf16 v[62:65], v[78:81], v[166:169], v[62:65]
	v_mfma_f32_16x16x32_bf16 v[58:61], v[86:89], v[166:169], v[58:61]
	v_mfma_f32_16x16x32_bf16 v[50:53], v[78:81], v[174:177], v[50:53]
	v_mfma_f32_16x16x32_bf16 v[42:45], v[86:89], v[174:177], v[42:45]
	v_mfma_f32_16x16x32_bf16 v[30:33], v[78:81], v[198:201], v[30:33]
	v_mfma_f32_16x16x32_bf16 v[26:29], v[86:89], v[198:201], v[26:29]
	v_mfma_f32_16x16x32_bf16 v[18:21], v[78:81], v[206:209], v[18:21]
	v_mfma_f32_16x16x32_bf16 v[10:13], v[86:89], v[206:209], v[10:13]
	v_mfma_f32_16x16x32_bf16 v[54:57], v[146:149], v[162:165], v[54:57]
	v_mfma_f32_16x16x32_bf16 v[46:49], v[154:157], v[162:165], v[46:49]
	v_mfma_f32_16x16x32_bf16 v[38:41], v[146:149], v[170:173], v[38:41]
	v_mfma_f32_16x16x32_bf16 v[34:37], v[154:157], v[170:173], v[34:37]
	v_mfma_f32_16x16x32_bf16 v[22:25], v[146:149], v[178:181], v[22:25]
	v_mfma_f32_16x16x32_bf16 v[14:17], v[154:157], v[178:181], v[14:17]
	v_mfma_f32_16x16x32_bf16 v[6:9], v[146:149], v[202:205], v[6:9]
	v_mfma_f32_16x16x32_bf16 v[2:5], v[154:157], v[202:205], v[2:5]
	v_mfma_f32_16x16x32_bf16 v[54:57], v[150:153], v[166:169], v[54:57]
	v_mfma_f32_16x16x32_bf16 v[46:49], v[158:161], v[166:169], v[46:49]
	v_mfma_f32_16x16x32_bf16 v[38:41], v[150:153], v[174:177], v[38:41]
	v_mfma_f32_16x16x32_bf16 v[34:37], v[158:161], v[174:177], v[34:37]
	v_mfma_f32_16x16x32_bf16 v[22:25], v[150:153], v[198:201], v[22:25]
	v_mfma_f32_16x16x32_bf16 v[14:17], v[158:161], v[198:201], v[14:17]
	v_mfma_f32_16x16x32_bf16 v[6:9], v[150:153], v[206:209], v[6:9]
	v_mfma_f32_16x16x32_bf16 v[2:5], v[158:161], v[206:209], v[2:5]
	s_setprio 0
	s_barrier
	s_add_i32 s86, s86, 2
	s_add_u32 s12, s12, 0x100
	s_addc_u32 s13, s13, 0
	s_add_u32 s84, s84, 0x100
	s_addc_u32 s85, s85, 0
	s_cmp_gt_u32 s86, 41
	s_cbranch_scc0 .LBB0_117
	s_and_b64 vcc, exec, s[50:51]
	s_cbranch_vccz .LBB0_120
	s_barrier

; #define PG8_STAGE(bufoff, gbase, voff) do { _Pragma("unroll") for (int _i = 0; _i < 2; ++_i) \
;         __builtin_amdgcn_global_load_lds((const unsigned*)((const char*)(gbase) + (voff)[_i]), (PG8_LAS unsigned*)(lds + (bufoff) + ldsw + _i * 8192), 16, 0, 0); } while (0)
; #define PG8_LDA(dst, b, h) do { _Pragma("unroll") for (int m = 0; m < 4; ++m) _Pragma("unroll") for (int k = 0; k < 2; ++k) dst[m][k] = *(const PG8_LAS bf16x8*)(lds + PG8_SA(b, h) + aoff + m * 2048 + k * 1024); } while (0)
; #define PG8_LDB(dst, b, h) do { _Pragma("unroll") for (int n = 0; n < 2; ++n) _Pragma("unroll") for (int k = 0; k < 2; ++k) dst[n][k] = *(const PG8_LAS bf16x8*)(lds + PG8_SB(b, h) + boff + n * 2048 + k * 1024); } while (0)
; #define PG8_MMA(ai, bj, At, Bt) do { __builtin_amdgcn_s_setprio(1); _Pragma("unroll") for (int m = 0; m < 4; ++m) _Pragma("unroll") for (int n = 0; n < 2; ++n) _Pragma("unroll") for (int k = 0; k < 2; ++k) \
;         acc[ai][bj][m][n] = __builtin_amdgcn_mfma_f32_16x16x32_bf16(Bt[n][k], At[m][k], acc[ai][bj][m][n], 0, 0, 0); __builtin_amdgcn_s_setprio(0); } while (0)
; #define PG8_WAIT_V(n) asm volatile("s_waitcnt vmcnt(" #n ")" ::: "memory")
; #define PG8_WAIT_L(n) asm volatile("s_waitcnt lgkmcnt(" #n ")" ::: "memory")
; #define PG8_BAR __builtin_amdgcn_s_barrier()
; #define PG8_SCHED __builtin_amdgcn_sched_barrier(0)
; template <class Epi, class Sched, bool ALIGN_EPI = false, bool SP2 = false>
; __device__ __forceinline__ void gemm_phase(PG8_LAS unsigned char* lds, const Gemm g, const Sched& S, const Epi& E) {
;     ...
;         for (int t = 0; t < nt; t += 2) {
;             const bool last = (t == nt - 2);
;             const char* a1 = cA + (size_t)(t + 1) * kstep;
;             const char* a2 = last ? nA : cA + (size_t)(t + 2) * kstep; const char* b2 = last ? nB : cB + (size_t)(t + 2) * kstep;
;             const char* a3 = a2 + kstep; const char* b3 = b2 + kstep;
;             if (last && has_next) S.a_ready(nxt);
;             if constexpr (SP2) {
;             PG8_LDB(B0, 0, 0); PG8_LDB(B1, 0, 1); PG8_SCHED; PG8_LDA(At, 0, 0); PG8_STAGE(PG8_SA(1, 1), a1 + hstep, voffA);
;             PG8_WAIT_V(8); PG8_WAIT_L(0); PG8_BAR; PG8_MMA(0, 0, At, B0); PG8_MMA(0, 1, At, B1); PG8_BAR; PG8_SCHED;
;             PG8_LDA(At, 0, 1); PG8_STAGE(PG8_SB(0, 0), b2, voffB); PG8_STAGE(PG8_SB(0, 1), b2 + hstep, voffB); PG8_STAGE(PG8_SA(0, 0), a2, voffA);
.LBB0_228:
	ds_read_b128 v[66:69], v220
	ds_read_b128 v[78:81], v220 offset:1024
	ds_read_b128 v[82:85], v220 offset:2048
	ds_read_b128 v[86:89], v220 offset:3072
	ds_read_b128 v[146:149], v221
	ds_read_b128 v[150:153], v221 offset:1024
	ds_read_b128 v[154:157], v221 offset:2048
	ds_read_b128 v[158:161], v221 offset:3072
	s_add_u32 s34, s12, 0xfff50080
	s_addc_u32 s35, s13, -1
	s_cmp_eq_u32 s84, 40
	s_cselect_b32 s59, s43, s35
	s_cselect_b32 s58, s42, s34
	s_cselect_b32 s57, s55, s83
	s_cselect_b32 s56, s54, s82
	v_lshl_add_u64 v[182:183], s[12:13], 0, v[190:191]
	s_add_i32 m0, s19, 0xc000
	ds_read_b128 v[162:165], v222
	ds_read_b128 v[166:169], v222 offset:1024
	ds_read_b128 v[170:173], v222 offset:2048
	ds_read_b128 v[174:177], v222 offset:3072
	ds_read_b128 v[178:181], v222 offset:4096
	ds_read_b128 v[198:201], v222 offset:5120
	ds_read_b128 v[202:205], v222 offset:6144
	ds_read_b128 v[206:209], v222 offset:7168
	global_load_lds_dwordx4 v[182:183], off
	v_lshl_add_u64 v[182:183], s[12:13], 0, v[192:193]
	s_add_i32 m0, s19, 0xe000
	s_nop 0
	global_load_lds_dwordx4 v[182:183], off
	s_waitcnt vmcnt(8)
	s_waitcnt lgkmcnt(0)
	s_barrier
	s_setprio 1
	s_waitcnt lgkmcnt(0)
	v_mfma_f32_16x16x32_bf16 v[142:145], v[66:69], v[162:165], v[142:145]
	v_mfma_f32_16x16x32_bf16 v[138:141], v[82:85], v[162:165], v[138:141]
	v_mfma_f32_16x16x32_bf16 v[130:133], v[66:69], v[170:173], v[130:133]
	v_mfma_f32_16x16x32_bf16 v[122:125], v[82:85], v[170:173], v[122:125]
	v_mfma_f32_16x16x32_bf16 v[110:113], v[66:69], v[178:181], v[110:113]
	v_mfma_f32_16x16x32_bf16 v[106:109], v[82:85], v[178:181], v[106:109]
	v_mfma_f32_16x16x32_bf16 v[98:101], v[66:69], v[202:205], v[98:101]
	v_mfma_f32_16x16x32_bf16 v[90:93], v[82:85], v[202:205], v[90:93]
	v_mfma_f32_16x16x32_bf16 v[142:145], v[78:81], v[166:169], v[142:145]
	v_mfma_f32_16x16x32_bf16 v[138:141], v[86:89], v[166:169], v[138:141]
	v_mfma_f32_16x16x32_bf16 v[130:133], v[78:81], v[174:177], v[130:133]
	v_mfma_f32_16x16x32_bf16 v[122:125], v[86:89], v[174:177], v[122:125]
	v_mfma_f32_16x16x32_bf16 v[110:113], v[78:81], v[198:201], v[110:113]
	v_mfma_f32_16x16x32_bf16 v[106:109], v[86:89], v[198:201], v[106:109]
	v_mfma_f32_16x16x32_bf16 v[98:101], v[78:81], v[206:209], v[98:101]
	v_mfma_f32_16x16x32_bf16 v[90:93], v[86:89], v[206:209], v[90:93]
	v_mfma_f32_16x16x32_bf16 v[134:137], v[146:149], v[162:165], v[134:137]
	v_mfma_f32_16x16x32_bf16 v[126:129], v[154:157], v[162:165], v[126:129]
	v_mfma_f32_16x16x32_bf16 v[118:121], v[146:149], v[170:173], v[118:121]
	v_mfma_f32_16x16x32_bf16 v[114:117], v[154:157], v[170:173], v[114:117]
	v_mfma_f32_16x16x32_bf16 v[102:105], v[146:149], v[178:181], v[102:105]
	v_mfma_f32_16x16x32_bf16 v[94:97], v[154:157], v[178:181], v[94:97]
	v_mfma_f32_16x16x32_bf16 v[74:77], v[146:149], v[202:205], v[74:77]
	v_mfma_f32_16x16x32_bf16 v[70:73], v[154:157], v[202:205], v[70:73]
	v_mfma_f32_16x16x32_bf16 v[134:137], v[150:153], v[166:169], v[134:137]
	v_mfma_f32_16x16x32_bf16 v[126:129], v[158:161], v[166:169], v[126:129]
	v_mfma_f32_16x16x32_bf16 v[118:121], v[150:153], v[174:177], v[118:121]
	v_mfma_f32_16x16x32_bf16 v[114:117], v[158:161], v[174:177], v[114:117]
	v_mfma_f32_16x16x32_bf16 v[102:105], v[150:153], v[198:201], v[102:105]
	v_mfma_f32_16x16x32_bf16 v[94:97], v[158:161], v[198:201], v[94:97]
	v_mfma_f32_16x16x32_bf16 v[74:77], v[150:153], v[206:209], v[74:77]
	v_mfma_f32_16x16x32_bf16 v[70:73], v[158:161], v[206:209], v[70:73]
	s_setprio 0
	s_barrier
	s_add_i32 s34, s71, s3
	v_lshl_add_u64 v[182:183], s[56:57], 0, v[184:185]
	s_mov_b32 m0, s34
	ds_read_b128 v[162:165], v222 offset:16384
	ds_read_b128 v[166:169], v222 offset:17408
	ds_read_b128 v[170:173], v222 offset:18432
	ds_read_b128 v[174:177], v222 offset:19456
	ds_read_b128 v[178:181], v222 offset:20480
	ds_read_b128 v[198:201], v222 offset:21504
	ds_read_b128 v[202:205], v222 offset:22528
	ds_read_b128 v[206:209], v222 offset:23552
	global_load_lds_dwordx4 v[182:183], off
	s_add_i32 m0, s34, 0x2000
	s_add_u32 s86, s56, 0xb0000
	v_lshl_add_u64 v[210:211], s[56:57], 0, v[186:187]
	s_addc_u32 s87, s57, 0
	s_add_i32 s34, s72, s3
	global_load_lds_dwordx4 v[210:211], off
	v_lshl_add_u64 v[212:213], s[86:87], 0, v[184:185]
	s_mov_b32 m0, s34
	v_lshl_add_u64 v[214:215], s[58:59], 0, v[186:187]
	global_load_lds_dwordx4 v[212:213], off
	v_lshl_add_u64 v[212:213], s[86:87], 0, v[186:187]
	s_add_i32 m0, s34, 0x2000
	s_nop 0
	global_load_lds_dwordx4 v[212:213], off
	v_lshl_add_u64 v[212:213], s[58:59], 0, v[184:185]
	s_mov_b32 m0, s19
	s_nop 0
	global_load_lds_dwordx4 v[212:213], off
	s_mov_b32 m0, s60
	s_nop 0
	global_load_lds_dwordx4 v[214:215], off
	s_waitcnt vmcnt(8)
	s_waitcnt lgkmcnt(0)
	s_barrier
; #define PG8_STAGE(bufoff, gbase, voff) do { _Pragma("unroll") for (int _i = 0; _i < 2; ++_i) \
;         __builtin_amdgcn_global_load_lds((const unsigned*)((const char*)(gbase) + (voff)[_i]), (PG8_LAS unsigned*)(lds + (bufoff) + ldsw + _i * 8192), 16, 0, 0); } while (0)
; #define PG8_LDA(dst, b, h) do { _Pragma("unroll") for (int m = 0; m < 4; ++m) _Pragma("unroll") for (int k = 0; k < 2; ++k) dst[m][k] = *(const PG8_LAS bf16x8*)(lds + PG8_SA(b, h) + aoff + m * 2048 + k * 1024); } while (0)
; #define PG8_LDB(dst, b, h) do { _Pragma("unroll") for (int n = 0; n < 2; ++n) _Pragma("unroll") for (int k = 0; k < 2; ++k) dst[n][k] = *(const PG8_LAS bf16x8*)(lds + PG8_SB(b, h) + boff + n * 2048 + k * 1024); } while (0)
; #define PG8_MMA(ai, bj, At, Bt) do { __builtin_amdgcn_s_setprio(1); _Pragma("unroll") for (int m = 0; m < 4; ++m) _Pragma("unroll") for (int n = 0; n < 2; ++n) _Pragma("unroll") for (int k = 0; k < 2; ++k) \
;         acc[ai][bj][m][n] = __builtin_amdgcn_mfma_f32_16x16x32_bf16(Bt[n][k], At[m][k], acc[ai][bj][m][n], 0, 0, 0); __builtin_amdgcn_s_setprio(0); } while (0)
; #define PG8_WAIT_V(n) asm volatile("s_waitcnt vmcnt(" #n ")" ::: "memory")
; #define PG8_WAIT_L(n) asm volatile("s_waitcnt lgkmcnt(" #n ")" ::: "memory")
; #define PG8_BAR __builtin_amdgcn_s_barrier()
; #define PG8_SCHED __builtin_amdgcn_sched_barrier(0)
; template <class Epi, class Sched, bool ALIGN_EPI = false, bool SP2 = false>
; __device__ __forceinline__ void gemm_phase(PG8_LAS unsigned char* lds, const Gemm g, const Sched& S, const Epi& E) {
;     ...
;             PG8_WAIT_V(8); PG8_WAIT_L(0); PG8_BAR; PG8_MMA(1, 0, At, B0); PG8_MMA(1, 1, At, B1); PG8_BAR; PG8_SCHED;
;             PG8_LDB(B0, 1, 0); PG8_LDB(B1, 1, 1); PG8_SCHED; PG8_LDA(At, 1, 0); PG8_STAGE(PG8_SA(0, 1), a2 + hstep, voffA);
;             PG8_WAIT_V(8); PG8_WAIT_L(0); PG8_BAR; PG8_MMA(0, 0, At, B0); PG8_MMA(0, 1, At, B1); PG8_BAR; PG8_SCHED;
	s_setprio 1
	s_waitcnt lgkmcnt(0)
	v_mfma_f32_16x16x32_bf16 v[62:65], v[66:69], v[162:165], v[62:65]
	v_mfma_f32_16x16x32_bf16 v[58:61], v[82:85], v[162:165], v[58:61]
	v_mfma_f32_16x16x32_bf16 v[50:53], v[66:69], v[170:173], v[50:53]
	v_mfma_f32_16x16x32_bf16 v[42:45], v[82:85], v[170:173], v[42:45]
	v_mfma_f32_16x16x32_bf16 v[30:33], v[66:69], v[178:181], v[30:33]
	v_mfma_f32_16x16x32_bf16 v[26:29], v[82:85], v[178:181], v[26:29]
	v_mfma_f32_16x16x32_bf16 v[18:21], v[66:69], v[202:205], v[18:21]
	v_mfma_f32_16x16x32_bf16 v[10:13], v[82:85], v[202:205], v[10:13]
	v_mfma_f32_16x16x32_bf16 v[62:65], v[78:81], v[166:169], v[62:65]
	v_mfma_f32_16x16x32_bf16 v[58:61], v[86:89], v[166:169], v[58:61]
	v_mfma_f32_16x16x32_bf16 v[50:53], v[78:81], v[174:177], v[50:53]
	v_mfma_f32_16x16x32_bf16 v[42:45], v[86:89], v[174:177], v[42:45]
	v_mfma_f32_16x16x32_bf16 v[30:33], v[78:81], v[198:201], v[30:33]
	v_mfma_f32_16x16x32_bf16 v[26:29], v[86:89], v[198:201], v[26:29]
	v_mfma_f32_16x16x32_bf16 v[18:21], v[78:81], v[206:209], v[18:21]
	v_mfma_f32_16x16x32_bf16 v[10:13], v[86:89], v[206:209], v[10:13]
	v_mfma_f32_16x16x32_bf16 v[54:57], v[146:149], v[162:165], v[54:57]
	v_mfma_f32_16x16x32_bf16 v[46:49], v[154:157], v[162:165], v[46:49]
	v_mfma_f32_16x16x32_bf16 v[38:41], v[146:149], v[170:173], v[38:41]
	v_mfma_f32_16x16x32_bf16 v[34:37], v[154:157], v[170:173], v[34:37]
	v_mfma_f32_16x16x32_bf16 v[22:25], v[146:149], v[178:181], v[22:25]
	v_mfma_f32_16x16x32_bf16 v[14:17], v[154:157], v[178:181], v[14:17]
	v_mfma_f32_16x16x32_bf16 v[6:9], v[146:149], v[202:205], v[6:9]
	v_mfma_f32_16x16x32_bf16 v[2:5], v[154:157], v[202:205], v[2:5]
	v_mfma_f32_16x16x32_bf16 v[54:57], v[150:153], v[166:169], v[54:57]
	v_mfma_f32_16x16x32_bf16 v[46:49], v[158:161], v[166:169], v[46:49]
	v_mfma_f32_16x16x32_bf16 v[38:41], v[150:153], v[174:177], v[38:41]
	v_mfma_f32_16x16x32_bf16 v[34:37], v[158:161], v[174:177], v[34:37]
	v_mfma_f32_16x16x32_bf16 v[22:25], v[150:153], v[198:201], v[22:25]
	v_mfma_f32_16x16x32_bf16 v[14:17], v[158:161], v[198:201], v[14:17]
	v_mfma_f32_16x16x32_bf16 v[6:9], v[150:153], v[206:209], v[6:9]
	v_mfma_f32_16x16x32_bf16 v[2:5], v[158:161], v[206:209], v[2:5]
	s_setprio 0
	s_barrier
	s_add_i32 s34, 0, 0x18000
	s_add_i32 s35, 0, 0x1c000
	v_add_u32_e32 v86, s34, v216
	v_add_u32_e32 v158, s35, v216
	ds_read_b128 v[66:69], v86
	ds_read_b128 v[78:81], v86 offset:1024
	ds_read_b128 v[82:85], v86 offset:2048
	ds_read_b128 v[86:89], v86 offset:3072
	ds_read_b128 v[146:149], v158
	ds_read_b128 v[150:153], v158 offset:1024
	ds_read_b128 v[154:157], v158 offset:2048
	ds_read_b128 v[158:161], v158 offset:3072
	s_add_u32 s58, s58, 0xb0000
	s_addc_u32 s59, s59, 0
	s_mov_b32 m0, s61
	v_lshl_add_u64 v[224:225], s[58:59], 0, v[184:185]
	ds_read_b128 v[162:165], v222 offset:32768
	ds_read_b128 v[166:169], v222 offset:33792
	ds_read_b128 v[170:173], v222 offset:34816
	ds_read_b128 v[174:177], v222 offset:35840
	ds_read_b128 v[178:181], v222 offset:36864
	ds_read_b128 v[198:201], v222 offset:37888
	ds_read_b128 v[202:205], v222 offset:38912
	ds_read_b128 v[206:209], v222 offset:39936
	global_load_lds_dwordx4 v[224:225], off
	v_lshl_add_u64 v[224:225], s[58:59], 0, v[186:187]
	s_mov_b32 m0, s62
	s_nop 0
	global_load_lds_dwordx4 v[224:225], off
	s_waitcnt vmcnt(8)
	s_waitcnt lgkmcnt(0)
	s_barrier
	s_setprio 1
	s_waitcnt lgkmcnt(0)
	v_mfma_f32_16x16x32_bf16 v[142:145], v[66:69], v[162:165], v[142:145]
	v_mfma_f32_16x16x32_bf16 v[138:141], v[82:85], v[162:165], v[138:141]
	v_mfma_f32_16x16x32_bf16 v[130:133], v[66:69], v[170:173], v[130:133]
	v_mfma_f32_16x16x32_bf16 v[122:125], v[82:85], v[170:173], v[122:125]
	v_mfma_f32_16x16x32_bf16 v[110:113], v[66:69], v[178:181], v[110:113]
	v_mfma_f32_16x16x32_bf16 v[106:109], v[82:85], v[178:181], v[106:109]
	v_mfma_f32_16x16x32_bf16 v[98:101], v[66:69], v[202:205], v[98:101]
	v_mfma_f32_16x16x32_bf16 v[90:93], v[82:85], v[202:205], v[90:93]
	v_mfma_f32_16x16x32_bf16 v[142:145], v[78:81], v[166:169], v[142:145]
	v_mfma_f32_16x16x32_bf16 v[138:141], v[86:89], v[166:169], v[138:141]
	v_mfma_f32_16x16x32_bf16 v[130:133], v[78:81], v[174:177], v[130:133]
	v_mfma_f32_16x16x32_bf16 v[122:125], v[86:89], v[174:177], v[122:125]
	v_mfma_f32_16x16x32_bf16 v[110:113], v[78:81], v[198:201], v[110:113]
	v_mfma_f32_16x16x32_bf16 v[106:109], v[86:89], v[198:201], v[106:109]
	v_mfma_f32_16x16x32_bf16 v[98:101], v[78:81], v[206:209], v[98:101]
	v_mfma_f32_16x16x32_bf16 v[90:93], v[86:89], v[206:209], v[90:93]
	v_mfma_f32_16x16x32_bf16 v[134:137], v[146:149], v[162:165], v[134:137]
	v_mfma_f32_16x16x32_bf16 v[126:129], v[154:157], v[162:165], v[126:129]
	v_mfma_f32_16x16x32_bf16 v[118:121], v[146:149], v[170:173], v[118:121]
	v_mfma_f32_16x16x32_bf16 v[114:117], v[154:157], v[170:173], v[114:117]
	v_mfma_f32_16x16x32_bf16 v[102:105], v[146:149], v[178:181], v[102:105]
	v_mfma_f32_16x16x32_bf16 v[94:97], v[154:157], v[178:181], v[94:97]
	v_mfma_f32_16x16x32_bf16 v[74:77], v[146:149], v[202:205], v[74:77]
	v_mfma_f32_16x16x32_bf16 v[70:73], v[154:157], v[202:205], v[70:73]
	v_mfma_f32_16x16x32_bf16 v[134:137], v[150:153], v[166:169], v[134:137]
	v_mfma_f32_16x16x32_bf16 v[126:129], v[158:161], v[166:169], v[126:129]
	v_mfma_f32_16x16x32_bf16 v[118:121], v[150:153], v[174:177], v[118:121]
	v_mfma_f32_16x16x32_bf16 v[114:117], v[158:161], v[174:177], v[114:117]
	v_mfma_f32_16x16x32_bf16 v[102:105], v[150:153], v[198:201], v[102:105]
	v_mfma_f32_16x16x32_bf16 v[94:97], v[158:161], v[198:201], v[94:97]
	v_mfma_f32_16x16x32_bf16 v[74:77], v[150:153], v[206:209], v[74:77]
	v_mfma_f32_16x16x32_bf16 v[70:73], v[158:161], v[206:209], v[70:73]
	s_setprio 0
	s_barrier
; #define PG8_STAGE(bufoff, gbase, voff) do { _Pragma("unroll") for (int _i = 0; _i < 2; ++_i) \
;         __builtin_amdgcn_global_load_lds((const unsigned*)((const char*)(gbase) + (voff)[_i]), (PG8_LAS unsigned*)(lds + (bufoff) + ldsw + _i * 8192), 16, 0, 0); } while (0)
; #define PG8_LDA(dst, b, h) do { _Pragma("unroll") for (int m = 0; m < 4; ++m) _Pragma("unroll") for (int k = 0; k < 2; ++k) dst[m][k] = *(const PG8_LAS bf16x8*)(lds + PG8_SA(b, h) + aoff + m * 2048 + k * 1024); } while (0)
; #define PG8_MMA(ai, bj, At, Bt) do { __builtin_amdgcn_s_setprio(1); _Pragma("unroll") for (int m = 0; m < 4; ++m) _Pragma("unroll") for (int n = 0; n < 2; ++n) _Pragma("unroll") for (int k = 0; k < 2; ++k) \
;         acc[ai][bj][m][n] = __builtin_amdgcn_mfma_f32_16x16x32_bf16(Bt[n][k], At[m][k], acc[ai][bj][m][n], 0, 0, 0); __builtin_amdgcn_s_setprio(0); } while (0)
; #define PG8_WAIT_V(n) asm volatile("s_waitcnt vmcnt(" #n ")" ::: "memory")
; #define PG8_WAIT_L(n) asm volatile("s_waitcnt lgkmcnt(" #n ")" ::: "memory")
; #define PG8_BAR __builtin_amdgcn_s_barrier()
; #define PG8_SCHED __builtin_amdgcn_sched_barrier(0)
; template <class Epi, class Sched, bool ALIGN_EPI = false, bool SP2 = false>
; __device__ __forceinline__ void gemm_phase(PG8_LAS unsigned char* lds, const Gemm g, const Sched& S, const Epi& E) {
;     ...
;             PG8_LDA(At, 1, 1); PG8_STAGE(PG8_SB(1, 0), b3, voffB); PG8_STAGE(PG8_SB(1, 1), b3 + hstep, voffB); PG8_STAGE(PG8_SA(1, 0), a3, voffA);
;             PG8_WAIT_V(8); PG8_WAIT_L(0); PG8_BAR; PG8_MMA(1, 0, At, B0); PG8_MMA(1, 1, At, B1); PG8_BAR; PG8_SCHED;
;     ...
;         if constexpr (ALIGN_EPI) { if (wr == 0) PG8_BAR; }
	s_add_i32 s34, s34, s3
	v_lshl_add_u64 v[182:183], v[182:183], 0, s[48:49]
	s_mov_b32 m0, s34
	ds_read_b128 v[162:165], v222 offset:49152
	ds_read_b128 v[166:169], v222 offset:50176
	ds_read_b128 v[170:173], v222 offset:51200
	ds_read_b128 v[174:177], v222 offset:52224
	ds_read_b128 v[178:181], v222 offset:53248
	ds_read_b128 v[198:201], v222 offset:54272
	ds_read_b128 v[202:205], v222 offset:55296
	ds_read_b128 v[206:209], v222 offset:56320
	global_load_lds_dwordx4 v[182:183], off
	s_add_i32 m0, s34, 0x2000
	s_add_u32 s56, s56, 0xb0080
	v_lshl_add_u64 v[182:183], v[210:211], 0, s[48:49]
	s_addc_u32 s57, s57, 0
	s_add_i32 s34, s35, s3
	global_load_lds_dwordx4 v[182:183], off
	v_lshl_add_u64 v[182:183], s[56:57], 0, v[184:185]
	s_mov_b32 m0, s34
	s_nop 0
	global_load_lds_dwordx4 v[182:183], off
	v_lshl_add_u64 v[182:183], s[56:57], 0, v[186:187]
	s_add_i32 m0, s34, 0x2000
	s_nop 0
	global_load_lds_dwordx4 v[182:183], off
	v_lshl_add_u64 v[182:183], v[212:213], 0, s[48:49]
	s_mov_b32 m0, s65
	s_nop 0
	global_load_lds_dwordx4 v[182:183], off
	v_lshl_add_u64 v[182:183], v[214:215], 0, s[48:49]
	s_mov_b32 m0, s66
	s_nop 0
	global_load_lds_dwordx4 v[182:183], off
	s_waitcnt vmcnt(8)
	s_waitcnt lgkmcnt(0)
	s_barrier
	s_setprio 1
	s_waitcnt lgkmcnt(0)
	v_mfma_f32_16x16x32_bf16 v[62:65], v[66:69], v[162:165], v[62:65]
	v_mfma_f32_16x16x32_bf16 v[58:61], v[82:85], v[162:165], v[58:61]
	v_mfma_f32_16x16x32_bf16 v[50:53], v[66:69], v[170:173], v[50:53]
	v_mfma_f32_16x16x32_bf16 v[42:45], v[82:85], v[170:173], v[42:45]
	v_mfma_f32_16x16x32_bf16 v[30:33], v[66:69], v[178:181], v[30:33]
	v_mfma_f32_16x16x32_bf16 v[26:29], v[82:85], v[178:181], v[26:29]
	v_mfma_f32_16x16x32_bf16 v[18:21], v[66:69], v[202:205], v[18:21]
	v_mfma_f32_16x16x32_bf16 v[10:13], v[82:85], v[202:205], v[10:13]
	v_mfma_f32_16x16x32_bf16 v[62:65], v[78:81], v[166:169], v[62:65]
	v_mfma_f32_16x16x32_bf16 v[58:61], v[86:89], v[166:169], v[58:61]
	v_mfma_f32_16x16x32_bf16 v[50:53], v[78:81], v[174:177], v[50:53]
	v_mfma_f32_16x16x32_bf16 v[42:45], v[86:89], v[174:177], v[42:45]
	v_mfma_f32_16x16x32_bf16 v[30:33], v[78:81], v[198:201], v[30:33]
	v_mfma_f32_16x16x32_bf16 v[26:29], v[86:89], v[198:201], v[26:29]
	v_mfma_f32_16x16x32_bf16 v[18:21], v[78:81], v[206:209], v[18:21]
	v_mfma_f32_16x16x32_bf16 v[10:13], v[86:89], v[206:209], v[10:13]
	v_mfma_f32_16x16x32_bf16 v[54:57], v[146:149], v[162:165], v[54:57]
	v_mfma_f32_16x16x32_bf16 v[46:49], v[154:157], v[162:165], v[46:49]
	v_mfma_f32_16x16x32_bf16 v[38:41], v[146:149], v[170:173], v[38:41]
	v_mfma_f32_16x16x32_bf16 v[34:37], v[154:157], v[170:173], v[34:37]
	v_mfma_f32_16x16x32_bf16 v[22:25], v[146:149], v[178:181], v[22:25]
	v_mfma_f32_16x16x32_bf16 v[14:17], v[154:157], v[178:181], v[14:17]
	v_mfma_f32_16x16x32_bf16 v[6:9], v[146:149], v[202:205], v[6:9]
	v_mfma_f32_16x16x32_bf16 v[2:5], v[154:157], v[202:205], v[2:5]
	v_mfma_f32_16x16x32_bf16 v[54:57], v[150:153], v[166:169], v[54:57]
	v_mfma_f32_16x16x32_bf16 v[46:49], v[158:161], v[166:169], v[46:49]
	v_mfma_f32_16x16x32_bf16 v[38:41], v[150:153], v[174:177], v[38:41]
	v_mfma_f32_16x16x32_bf16 v[34:37], v[158:161], v[174:177], v[34:37]
	v_mfma_f32_16x16x32_bf16 v[22:25], v[150:153], v[198:201], v[22:25]
	v_mfma_f32_16x16x32_bf16 v[14:17], v[158:161], v[198:201], v[14:17]
	v_mfma_f32_16x16x32_bf16 v[6:9], v[150:153], v[206:209], v[6:9]
	v_mfma_f32_16x16x32_bf16 v[2:5], v[158:161], v[206:209], v[2:5]
	s_setprio 0
	s_barrier
	s_add_i32 s84, s84, 2
	s_add_u32 s12, s12, 0x100
	s_addc_u32 s13, s13, 0
	s_add_u32 s82, s82, 0x100
	s_addc_u32 s83, s83, 0
	s_cmp_gt_u32 s84, 41
	s_cbranch_scc0 .LBB0_228
	s_and_b64 vcc, exec, s[50:51]
	s_cbranch_vccz .LBB0_231
	s_barrier

; #define PG8_STAGE(bufoff, gbase, voff) do { _Pragma("unroll") for (int _i = 0; _i < 2; ++_i) \
;         __builtin_amdgcn_global_load_lds((const unsigned*)((const char*)(gbase) + (voff)[_i]), (PG8_LAS unsigned*)(lds + (bufoff) + ldsw + _i * 8192), 16, 0, 0); } while (0)
; #define PG8_LDA(dst, b, h) do { _Pragma("unroll") for (int m = 0; m < 4; ++m) _Pragma("unroll") for (int k = 0; k < 2; ++k) dst[m][k] = *(const PG8_LAS bf16x8*)(lds + PG8_SA(b, h) + aoff + m * 2048 + k * 1024); } while (0)
; #define PG8_LDB(dst, b, h) do { _Pragma("unroll") for (int n = 0; n < 2; ++n) _Pragma("unroll") for (int k = 0; k < 2; ++k) dst[n][k] = *(const PG8_LAS bf16x8*)(lds + PG8_SB(b, h) + boff + n * 2048 + k * 1024); } while (0)
; #define PG8_MMA(ai, bj, At, Bt) do { __builtin_amdgcn_s_setprio(1); _Pragma("unroll") for (int m = 0; m < 4; ++m) _Pragma("unroll") for (int n = 0; n < 2; ++n) _Pragma("unroll") for (int k = 0; k < 2; ++k) \
;         acc[ai][bj][m][n] = __builtin_amdgcn_mfma_f32_16x16x32_bf16(Bt[n][k], At[m][k], acc[ai][bj][m][n], 0, 0, 0); __builtin_amdgcn_s_setprio(0); } while (0)
; #define PG8_WAIT_V(n) asm volatile("s_waitcnt vmcnt(" #n ")" ::: "memory")
; #define PG8_WAIT_L(n) asm volatile("s_waitcnt lgkmcnt(" #n ")" ::: "memory")
; #define PG8_BAR __builtin_amdgcn_s_barrier()
; #define PG8_SCHED __builtin_amdgcn_sched_barrier(0)
; template <class Epi, class Sched, bool ALIGN_EPI = false, bool SP2 = false>
; __device__ __forceinline__ void gemm_phase(PG8_LAS unsigned char* lds, const Gemm g, const Sched& S, const Epi& E) {
;     ...
;         for (int t = 0; t < nt; t += 2) {
;             const bool last = (t == nt - 2);
;             const char* a1 = cA + (size_t)(t + 1) * kstep;
;             const char* a2 = last ? nA : cA + (size_t)(t + 2) * kstep; const char* b2 = last ? nB : cB + (size_t)(t + 2) * kstep;
;             const char* a3 = a2 + kstep; const char* b3 = b2 + kstep;
;             if (last && has_next) S.a_ready(nxt);
;             if constexpr (SP2) {
;             PG8_LDB(B0, 0, 0); PG8_LDB(B1, 0, 1); PG8_SCHED; PG8_LDA(At, 0, 0); PG8_STAGE(PG8_SA(1, 1), a1 + hstep, voffA);
;             PG8_WAIT_V(8); PG8_WAIT_L(0); PG8_BAR; PG8_MMA(0, 0, At, B0); PG8_MMA(0, 1, At, B1); PG8_BAR; PG8_SCHED;
;             PG8_LDA(At, 0, 1); PG8_STAGE(PG8_SB(0, 0), b2, voffB); PG8_STAGE(PG8_SB(0, 1), b2 + hstep, voffB); PG8_STAGE(PG8_SA(0, 0), a2, voffA);
.LBB0_370:
	ds_read_b128 v[142:145], v148
	ds_read_b128 v[152:155], v148 offset:1024
	ds_read_b128 v[156:159], v148 offset:2048
	ds_read_b128 v[160:163], v148 offset:3072
	ds_read_b128 v[164:167], v149
	ds_read_b128 v[168:171], v149 offset:1024
	ds_read_b128 v[172:175], v149 offset:2048
	ds_read_b128 v[176:179], v149 offset:3072
	s_add_u32 s34, s42, 0xfffc0080
	s_addc_u32 s35, s43, -1
	s_cmp_eq_u32 s66, 12
	s_cselect_b32 s47, s17, s35
	s_cselect_b32 s46, s62, s34
	s_cselect_b32 s45, s15, s65
	s_cselect_b32 s44, s63, s64
	v_lshl_add_u64 v[212:213], s[42:43], 0, v[134:135]
	s_add_i32 m0, s41, 0xc000
	ds_read_b128 v[180:183], v150
	ds_read_b128 v[184:187], v150 offset:1024
	ds_read_b128 v[188:191], v150 offset:2048
	ds_read_b128 v[192:195], v150 offset:3072
	ds_read_b128 v[196:199], v150 offset:4096
	ds_read_b128 v[200:203], v150 offset:5120
	ds_read_b128 v[204:207], v150 offset:6144
	ds_read_b128 v[208:211], v150 offset:7168
	global_load_lds_dwordx4 v[212:213], off
	v_lshl_add_u64 v[212:213], s[42:43], 0, v[136:137]
	s_add_i32 m0, s41, 0xe000
	s_nop 0
	global_load_lds_dwordx4 v[212:213], off
	s_waitcnt vmcnt(8)
	s_waitcnt lgkmcnt(0)
	s_barrier
	s_setprio 1
	s_waitcnt lgkmcnt(0)
	v_mfma_f32_16x16x32_bf16 v[126:129], v[142:145], v[180:183], v[126:129]
	v_mfma_f32_16x16x32_bf16 v[122:125], v[156:159], v[180:183], v[122:125]
	v_mfma_f32_16x16x32_bf16 v[110:113], v[142:145], v[188:191], v[110:113]
	v_mfma_f32_16x16x32_bf16 v[106:109], v[156:159], v[188:191], v[106:109]
	v_mfma_f32_16x16x32_bf16 v[94:97], v[142:145], v[196:199], v[94:97]
	v_mfma_f32_16x16x32_bf16 v[90:93], v[156:159], v[196:199], v[90:93]
	v_mfma_f32_16x16x32_bf16 v[78:81], v[142:145], v[204:207], v[78:81]
	v_mfma_f32_16x16x32_bf16 v[74:77], v[156:159], v[204:207], v[74:77]
	v_mfma_f32_16x16x32_bf16 v[126:129], v[152:155], v[184:187], v[126:129]
	v_mfma_f32_16x16x32_bf16 v[122:125], v[160:163], v[184:187], v[122:125]
	v_mfma_f32_16x16x32_bf16 v[110:113], v[152:155], v[192:195], v[110:113]
	v_mfma_f32_16x16x32_bf16 v[106:109], v[160:163], v[192:195], v[106:109]
	v_mfma_f32_16x16x32_bf16 v[94:97], v[152:155], v[200:203], v[94:97]
	v_mfma_f32_16x16x32_bf16 v[90:93], v[160:163], v[200:203], v[90:93]
	v_mfma_f32_16x16x32_bf16 v[78:81], v[152:155], v[208:211], v[78:81]
	v_mfma_f32_16x16x32_bf16 v[74:77], v[160:163], v[208:211], v[74:77]
	v_mfma_f32_16x16x32_bf16 v[118:121], v[164:167], v[180:183], v[118:121]
	v_mfma_f32_16x16x32_bf16 v[114:117], v[172:175], v[180:183], v[114:117]
	v_mfma_f32_16x16x32_bf16 v[102:105], v[164:167], v[188:191], v[102:105]
	v_mfma_f32_16x16x32_bf16 v[98:101], v[172:175], v[188:191], v[98:101]
	v_mfma_f32_16x16x32_bf16 v[86:89], v[164:167], v[196:199], v[86:89]
	v_mfma_f32_16x16x32_bf16 v[82:85], v[172:175], v[196:199], v[82:85]
	v_mfma_f32_16x16x32_bf16 v[70:73], v[164:167], v[204:207], v[70:73]
	v_mfma_f32_16x16x32_bf16 v[66:69], v[172:175], v[204:207], v[66:69]
	v_mfma_f32_16x16x32_bf16 v[118:121], v[168:171], v[184:187], v[118:121]
	v_mfma_f32_16x16x32_bf16 v[114:117], v[176:179], v[184:187], v[114:117]
	v_mfma_f32_16x16x32_bf16 v[102:105], v[168:171], v[192:195], v[102:105]
	v_mfma_f32_16x16x32_bf16 v[98:101], v[176:179], v[192:195], v[98:101]
	v_mfma_f32_16x16x32_bf16 v[86:89], v[168:171], v[200:203], v[86:89]
	v_mfma_f32_16x16x32_bf16 v[82:85], v[176:179], v[200:203], v[82:85]
	v_mfma_f32_16x16x32_bf16 v[70:73], v[168:171], v[208:211], v[70:73]
	v_mfma_f32_16x16x32_bf16 v[66:69], v[176:179], v[208:211], v[66:69]
	s_setprio 0
	s_barrier
	s_add_i32 s34, s58, s48
	v_lshl_add_u64 v[212:213], s[44:45], 0, v[132:133]
	s_mov_b32 m0, s34
	ds_read_b128 v[180:183], v150 offset:16384
	ds_read_b128 v[184:187], v150 offset:17408
	ds_read_b128 v[188:191], v150 offset:18432
	ds_read_b128 v[192:195], v150 offset:19456
	ds_read_b128 v[196:199], v150 offset:20480
	ds_read_b128 v[200:203], v150 offset:21504
	ds_read_b128 v[204:207], v150 offset:22528
	ds_read_b128 v[208:211], v150 offset:23552
	global_load_lds_dwordx4 v[212:213], off
	s_add_i32 m0, s34, 0x2000
	s_add_u32 s68, s44, 0x40000
	v_lshl_add_u64 v[214:215], s[44:45], 0, v[130:131]
	s_addc_u32 s69, s45, 0
	s_add_i32 s34, s59, s48
	global_load_lds_dwordx4 v[214:215], off
	v_lshl_add_u64 v[216:217], s[68:69], 0, v[132:133]
	s_mov_b32 m0, s34
	v_lshl_add_u64 v[218:219], s[46:47], 0, v[130:131]
	global_load_lds_dwordx4 v[216:217], off
	v_lshl_add_u64 v[216:217], s[68:69], 0, v[130:131]
	s_add_i32 m0, s34, 0x2000
	s_nop 0
	global_load_lds_dwordx4 v[216:217], off
	v_lshl_add_u64 v[216:217], s[46:47], 0, v[132:133]
	s_mov_b32 m0, s41
	s_nop 0
	global_load_lds_dwordx4 v[216:217], off
	s_mov_b32 m0, s51
	s_nop 0
	global_load_lds_dwordx4 v[218:219], off
	s_waitcnt vmcnt(8)
	s_waitcnt lgkmcnt(0)
	s_barrier
; #define PG8_STAGE(bufoff, gbase, voff) do { _Pragma("unroll") for (int _i = 0; _i < 2; ++_i) \
;         __builtin_amdgcn_global_load_lds((const unsigned*)((const char*)(gbase) + (voff)[_i]), (PG8_LAS unsigned*)(lds + (bufoff) + ldsw + _i * 8192), 16, 0, 0); } while (0)
; #define PG8_LDA(dst, b, h) do { _Pragma("unroll") for (int m = 0; m < 4; ++m) _Pragma("unroll") for (int k = 0; k < 2; ++k) dst[m][k] = *(const PG8_LAS bf16x8*)(lds + PG8_SA(b, h) + aoff + m * 2048 + k * 1024); } while (0)
; #define PG8_LDB(dst, b, h) do { _Pragma("unroll") for (int n = 0; n < 2; ++n) _Pragma("unroll") for (int k = 0; k < 2; ++k) dst[n][k] = *(const PG8_LAS bf16x8*)(lds + PG8_SB(b, h) + boff + n * 2048 + k * 1024); } while (0)
; #define PG8_MMA(ai, bj, At, Bt) do { __builtin_amdgcn_s_setprio(1); _Pragma("unroll") for (int m = 0; m < 4; ++m) _Pragma("unroll") for (int n = 0; n < 2; ++n) _Pragma("unroll") for (int k = 0; k < 2; ++k) \
;         acc[ai][bj][m][n] = __builtin_amdgcn_mfma_f32_16x16x32_bf16(Bt[n][k], At[m][k], acc[ai][bj][m][n], 0, 0, 0); __builtin_amdgcn_s_setprio(0); } while (0)
; #define PG8_WAIT_V(n) asm volatile("s_waitcnt vmcnt(" #n ")" ::: "memory")
; #define PG8_WAIT_L(n) asm volatile("s_waitcnt lgkmcnt(" #n ")" ::: "memory")
; #define PG8_BAR __builtin_amdgcn_s_barrier()
; #define PG8_SCHED __builtin_amdgcn_sched_barrier(0)
; template <class Epi, class Sched, bool ALIGN_EPI = false, bool SP2 = false>
; __device__ __forceinline__ void gemm_phase(PG8_LAS unsigned char* lds, const Gemm g, const Sched& S, const Epi& E) {
;     ...
;             PG8_WAIT_V(8); PG8_WAIT_L(0); PG8_BAR; PG8_MMA(1, 0, At, B0); PG8_MMA(1, 1, At, B1); PG8_BAR; PG8_SCHED;
;             PG8_LDB(B0, 1, 0); PG8_LDB(B1, 1, 1); PG8_SCHED; PG8_LDA(At, 1, 0); PG8_STAGE(PG8_SA(0, 1), a2 + hstep, voffA);
;             PG8_WAIT_V(8); PG8_WAIT_L(0); PG8_BAR; PG8_MMA(0, 0, At, B0); PG8_MMA(0, 1, At, B1); PG8_BAR; PG8_SCHED;
	s_setprio 1
	s_waitcnt lgkmcnt(0)
	v_mfma_f32_16x16x32_bf16 v[62:65], v[142:145], v[180:183], v[62:65]
	v_mfma_f32_16x16x32_bf16 v[58:61], v[156:159], v[180:183], v[58:61]
	v_mfma_f32_16x16x32_bf16 v[46:49], v[142:145], v[188:191], v[46:49]
	v_mfma_f32_16x16x32_bf16 v[42:45], v[156:159], v[188:191], v[42:45]
	v_mfma_f32_16x16x32_bf16 v[30:33], v[142:145], v[196:199], v[30:33]
	v_mfma_f32_16x16x32_bf16 v[26:29], v[156:159], v[196:199], v[26:29]
	v_mfma_f32_16x16x32_bf16 v[14:17], v[142:145], v[204:207], v[14:17]
	v_mfma_f32_16x16x32_bf16 v[10:13], v[156:159], v[204:207], v[10:13]
	v_mfma_f32_16x16x32_bf16 v[62:65], v[152:155], v[184:187], v[62:65]
	v_mfma_f32_16x16x32_bf16 v[58:61], v[160:163], v[184:187], v[58:61]
	v_mfma_f32_16x16x32_bf16 v[46:49], v[152:155], v[192:195], v[46:49]
	v_mfma_f32_16x16x32_bf16 v[42:45], v[160:163], v[192:195], v[42:45]
	v_mfma_f32_16x16x32_bf16 v[30:33], v[152:155], v[200:203], v[30:33]
	v_mfma_f32_16x16x32_bf16 v[26:29], v[160:163], v[200:203], v[26:29]
	v_mfma_f32_16x16x32_bf16 v[14:17], v[152:155], v[208:211], v[14:17]
	v_mfma_f32_16x16x32_bf16 v[10:13], v[160:163], v[208:211], v[10:13]
	v_mfma_f32_16x16x32_bf16 v[54:57], v[164:167], v[180:183], v[54:57]
	v_mfma_f32_16x16x32_bf16 v[50:53], v[172:175], v[180:183], v[50:53]
	v_mfma_f32_16x16x32_bf16 v[38:41], v[164:167], v[188:191], v[38:41]
	v_mfma_f32_16x16x32_bf16 v[34:37], v[172:175], v[188:191], v[34:37]
	v_mfma_f32_16x16x32_bf16 v[22:25], v[164:167], v[196:199], v[22:25]
	v_mfma_f32_16x16x32_bf16 v[18:21], v[172:175], v[196:199], v[18:21]
	v_mfma_f32_16x16x32_bf16 v[6:9], v[164:167], v[204:207], v[6:9]
	v_mfma_f32_16x16x32_bf16 v[2:5], v[172:175], v[204:207], v[2:5]
	v_mfma_f32_16x16x32_bf16 v[54:57], v[168:171], v[184:187], v[54:57]
	v_mfma_f32_16x16x32_bf16 v[50:53], v[176:179], v[184:187], v[50:53]
	v_mfma_f32_16x16x32_bf16 v[38:41], v[168:171], v[192:195], v[38:41]
	v_mfma_f32_16x16x32_bf16 v[34:37], v[176:179], v[192:195], v[34:37]
	v_mfma_f32_16x16x32_bf16 v[22:25], v[168:171], v[200:203], v[22:25]
	v_mfma_f32_16x16x32_bf16 v[18:21], v[176:179], v[200:203], v[18:21]
	v_mfma_f32_16x16x32_bf16 v[6:9], v[168:171], v[208:211], v[6:9]
	v_mfma_f32_16x16x32_bf16 v[2:5], v[176:179], v[208:211], v[2:5]
	s_setprio 0
	s_barrier
	s_add_i32 s34, 0, 0x18000
	v_add_u32_e32 v151, s34, v146
	s_add_i32 s35, 0, 0x1c000
	ds_read_b128 v[142:145], v151
	ds_read_b128 v[152:155], v151 offset:1024
	ds_read_b128 v[156:159], v151 offset:2048
	ds_read_b128 v[160:163], v151 offset:3072
	v_add_u32_e32 v151, s35, v146
	ds_read_b128 v[164:167], v151
	ds_read_b128 v[168:171], v151 offset:1024
	ds_read_b128 v[172:175], v151 offset:2048
	ds_read_b128 v[176:179], v151 offset:3072
	s_add_u32 s46, s46, 0x40000
	s_addc_u32 s47, s47, 0
	s_mov_b32 m0, s52
	v_lshl_add_u64 v[220:221], s[46:47], 0, v[132:133]
	ds_read_b128 v[180:183], v150 offset:32768
	ds_read_b128 v[184:187], v150 offset:33792
	ds_read_b128 v[188:191], v150 offset:34816
	ds_read_b128 v[192:195], v150 offset:35840
	ds_read_b128 v[196:199], v150 offset:36864
	ds_read_b128 v[200:203], v150 offset:37888
	ds_read_b128 v[204:207], v150 offset:38912
	ds_read_b128 v[208:211], v150 offset:39936
	global_load_lds_dwordx4 v[220:221], off
	v_lshl_add_u64 v[220:221], s[46:47], 0, v[130:131]
	s_mov_b32 m0, s53
	s_nop 0
	global_load_lds_dwordx4 v[220:221], off
	s_waitcnt vmcnt(8)
	s_waitcnt lgkmcnt(0)
	s_barrier
	s_setprio 1
	s_waitcnt lgkmcnt(0)
	v_mfma_f32_16x16x32_bf16 v[126:129], v[142:145], v[180:183], v[126:129]
	v_mfma_f32_16x16x32_bf16 v[122:125], v[156:159], v[180:183], v[122:125]
	v_mfma_f32_16x16x32_bf16 v[110:113], v[142:145], v[188:191], v[110:113]
	v_mfma_f32_16x16x32_bf16 v[106:109], v[156:159], v[188:191], v[106:109]
	v_mfma_f32_16x16x32_bf16 v[94:97], v[142:145], v[196:199], v[94:97]
	v_mfma_f32_16x16x32_bf16 v[90:93], v[156:159], v[196:199], v[90:93]
	v_mfma_f32_16x16x32_bf16 v[78:81], v[142:145], v[204:207], v[78:81]
	v_mfma_f32_16x16x32_bf16 v[74:77], v[156:159], v[204:207], v[74:77]
	v_mfma_f32_16x16x32_bf16 v[126:129], v[152:155], v[184:187], v[126:129]
	v_mfma_f32_16x16x32_bf16 v[122:125], v[160:163], v[184:187], v[122:125]
	v_mfma_f32_16x16x32_bf16 v[110:113], v[152:155], v[192:195], v[110:113]
	v_mfma_f32_16x16x32_bf16 v[106:109], v[160:163], v[192:195], v[106:109]
	v_mfma_f32_16x16x32_bf16 v[94:97], v[152:155], v[200:203], v[94:97]
	v_mfma_f32_16x16x32_bf16 v[90:93], v[160:163], v[200:203], v[90:93]
	v_mfma_f32_16x16x32_bf16 v[78:81], v[152:155], v[208:211], v[78:81]
	v_mfma_f32_16x16x32_bf16 v[74:77], v[160:163], v[208:211], v[74:77]
	v_mfma_f32_16x16x32_bf16 v[118:121], v[164:167], v[180:183], v[118:121]
	v_mfma_f32_16x16x32_bf16 v[114:117], v[172:175], v[180:183], v[114:117]
	v_mfma_f32_16x16x32_bf16 v[102:105], v[164:167], v[188:191], v[102:105]
	v_mfma_f32_16x16x32_bf16 v[98:101], v[172:175], v[188:191], v[98:101]
	v_mfma_f32_16x16x32_bf16 v[86:89], v[164:167], v[196:199], v[86:89]
	v_mfma_f32_16x16x32_bf16 v[82:85], v[172:175], v[196:199], v[82:85]
	v_mfma_f32_16x16x32_bf16 v[70:73], v[164:167], v[204:207], v[70:73]
	v_mfma_f32_16x16x32_bf16 v[66:69], v[172:175], v[204:207], v[66:69]
	v_mfma_f32_16x16x32_bf16 v[118:121], v[168:171], v[184:187], v[118:121]
	v_mfma_f32_16x16x32_bf16 v[114:117], v[176:179], v[184:187], v[114:117]
	v_mfma_f32_16x16x32_bf16 v[102:105], v[168:171], v[192:195], v[102:105]
	v_mfma_f32_16x16x32_bf16 v[98:101], v[176:179], v[192:195], v[98:101]
	v_mfma_f32_16x16x32_bf16 v[86:89], v[168:171], v[200:203], v[86:89]
	v_mfma_f32_16x16x32_bf16 v[82:85], v[176:179], v[200:203], v[82:85]
	v_mfma_f32_16x16x32_bf16 v[70:73], v[168:171], v[208:211], v[70:73]
	v_mfma_f32_16x16x32_bf16 v[66:69], v[176:179], v[208:211], v[66:69]
	s_setprio 0
	s_barrier
; #define PG8_STAGE(bufoff, gbase, voff) do { _Pragma("unroll") for (int _i = 0; _i < 2; ++_i) \
;         __builtin_amdgcn_global_load_lds((const unsigned*)((const char*)(gbase) + (voff)[_i]), (PG8_LAS unsigned*)(lds + (bufoff) + ldsw + _i * 8192), 16, 0, 0); } while (0)
; #define PG8_LDA(dst, b, h) do { _Pragma("unroll") for (int m = 0; m < 4; ++m) _Pragma("unroll") for (int k = 0; k < 2; ++k) dst[m][k] = *(const PG8_LAS bf16x8*)(lds + PG8_SA(b, h) + aoff + m * 2048 + k * 1024); } while (0)
; #define PG8_MMA(ai, bj, At, Bt) do { __builtin_amdgcn_s_setprio(1); _Pragma("unroll") for (int m = 0; m < 4; ++m) _Pragma("unroll") for (int n = 0; n < 2; ++n) _Pragma("unroll") for (int k = 0; k < 2; ++k) \
;         acc[ai][bj][m][n] = __builtin_amdgcn_mfma_f32_16x16x32_bf16(Bt[n][k], At[m][k], acc[ai][bj][m][n], 0, 0, 0); __builtin_amdgcn_s_setprio(0); } while (0)
; #define PG8_WAIT_V(n) asm volatile("s_waitcnt vmcnt(" #n ")" ::: "memory")
; #define PG8_WAIT_L(n) asm volatile("s_waitcnt lgkmcnt(" #n ")" ::: "memory")
; #define PG8_BAR __builtin_amdgcn_s_barrier()
; #define PG8_SCHED __builtin_amdgcn_sched_barrier(0)
; template <class Epi, class Sched, bool ALIGN_EPI = false, bool SP2 = false>
; __device__ __forceinline__ void gemm_phase(PG8_LAS unsigned char* lds, const Gemm g, const Sched& S, const Epi& E) {
;     ...
;             PG8_LDA(At, 1, 1); PG8_STAGE(PG8_SB(1, 0), b3, voffB); PG8_STAGE(PG8_SB(1, 1), b3 + hstep, voffB); PG8_STAGE(PG8_SA(1, 0), a3, voffA);
;             PG8_WAIT_V(8); PG8_WAIT_L(0); PG8_BAR; PG8_MMA(1, 0, At, B0); PG8_MMA(1, 1, At, B1); PG8_BAR; PG8_SCHED;
;     ...
;         if constexpr (ALIGN_EPI) { if (wr == 0) PG8_BAR; }
	s_add_i32 s34, s34, s48
	v_lshl_add_u64 v[212:213], v[212:213], 0, s[10:11]
	s_mov_b32 m0, s34
	ds_read_b128 v[180:183], v150 offset:49152
	ds_read_b128 v[184:187], v150 offset:50176
	ds_read_b128 v[188:191], v150 offset:51200
	ds_read_b128 v[192:195], v150 offset:52224
	ds_read_b128 v[196:199], v150 offset:53248
	ds_read_b128 v[200:203], v150 offset:54272
	ds_read_b128 v[204:207], v150 offset:55296
	ds_read_b128 v[208:211], v150 offset:56320
	global_load_lds_dwordx4 v[212:213], off
	s_add_i32 m0, s34, 0x2000
	s_add_u32 s44, s44, 0x40080
	v_lshl_add_u64 v[212:213], v[214:215], 0, s[10:11]
	s_addc_u32 s45, s45, 0
	s_add_i32 s34, s35, s48
	global_load_lds_dwordx4 v[212:213], off
	v_lshl_add_u64 v[212:213], s[44:45], 0, v[132:133]
	s_mov_b32 m0, s34
	s_nop 0
	global_load_lds_dwordx4 v[212:213], off
	v_lshl_add_u64 v[212:213], s[44:45], 0, v[130:131]
	s_add_i32 m0, s34, 0x2000
	s_nop 0
	global_load_lds_dwordx4 v[212:213], off
	v_lshl_add_u64 v[212:213], v[216:217], 0, s[10:11]
	s_mov_b32 m0, s55
	s_nop 0
	global_load_lds_dwordx4 v[212:213], off
	v_lshl_add_u64 v[212:213], v[218:219], 0, s[10:11]
	s_mov_b32 m0, s56
	s_nop 0
	global_load_lds_dwordx4 v[212:213], off
	s_waitcnt vmcnt(8)
	s_waitcnt lgkmcnt(0)
	s_barrier
	s_setprio 1
	s_waitcnt lgkmcnt(0)
	v_mfma_f32_16x16x32_bf16 v[62:65], v[142:145], v[180:183], v[62:65]
	v_mfma_f32_16x16x32_bf16 v[58:61], v[156:159], v[180:183], v[58:61]
	v_mfma_f32_16x16x32_bf16 v[46:49], v[142:145], v[188:191], v[46:49]
	v_mfma_f32_16x16x32_bf16 v[42:45], v[156:159], v[188:191], v[42:45]
	v_mfma_f32_16x16x32_bf16 v[30:33], v[142:145], v[196:199], v[30:33]
	v_mfma_f32_16x16x32_bf16 v[26:29], v[156:159], v[196:199], v[26:29]
	v_mfma_f32_16x16x32_bf16 v[14:17], v[142:145], v[204:207], v[14:17]
	v_mfma_f32_16x16x32_bf16 v[10:13], v[156:159], v[204:207], v[10:13]
	v_mfma_f32_16x16x32_bf16 v[62:65], v[152:155], v[184:187], v[62:65]
	v_mfma_f32_16x16x32_bf16 v[58:61], v[160:163], v[184:187], v[58:61]
	v_mfma_f32_16x16x32_bf16 v[46:49], v[152:155], v[192:195], v[46:49]
	v_mfma_f32_16x16x32_bf16 v[42:45], v[160:163], v[192:195], v[42:45]
	v_mfma_f32_16x16x32_bf16 v[30:33], v[152:155], v[200:203], v[30:33]
	v_mfma_f32_16x16x32_bf16 v[26:29], v[160:163], v[200:203], v[26:29]
	v_mfma_f32_16x16x32_bf16 v[14:17], v[152:155], v[208:211], v[14:17]
	v_mfma_f32_16x16x32_bf16 v[10:13], v[160:163], v[208:211], v[10:13]
	v_mfma_f32_16x16x32_bf16 v[54:57], v[164:167], v[180:183], v[54:57]
	v_mfma_f32_16x16x32_bf16 v[50:53], v[172:175], v[180:183], v[50:53]
	v_mfma_f32_16x16x32_bf16 v[38:41], v[164:167], v[188:191], v[38:41]
	v_mfma_f32_16x16x32_bf16 v[34:37], v[172:175], v[188:191], v[34:37]
	v_mfma_f32_16x16x32_bf16 v[22:25], v[164:167], v[196:199], v[22:25]
	v_mfma_f32_16x16x32_bf16 v[18:21], v[172:175], v[196:199], v[18:21]
	v_mfma_f32_16x16x32_bf16 v[6:9], v[164:167], v[204:207], v[6:9]
	v_mfma_f32_16x16x32_bf16 v[2:5], v[172:175], v[204:207], v[2:5]
	v_mfma_f32_16x16x32_bf16 v[54:57], v[168:171], v[184:187], v[54:57]
	v_mfma_f32_16x16x32_bf16 v[50:53], v[176:179], v[184:187], v[50:53]
	v_mfma_f32_16x16x32_bf16 v[38:41], v[168:171], v[192:195], v[38:41]
	v_mfma_f32_16x16x32_bf16 v[34:37], v[176:179], v[192:195], v[34:37]
	v_mfma_f32_16x16x32_bf16 v[22:25], v[168:171], v[200:203], v[22:25]
	v_mfma_f32_16x16x32_bf16 v[18:21], v[176:179], v[200:203], v[18:21]
	v_mfma_f32_16x16x32_bf16 v[6:9], v[168:171], v[208:211], v[6:9]
	v_mfma_f32_16x16x32_bf16 v[2:5], v[176:179], v[208:211], v[2:5]
	s_setprio 0
	s_barrier
	s_add_i32 s66, s66, 2
	s_add_u32 s42, s42, 0x100
	s_addc_u32 s43, s43, 0
	s_add_u32 s64, s64, 0x100
	s_addc_u32 s65, s65, 0
	s_cmp_gt_u32 s66, 13
	s_cbranch_scc0 .LBB0_370
	s_and_b64 vcc, exec, s[12:13]
	s_cbranch_vccz .LBB0_373
	s_barrier

; #define PG8_STAGE(bufoff, gbase, voff) do { _Pragma("unroll") for (int _i = 0; _i < 2; ++_i) \
;         __builtin_amdgcn_global_load_lds((const unsigned*)((const char*)(gbase) + (voff)[_i]), (PG8_LAS unsigned*)(lds + (bufoff) + ldsw + _i * 8192), 16, 0, 0); } while (0)
; #define PG8_LDA(dst, b, h) do { _Pragma("unroll") for (int m = 0; m < 4; ++m) _Pragma("unroll") for (int k = 0; k < 2; ++k) dst[m][k] = *(const PG8_LAS bf16x8*)(lds + PG8_SA(b, h) + aoff + m * 2048 + k * 1024); } while (0)
; #define PG8_LDB(dst, b, h) do { _Pragma("unroll") for (int n = 0; n < 2; ++n) _Pragma("unroll") for (int k = 0; k < 2; ++k) dst[n][k] = *(const PG8_LAS bf16x8*)(lds + PG8_SB(b, h) + boff + n * 2048 + k * 1024); } while (0)
; #define PG8_MMA(ai, bj, At, Bt) do { __builtin_amdgcn_s_setprio(1); _Pragma("unroll") for (int m = 0; m < 4; ++m) _Pragma("unroll") for (int n = 0; n < 2; ++n) _Pragma("unroll") for (int k = 0; k < 2; ++k) \
;         acc[ai][bj][m][n] = __builtin_amdgcn_mfma_f32_16x16x32_bf16(Bt[n][k], At[m][k], acc[ai][bj][m][n], 0, 0, 0); __builtin_amdgcn_s_setprio(0); } while (0)
; #define PG8_WAIT_V(n) asm volatile("s_waitcnt vmcnt(" #n ")" ::: "memory")
; #define PG8_WAIT_L(n) asm volatile("s_waitcnt lgkmcnt(" #n ")" ::: "memory")
; #define PG8_BAR __builtin_amdgcn_s_barrier()
; #define PG8_SCHED __builtin_amdgcn_sched_barrier(0)
; template <class Epi, class Sched, bool ALIGN_EPI = false, bool SP2 = false>
; __device__ __forceinline__ void gemm_phase(PG8_LAS unsigned char* lds, const Gemm g, const Sched& S, const Epi& E) {
;     ...
;         for (int t = 0; t < nt; t += 2) {
;             const bool last = (t == nt - 2);
;             const char* a1 = cA + (size_t)(t + 1) * kstep;
;             const char* a2 = last ? nA : cA + (size_t)(t + 2) * kstep; const char* b2 = last ? nB : cB + (size_t)(t + 2) * kstep;
;             const char* a3 = a2 + kstep; const char* b3 = b2 + kstep;
;             if (last && has_next) S.a_ready(nxt);
;             if constexpr (SP2) {
;             PG8_LDB(B0, 0, 0); PG8_LDB(B1, 0, 1); PG8_SCHED; PG8_LDA(At, 0, 0); PG8_STAGE(PG8_SA(1, 1), a1 + hstep, voffA);
;             PG8_WAIT_V(8); PG8_WAIT_L(0); PG8_BAR; PG8_MMA(0, 0, At, B0); PG8_MMA(0, 1, At, B1); PG8_BAR; PG8_SCHED;
;             PG8_LDA(At, 0, 1); PG8_STAGE(PG8_SB(0, 0), b2, voffB); PG8_STAGE(PG8_SB(0, 1), b2 + hstep, voffB); PG8_STAGE(PG8_SA(0, 0), a2, voffA);
.LBB0_579:
	ds_read_b128 v[130:133], v178
	ds_read_b128 v[148:151], v178 offset:1024
	ds_read_b128 v[152:155], v178 offset:2048
	ds_read_b128 v[156:159], v178 offset:3072
	ds_read_b128 v[160:163], v179
	ds_read_b128 v[164:167], v179 offset:1024
	ds_read_b128 v[168:171], v179 offset:2048
	ds_read_b128 v[184:187], v179 offset:3072
	s_add_u32 s12, s10, 0xfffc0080
	s_addc_u32 s13, s11, -1
	s_cmp_eq_u32 vcc_lo, 12
	s_cselect_b32 s15, s9, s13
	s_cselect_b32 s14, s67, s12
	s_cselect_b32 s13, s65, s97
	s_cselect_b32 s12, s72, s73
	v_lshl_add_u64 v[220:221], s[10:11], 0, v[140:141]
	s_add_i32 m0, s61, 0xc000
	ds_read_b128 v[188:191], v180
	ds_read_b128 v[192:195], v180 offset:1024
	ds_read_b128 v[196:199], v180 offset:2048
	ds_read_b128 v[200:203], v180 offset:3072
	ds_read_b128 v[204:207], v180 offset:4096
	ds_read_b128 v[208:211], v180 offset:5120
	ds_read_b128 v[212:215], v180 offset:6144
	ds_read_b128 v[216:219], v180 offset:7168
	global_load_lds_dwordx4 v[220:221], off
	v_lshl_add_u64 v[220:221], s[10:11], 0, v[142:143]
	s_add_i32 m0, s61, 0xe000
	s_nop 0
	global_load_lds_dwordx4 v[220:221], off
	s_waitcnt vmcnt(8)
	s_waitcnt lgkmcnt(0)
	s_barrier
	s_setprio 1
	s_waitcnt lgkmcnt(0)
	v_mfma_f32_16x16x32_bf16 v[126:129], v[130:133], v[188:191], v[126:129]
	v_mfma_f32_16x16x32_bf16 v[122:125], v[152:155], v[188:191], v[122:125]
	v_mfma_f32_16x16x32_bf16 v[118:121], v[130:133], v[196:199], v[118:121]
	v_mfma_f32_16x16x32_bf16 v[114:117], v[152:155], v[196:199], v[114:117]
	v_mfma_f32_16x16x32_bf16 v[102:105], v[130:133], v[204:207], v[102:105]
	v_mfma_f32_16x16x32_bf16 v[98:101], v[152:155], v[204:207], v[98:101]
	v_mfma_f32_16x16x32_bf16 v[86:89], v[130:133], v[212:215], v[86:89]
	v_mfma_f32_16x16x32_bf16 v[82:85], v[152:155], v[212:215], v[82:85]
	v_mfma_f32_16x16x32_bf16 v[126:129], v[148:151], v[192:195], v[126:129]
	v_mfma_f32_16x16x32_bf16 v[122:125], v[156:159], v[192:195], v[122:125]
	v_mfma_f32_16x16x32_bf16 v[118:121], v[148:151], v[200:203], v[118:121]
	v_mfma_f32_16x16x32_bf16 v[114:117], v[156:159], v[200:203], v[114:117]
	v_mfma_f32_16x16x32_bf16 v[102:105], v[148:151], v[208:211], v[102:105]
	v_mfma_f32_16x16x32_bf16 v[98:101], v[156:159], v[208:211], v[98:101]
	v_mfma_f32_16x16x32_bf16 v[86:89], v[148:151], v[216:219], v[86:89]
	v_mfma_f32_16x16x32_bf16 v[82:85], v[156:159], v[216:219], v[82:85]
	v_mfma_f32_16x16x32_bf16 v[110:113], v[160:163], v[188:191], v[110:113]
	v_mfma_f32_16x16x32_bf16 v[106:109], v[168:171], v[188:191], v[106:109]
	v_mfma_f32_16x16x32_bf16 v[94:97], v[160:163], v[196:199], v[94:97]
	v_mfma_f32_16x16x32_bf16 v[90:93], v[168:171], v[196:199], v[90:93]
	v_mfma_f32_16x16x32_bf16 v[78:81], v[160:163], v[204:207], v[78:81]
	v_mfma_f32_16x16x32_bf16 v[74:77], v[168:171], v[204:207], v[74:77]
	v_mfma_f32_16x16x32_bf16 v[70:73], v[160:163], v[212:215], v[70:73]
	v_mfma_f32_16x16x32_bf16 v[66:69], v[168:171], v[212:215], v[66:69]
	v_mfma_f32_16x16x32_bf16 v[110:113], v[164:167], v[192:195], v[110:113]
	v_mfma_f32_16x16x32_bf16 v[106:109], v[184:187], v[192:195], v[106:109]
	v_mfma_f32_16x16x32_bf16 v[94:97], v[164:167], v[200:203], v[94:97]
	v_mfma_f32_16x16x32_bf16 v[90:93], v[184:187], v[200:203], v[90:93]
	v_mfma_f32_16x16x32_bf16 v[78:81], v[164:167], v[208:211], v[78:81]
	v_mfma_f32_16x16x32_bf16 v[74:77], v[184:187], v[208:211], v[74:77]
	v_mfma_f32_16x16x32_bf16 v[70:73], v[164:167], v[216:219], v[70:73]
	v_mfma_f32_16x16x32_bf16 v[66:69], v[184:187], v[216:219], v[66:69]
	s_setprio 0
	s_barrier
	s_add_i32 s34, s86, s77
	v_lshl_add_u64 v[220:221], s[12:13], 0, v[134:135]
	s_mov_b32 m0, s34
	ds_read_b128 v[188:191], v180 offset:16384
	ds_read_b128 v[192:195], v180 offset:17408
	ds_read_b128 v[196:199], v180 offset:18432
	ds_read_b128 v[200:203], v180 offset:19456
	ds_read_b128 v[204:207], v180 offset:20480
	ds_read_b128 v[208:211], v180 offset:21504
	ds_read_b128 v[212:215], v180 offset:22528
	ds_read_b128 v[216:219], v180 offset:23552
	global_load_lds_dwordx4 v[220:221], off
	s_add_i32 m0, s34, 0x2000
	s_add_u32 s34, s12, 0x40000
	v_lshl_add_u64 v[222:223], s[12:13], 0, v[136:137]
	s_addc_u32 s35, s13, 0
	s_add_i32 vcc_hi, s87, s77
	global_load_lds_dwordx4 v[222:223], off
	v_lshl_add_u64 v[224:225], s[34:35], 0, v[134:135]
	s_mov_b32 m0, vcc_hi
	v_lshl_add_u64 v[226:227], s[14:15], 0, v[136:137]
	global_load_lds_dwordx4 v[224:225], off
	v_lshl_add_u64 v[224:225], s[34:35], 0, v[136:137]
	s_add_i32 m0, vcc_hi, 0x2000
	s_nop 0
	global_load_lds_dwordx4 v[224:225], off
	v_lshl_add_u64 v[224:225], s[14:15], 0, v[134:135]
	s_mov_b32 m0, s61
	s_nop 0
	global_load_lds_dwordx4 v[224:225], off
	s_mov_b32 m0, s78
	s_nop 0
	global_load_lds_dwordx4 v[226:227], off
	s_waitcnt vmcnt(8)
	s_waitcnt lgkmcnt(0)
	s_barrier
; #define PG8_STAGE(bufoff, gbase, voff) do { _Pragma("unroll") for (int _i = 0; _i < 2; ++_i) \
;         __builtin_amdgcn_global_load_lds((const unsigned*)((const char*)(gbase) + (voff)[_i]), (PG8_LAS unsigned*)(lds + (bufoff) + ldsw + _i * 8192), 16, 0, 0); } while (0)
; #define PG8_LDA(dst, b, h) do { _Pragma("unroll") for (int m = 0; m < 4; ++m) _Pragma("unroll") for (int k = 0; k < 2; ++k) dst[m][k] = *(const PG8_LAS bf16x8*)(lds + PG8_SA(b, h) + aoff + m * 2048 + k * 1024); } while (0)
; #define PG8_LDB(dst, b, h) do { _Pragma("unroll") for (int n = 0; n < 2; ++n) _Pragma("unroll") for (int k = 0; k < 2; ++k) dst[n][k] = *(const PG8_LAS bf16x8*)(lds + PG8_SB(b, h) + boff + n * 2048 + k * 1024); } while (0)
; #define PG8_MMA(ai, bj, At, Bt) do { __builtin_amdgcn_s_setprio(1); _Pragma("unroll") for (int m = 0; m < 4; ++m) _Pragma("unroll") for (int n = 0; n < 2; ++n) _Pragma("unroll") for (int k = 0; k < 2; ++k) \
;         acc[ai][bj][m][n] = __builtin_amdgcn_mfma_f32_16x16x32_bf16(Bt[n][k], At[m][k], acc[ai][bj][m][n], 0, 0, 0); __builtin_amdgcn_s_setprio(0); } while (0)
; #define PG8_WAIT_V(n) asm volatile("s_waitcnt vmcnt(" #n ")" ::: "memory")
; #define PG8_WAIT_L(n) asm volatile("s_waitcnt lgkmcnt(" #n ")" ::: "memory")
; #define PG8_BAR __builtin_amdgcn_s_barrier()
; #define PG8_SCHED __builtin_amdgcn_sched_barrier(0)
; template <class Epi, class Sched, bool ALIGN_EPI = false, bool SP2 = false>
; __device__ __forceinline__ void gemm_phase(PG8_LAS unsigned char* lds, const Gemm g, const Sched& S, const Epi& E) {
;     ...
;             PG8_WAIT_V(8); PG8_WAIT_L(0); PG8_BAR; PG8_MMA(1, 0, At, B0); PG8_MMA(1, 1, At, B1); PG8_BAR; PG8_SCHED;
;             PG8_LDB(B0, 1, 0); PG8_LDB(B1, 1, 1); PG8_SCHED; PG8_LDA(At, 1, 0); PG8_STAGE(PG8_SA(0, 1), a2 + hstep, voffA);
;             PG8_WAIT_V(8); PG8_WAIT_L(0); PG8_BAR; PG8_MMA(0, 0, At, B0); PG8_MMA(0, 1, At, B1); PG8_BAR; PG8_SCHED;
	s_setprio 1
	s_waitcnt lgkmcnt(0)
	v_mfma_f32_16x16x32_bf16 v[62:65], v[130:133], v[188:191], v[62:65]
	v_mfma_f32_16x16x32_bf16 v[58:61], v[152:155], v[188:191], v[58:61]
	v_mfma_f32_16x16x32_bf16 v[54:57], v[130:133], v[196:199], v[54:57]
	v_mfma_f32_16x16x32_bf16 v[50:53], v[152:155], v[196:199], v[50:53]
	v_mfma_f32_16x16x32_bf16 v[38:41], v[130:133], v[204:207], v[38:41]
	v_mfma_f32_16x16x32_bf16 v[34:37], v[152:155], v[204:207], v[34:37]
	v_mfma_f32_16x16x32_bf16 v[22:25], v[130:133], v[212:215], v[22:25]
	v_mfma_f32_16x16x32_bf16 v[18:21], v[152:155], v[212:215], v[18:21]
	v_mfma_f32_16x16x32_bf16 v[62:65], v[148:151], v[192:195], v[62:65]
	v_mfma_f32_16x16x32_bf16 v[58:61], v[156:159], v[192:195], v[58:61]
	v_mfma_f32_16x16x32_bf16 v[54:57], v[148:151], v[200:203], v[54:57]
	v_mfma_f32_16x16x32_bf16 v[50:53], v[156:159], v[200:203], v[50:53]
	v_mfma_f32_16x16x32_bf16 v[38:41], v[148:151], v[208:211], v[38:41]
	v_mfma_f32_16x16x32_bf16 v[34:37], v[156:159], v[208:211], v[34:37]
	v_mfma_f32_16x16x32_bf16 v[22:25], v[148:151], v[216:219], v[22:25]
	v_mfma_f32_16x16x32_bf16 v[18:21], v[156:159], v[216:219], v[18:21]
	v_mfma_f32_16x16x32_bf16 v[46:49], v[160:163], v[188:191], v[46:49]
	v_mfma_f32_16x16x32_bf16 v[42:45], v[168:171], v[188:191], v[42:45]
	v_mfma_f32_16x16x32_bf16 v[30:33], v[160:163], v[196:199], v[30:33]
	v_mfma_f32_16x16x32_bf16 v[26:29], v[168:171], v[196:199], v[26:29]
	v_mfma_f32_16x16x32_bf16 v[14:17], v[160:163], v[204:207], v[14:17]
	v_mfma_f32_16x16x32_bf16 v[10:13], v[168:171], v[204:207], v[10:13]
	v_mfma_f32_16x16x32_bf16 v[6:9], v[160:163], v[212:215], v[6:9]
	v_mfma_f32_16x16x32_bf16 v[2:5], v[168:171], v[212:215], v[2:5]
	v_mfma_f32_16x16x32_bf16 v[46:49], v[164:167], v[192:195], v[46:49]
	v_mfma_f32_16x16x32_bf16 v[42:45], v[184:187], v[192:195], v[42:45]
	v_mfma_f32_16x16x32_bf16 v[30:33], v[164:167], v[200:203], v[30:33]
	v_mfma_f32_16x16x32_bf16 v[26:29], v[184:187], v[200:203], v[26:29]
	v_mfma_f32_16x16x32_bf16 v[14:17], v[164:167], v[208:211], v[14:17]
	v_mfma_f32_16x16x32_bf16 v[10:13], v[184:187], v[208:211], v[10:13]
	v_mfma_f32_16x16x32_bf16 v[6:9], v[164:167], v[216:219], v[6:9]
	v_mfma_f32_16x16x32_bf16 v[2:5], v[184:187], v[216:219], v[2:5]
	s_setprio 0
	s_barrier
	s_add_i32 s34, 0, 0x18000
	v_add_u32_e32 v138, s34, v173
	s_add_i32 s35, 0, 0x1c000
	ds_read_b128 v[130:133], v138
	ds_read_b128 v[148:151], v138 offset:1024
	ds_read_b128 v[152:155], v138 offset:2048
	ds_read_b128 v[156:159], v138 offset:3072
	v_add_u32_e32 v138, s35, v173
	ds_read_b128 v[160:163], v138
	ds_read_b128 v[164:167], v138 offset:1024
	ds_read_b128 v[168:171], v138 offset:2048
	ds_read_b128 v[184:187], v138 offset:3072
	s_add_u32 s14, s14, 0x40000
	s_addc_u32 s15, s15, 0
	s_mov_b32 m0, s79
	v_lshl_add_u64 v[228:229], s[14:15], 0, v[134:135]
	ds_read_b128 v[188:191], v180 offset:32768
	ds_read_b128 v[192:195], v180 offset:33792
	ds_read_b128 v[196:199], v180 offset:34816
	ds_read_b128 v[200:203], v180 offset:35840
	ds_read_b128 v[204:207], v180 offset:36864
	ds_read_b128 v[208:211], v180 offset:37888
	ds_read_b128 v[212:215], v180 offset:38912
	ds_read_b128 v[216:219], v180 offset:39936
	global_load_lds_dwordx4 v[228:229], off
	v_lshl_add_u64 v[228:229], s[14:15], 0, v[136:137]
	s_mov_b32 m0, s80
	s_nop 0
	global_load_lds_dwordx4 v[228:229], off
	s_waitcnt vmcnt(8)
	s_waitcnt lgkmcnt(0)
	s_barrier
	s_setprio 1
	s_waitcnt lgkmcnt(0)
	v_mfma_f32_16x16x32_bf16 v[126:129], v[130:133], v[188:191], v[126:129]
	v_mfma_f32_16x16x32_bf16 v[122:125], v[152:155], v[188:191], v[122:125]
	v_mfma_f32_16x16x32_bf16 v[118:121], v[130:133], v[196:199], v[118:121]
	v_mfma_f32_16x16x32_bf16 v[114:117], v[152:155], v[196:199], v[114:117]
	v_mfma_f32_16x16x32_bf16 v[102:105], v[130:133], v[204:207], v[102:105]
	v_mfma_f32_16x16x32_bf16 v[98:101], v[152:155], v[204:207], v[98:101]
	v_mfma_f32_16x16x32_bf16 v[86:89], v[130:133], v[212:215], v[86:89]
	v_mfma_f32_16x16x32_bf16 v[82:85], v[152:155], v[212:215], v[82:85]
	v_mfma_f32_16x16x32_bf16 v[126:129], v[148:151], v[192:195], v[126:129]
	v_mfma_f32_16x16x32_bf16 v[122:125], v[156:159], v[192:195], v[122:125]
	v_mfma_f32_16x16x32_bf16 v[118:121], v[148:151], v[200:203], v[118:121]
	v_mfma_f32_16x16x32_bf16 v[114:117], v[156:159], v[200:203], v[114:117]
	v_mfma_f32_16x16x32_bf16 v[102:105], v[148:151], v[208:211], v[102:105]
	v_mfma_f32_16x16x32_bf16 v[98:101], v[156:159], v[208:211], v[98:101]
	v_mfma_f32_16x16x32_bf16 v[86:89], v[148:151], v[216:219], v[86:89]
	v_mfma_f32_16x16x32_bf16 v[82:85], v[156:159], v[216:219], v[82:85]
	v_mfma_f32_16x16x32_bf16 v[110:113], v[160:163], v[188:191], v[110:113]
	v_mfma_f32_16x16x32_bf16 v[106:109], v[168:171], v[188:191], v[106:109]
	v_mfma_f32_16x16x32_bf16 v[94:97], v[160:163], v[196:199], v[94:97]
	v_mfma_f32_16x16x32_bf16 v[90:93], v[168:171], v[196:199], v[90:93]
	v_mfma_f32_16x16x32_bf16 v[78:81], v[160:163], v[204:207], v[78:81]
	v_mfma_f32_16x16x32_bf16 v[74:77], v[168:171], v[204:207], v[74:77]
	v_mfma_f32_16x16x32_bf16 v[70:73], v[160:163], v[212:215], v[70:73]
	v_mfma_f32_16x16x32_bf16 v[66:69], v[168:171], v[212:215], v[66:69]
	v_mfma_f32_16x16x32_bf16 v[110:113], v[164:167], v[192:195], v[110:113]
	v_mfma_f32_16x16x32_bf16 v[106:109], v[184:187], v[192:195], v[106:109]
	v_mfma_f32_16x16x32_bf16 v[94:97], v[164:167], v[200:203], v[94:97]
	v_mfma_f32_16x16x32_bf16 v[90:93], v[184:187], v[200:203], v[90:93]
	v_mfma_f32_16x16x32_bf16 v[78:81], v[164:167], v[208:211], v[78:81]
	v_mfma_f32_16x16x32_bf16 v[74:77], v[184:187], v[208:211], v[74:77]
	v_mfma_f32_16x16x32_bf16 v[70:73], v[164:167], v[216:219], v[70:73]
	v_mfma_f32_16x16x32_bf16 v[66:69], v[184:187], v[216:219], v[66:69]
	s_setprio 0
	s_barrier
; #define PG8_STAGE(bufoff, gbase, voff) do { _Pragma("unroll") for (int _i = 0; _i < 2; ++_i) \
;         __builtin_amdgcn_global_load_lds((const unsigned*)((const char*)(gbase) + (voff)[_i]), (PG8_LAS unsigned*)(lds + (bufoff) + ldsw + _i * 8192), 16, 0, 0); } while (0)
; #define PG8_LDA(dst, b, h) do { _Pragma("unroll") for (int m = 0; m < 4; ++m) _Pragma("unroll") for (int k = 0; k < 2; ++k) dst[m][k] = *(const PG8_LAS bf16x8*)(lds + PG8_SA(b, h) + aoff + m * 2048 + k * 1024); } while (0)
; #define PG8_MMA(ai, bj, At, Bt) do { __builtin_amdgcn_s_setprio(1); _Pragma("unroll") for (int m = 0; m < 4; ++m) _Pragma("unroll") for (int n = 0; n < 2; ++n) _Pragma("unroll") for (int k = 0; k < 2; ++k) \
;         acc[ai][bj][m][n] = __builtin_amdgcn_mfma_f32_16x16x32_bf16(Bt[n][k], At[m][k], acc[ai][bj][m][n], 0, 0, 0); __builtin_amdgcn_s_setprio(0); } while (0)
; #define PG8_WAIT_V(n) asm volatile("s_waitcnt vmcnt(" #n ")" ::: "memory")
; #define PG8_WAIT_L(n) asm volatile("s_waitcnt lgkmcnt(" #n ")" ::: "memory")
; #define PG8_BAR __builtin_amdgcn_s_barrier()
; #define PG8_SCHED __builtin_amdgcn_sched_barrier(0)
; template <class Epi, class Sched, bool ALIGN_EPI = false, bool SP2 = false>
; __device__ __forceinline__ void gemm_phase(PG8_LAS unsigned char* lds, const Gemm g, const Sched& S, const Epi& E) {
;     ...
;             PG8_LDA(At, 1, 1); PG8_STAGE(PG8_SB(1, 0), b3, voffB); PG8_STAGE(PG8_SB(1, 1), b3 + hstep, voffB); PG8_STAGE(PG8_SA(1, 0), a3, voffA);
;             PG8_WAIT_V(8); PG8_WAIT_L(0); PG8_BAR; PG8_MMA(1, 0, At, B0); PG8_MMA(1, 1, At, B1); PG8_BAR; PG8_SCHED;
;     ...
;         if constexpr (ALIGN_EPI) { if (wr == 0) PG8_BAR; }
	s_add_i32 s14, s34, s77
	v_lshl_add_u64 v[220:221], v[220:221], 0, s[56:57]
	s_mov_b32 m0, s14
	ds_read_b128 v[188:191], v180 offset:49152
	ds_read_b128 v[192:195], v180 offset:50176
	ds_read_b128 v[196:199], v180 offset:51200
	ds_read_b128 v[200:203], v180 offset:52224
	ds_read_b128 v[204:207], v180 offset:53248
	ds_read_b128 v[208:211], v180 offset:54272
	ds_read_b128 v[212:215], v180 offset:55296
	ds_read_b128 v[216:219], v180 offset:56320
	global_load_lds_dwordx4 v[220:221], off
	s_add_i32 m0, s14, 0x2000
	s_add_u32 s12, s12, 0x40080
	v_lshl_add_u64 v[220:221], v[222:223], 0, s[56:57]
	s_addc_u32 s13, s13, 0
	s_add_i32 s14, s35, s77
	global_load_lds_dwordx4 v[220:221], off
	v_lshl_add_u64 v[220:221], s[12:13], 0, v[134:135]
	s_mov_b32 m0, s14
	s_nop 0
	global_load_lds_dwordx4 v[220:221], off
	v_lshl_add_u64 v[220:221], s[12:13], 0, v[136:137]
	s_add_i32 m0, s14, 0x2000
	s_nop 0
	global_load_lds_dwordx4 v[220:221], off
	v_lshl_add_u64 v[220:221], v[224:225], 0, s[56:57]
	s_mov_b32 m0, s82
	s_nop 0
	global_load_lds_dwordx4 v[220:221], off
	v_lshl_add_u64 v[220:221], v[226:227], 0, s[56:57]
	s_mov_b32 m0, s83
	s_nop 0
	global_load_lds_dwordx4 v[220:221], off
	s_waitcnt vmcnt(8)
	s_waitcnt lgkmcnt(0)
	s_barrier
	s_setprio 1
	s_waitcnt lgkmcnt(0)
	v_mfma_f32_16x16x32_bf16 v[62:65], v[130:133], v[188:191], v[62:65]
	v_mfma_f32_16x16x32_bf16 v[58:61], v[152:155], v[188:191], v[58:61]
	v_mfma_f32_16x16x32_bf16 v[54:57], v[130:133], v[196:199], v[54:57]
	v_mfma_f32_16x16x32_bf16 v[50:53], v[152:155], v[196:199], v[50:53]
	v_mfma_f32_16x16x32_bf16 v[38:41], v[130:133], v[204:207], v[38:41]
	v_mfma_f32_16x16x32_bf16 v[34:37], v[152:155], v[204:207], v[34:37]
	v_mfma_f32_16x16x32_bf16 v[22:25], v[130:133], v[212:215], v[22:25]
	v_mfma_f32_16x16x32_bf16 v[18:21], v[152:155], v[212:215], v[18:21]
	v_mfma_f32_16x16x32_bf16 v[62:65], v[148:151], v[192:195], v[62:65]
	v_mfma_f32_16x16x32_bf16 v[58:61], v[156:159], v[192:195], v[58:61]
	v_mfma_f32_16x16x32_bf16 v[54:57], v[148:151], v[200:203], v[54:57]
	v_mfma_f32_16x16x32_bf16 v[50:53], v[156:159], v[200:203], v[50:53]
	v_mfma_f32_16x16x32_bf16 v[38:41], v[148:151], v[208:211], v[38:41]
	v_mfma_f32_16x16x32_bf16 v[34:37], v[156:159], v[208:211], v[34:37]
	v_mfma_f32_16x16x32_bf16 v[22:25], v[148:151], v[216:219], v[22:25]
	v_mfma_f32_16x16x32_bf16 v[18:21], v[156:159], v[216:219], v[18:21]
	v_mfma_f32_16x16x32_bf16 v[46:49], v[160:163], v[188:191], v[46:49]
	v_mfma_f32_16x16x32_bf16 v[42:45], v[168:171], v[188:191], v[42:45]
	v_mfma_f32_16x16x32_bf16 v[30:33], v[160:163], v[196:199], v[30:33]
	v_mfma_f32_16x16x32_bf16 v[26:29], v[168:171], v[196:199], v[26:29]
	v_mfma_f32_16x16x32_bf16 v[14:17], v[160:163], v[204:207], v[14:17]
	v_mfma_f32_16x16x32_bf16 v[10:13], v[168:171], v[204:207], v[10:13]
	v_mfma_f32_16x16x32_bf16 v[6:9], v[160:163], v[212:215], v[6:9]
	v_mfma_f32_16x16x32_bf16 v[2:5], v[168:171], v[212:215], v[2:5]
	v_mfma_f32_16x16x32_bf16 v[46:49], v[164:167], v[192:195], v[46:49]
	v_mfma_f32_16x16x32_bf16 v[42:45], v[184:187], v[192:195], v[42:45]
	v_mfma_f32_16x16x32_bf16 v[30:33], v[164:167], v[200:203], v[30:33]
	v_mfma_f32_16x16x32_bf16 v[26:29], v[184:187], v[200:203], v[26:29]
	v_mfma_f32_16x16x32_bf16 v[14:17], v[164:167], v[208:211], v[14:17]
	v_mfma_f32_16x16x32_bf16 v[10:13], v[184:187], v[208:211], v[10:13]
	v_mfma_f32_16x16x32_bf16 v[6:9], v[164:167], v[216:219], v[6:9]
	v_mfma_f32_16x16x32_bf16 v[2:5], v[184:187], v[216:219], v[2:5]
	s_setprio 0
	s_barrier
	s_add_i32 vcc_lo, vcc_lo, 2
	s_add_u32 s10, s10, 0x100
	s_addc_u32 s11, s11, 0
	s_add_u32 s73, s73, 0x100
	s_addc_u32 s97, s97, 0
	s_cmp_gt_u32 vcc_lo, 13
	s_cbranch_scc0 .LBB0_579
	s_and_b64 vcc, exec, s[58:59]
	s_cbranch_vccz .LBB0_582
	s_barrier

; #define PG8_STAGE(bufoff, gbase, voff) do { _Pragma("unroll") for (int _i = 0; _i < 2; ++_i) \
;         __builtin_amdgcn_global_load_lds((const unsigned*)((const char*)(gbase) + (voff)[_i]), (PG8_LAS unsigned*)(lds + (bufoff) + ldsw + _i * 8192), 16, 0, 0); } while (0)
; #define PG8_LDA(dst, b, h) do { _Pragma("unroll") for (int m = 0; m < 4; ++m) _Pragma("unroll") for (int k = 0; k < 2; ++k) dst[m][k] = *(const PG8_LAS bf16x8*)(lds + PG8_SA(b, h) + aoff + m * 2048 + k * 1024); } while (0)
; #define PG8_LDB(dst, b, h) do { _Pragma("unroll") for (int n = 0; n < 2; ++n) _Pragma("unroll") for (int k = 0; k < 2; ++k) dst[n][k] = *(const PG8_LAS bf16x8*)(lds + PG8_SB(b, h) + boff + n * 2048 + k * 1024); } while (0)
; #define PG8_MMA(ai, bj, At, Bt) do { __builtin_amdgcn_s_setprio(1); _Pragma("unroll") for (int m = 0; m < 4; ++m) _Pragma("unroll") for (int n = 0; n < 2; ++n) _Pragma("unroll") for (int k = 0; k < 2; ++k) \
;         acc[ai][bj][m][n] = __builtin_amdgcn_mfma_f32_16x16x32_bf16(Bt[n][k], At[m][k], acc[ai][bj][m][n], 0, 0, 0); __builtin_amdgcn_s_setprio(0); } while (0)
; #define PG8_WAIT_V(n) asm volatile("s_waitcnt vmcnt(" #n ")" ::: "memory")
; #define PG8_WAIT_L(n) asm volatile("s_waitcnt lgkmcnt(" #n ")" ::: "memory")
; #define PG8_BAR __builtin_amdgcn_s_barrier()
; #define PG8_SCHED __builtin_amdgcn_sched_barrier(0)
; template <class Epi, class Sched, bool ALIGN_EPI = false, bool SP2 = false>
; __device__ __forceinline__ void gemm_phase(PG8_LAS unsigned char* lds, const Gemm g, const Sched& S, const Epi& E) {
;     ...
;         for (int t = 0; t < nt; t += 2) {
;             const bool last = (t == nt - 2);
;             const char* a1 = cA + (size_t)(t + 1) * kstep;
;             const char* a2 = last ? nA : cA + (size_t)(t + 2) * kstep; const char* b2 = last ? nB : cB + (size_t)(t + 2) * kstep;
;             const char* a3 = a2 + kstep; const char* b3 = b2 + kstep;
;             if (last && has_next) S.a_ready(nxt);
;             if constexpr (SP2) {
;             PG8_LDB(B0, 0, 0); PG8_LDB(B1, 0, 1); PG8_SCHED; PG8_LDA(At, 0, 0); PG8_STAGE(PG8_SA(1, 1), a1 + hstep, voffA);
;             PG8_WAIT_V(8); PG8_WAIT_L(0); PG8_BAR; PG8_MMA(0, 0, At, B0); PG8_MMA(0, 1, At, B1); PG8_BAR; PG8_SCHED;
;             PG8_LDA(At, 0, 1); PG8_STAGE(PG8_SB(0, 0), b2, voffB); PG8_STAGE(PG8_SB(0, 1), b2 + hstep, voffB); PG8_STAGE(PG8_SA(0, 0), a2, voffA);
.LBB0_1331:
	ds_read_b128 v[74:77], v220
	ds_read_b128 v[82:85], v220 offset:1024
	ds_read_b128 v[86:89], v220 offset:2048
	ds_read_b128 v[90:93], v220 offset:3072
	ds_read_b128 v[146:149], v221
	ds_read_b128 v[150:153], v221 offset:1024
	ds_read_b128 v[154:157], v221 offset:2048
	ds_read_b128 v[158:161], v221 offset:3072
	s_add_u32 s34, s12, 0xfffc0080
	s_addc_u32 s35, s13, -1
	s_cmp_eq_u32 s80, 12
	s_cselect_b32 s65, s43, s35
	s_cselect_b32 s64, s55, s34
	s_cselect_b32 s63, s53, s79
	s_cselect_b32 s62, s61, s78
	v_lshl_add_u64 v[182:183], s[12:13], 0, v[190:191]
	s_add_i32 m0, s19, 0xc000
	ds_read_b128 v[162:165], v222
	ds_read_b128 v[166:169], v222 offset:1024
	ds_read_b128 v[170:173], v222 offset:2048
	ds_read_b128 v[174:177], v222 offset:3072
	ds_read_b128 v[178:181], v222 offset:4096
	ds_read_b128 v[198:201], v222 offset:5120
	ds_read_b128 v[202:205], v222 offset:6144
	ds_read_b128 v[206:209], v222 offset:7168
	global_load_lds_dwordx4 v[182:183], off
	v_lshl_add_u64 v[182:183], s[12:13], 0, v[192:193]
	s_add_i32 m0, s19, 0xe000
	s_nop 0
	global_load_lds_dwordx4 v[182:183], off
	s_waitcnt vmcnt(8)
	s_waitcnt lgkmcnt(0)
	s_barrier
	s_setprio 1
	s_waitcnt lgkmcnt(0)
	v_mfma_f32_16x16x32_bf16 v[142:145], v[74:77], v[162:165], v[142:145]
	v_mfma_f32_16x16x32_bf16 v[138:141], v[86:89], v[162:165], v[138:141]
	v_mfma_f32_16x16x32_bf16 v[134:137], v[74:77], v[170:173], v[134:137]
	v_mfma_f32_16x16x32_bf16 v[122:125], v[86:89], v[170:173], v[122:125]
	v_mfma_f32_16x16x32_bf16 v[110:113], v[74:77], v[178:181], v[110:113]
	v_mfma_f32_16x16x32_bf16 v[106:109], v[86:89], v[178:181], v[106:109]
	v_mfma_f32_16x16x32_bf16 v[102:105], v[74:77], v[202:205], v[102:105]
	v_mfma_f32_16x16x32_bf16 v[78:81], v[86:89], v[202:205], v[78:81]
	v_mfma_f32_16x16x32_bf16 v[142:145], v[82:85], v[166:169], v[142:145]
	v_mfma_f32_16x16x32_bf16 v[138:141], v[90:93], v[166:169], v[138:141]
	v_mfma_f32_16x16x32_bf16 v[134:137], v[82:85], v[174:177], v[134:137]
	v_mfma_f32_16x16x32_bf16 v[122:125], v[90:93], v[174:177], v[122:125]
	v_mfma_f32_16x16x32_bf16 v[110:113], v[82:85], v[198:201], v[110:113]
	v_mfma_f32_16x16x32_bf16 v[106:109], v[90:93], v[198:201], v[106:109]
	v_mfma_f32_16x16x32_bf16 v[102:105], v[82:85], v[206:209], v[102:105]
	v_mfma_f32_16x16x32_bf16 v[78:81], v[90:93], v[206:209], v[78:81]
	v_mfma_f32_16x16x32_bf16 v[130:133], v[146:149], v[162:165], v[130:133]
	v_mfma_f32_16x16x32_bf16 v[126:129], v[154:157], v[162:165], v[126:129]
	v_mfma_f32_16x16x32_bf16 v[118:121], v[146:149], v[170:173], v[118:121]
	v_mfma_f32_16x16x32_bf16 v[114:117], v[154:157], v[170:173], v[114:117]
	v_mfma_f32_16x16x32_bf16 v[98:101], v[146:149], v[178:181], v[98:101]
	v_mfma_f32_16x16x32_bf16 v[94:97], v[154:157], v[178:181], v[94:97]
	v_mfma_f32_16x16x32_bf16 v[70:73], v[146:149], v[202:205], v[70:73]
	v_mfma_f32_16x16x32_bf16 v[66:69], v[154:157], v[202:205], v[66:69]
	v_mfma_f32_16x16x32_bf16 v[130:133], v[150:153], v[166:169], v[130:133]
	v_mfma_f32_16x16x32_bf16 v[126:129], v[158:161], v[166:169], v[126:129]
	v_mfma_f32_16x16x32_bf16 v[118:121], v[150:153], v[174:177], v[118:121]
	v_mfma_f32_16x16x32_bf16 v[114:117], v[158:161], v[174:177], v[114:117]
	v_mfma_f32_16x16x32_bf16 v[98:101], v[150:153], v[198:201], v[98:101]
	v_mfma_f32_16x16x32_bf16 v[94:97], v[158:161], v[198:201], v[94:97]
	v_mfma_f32_16x16x32_bf16 v[70:73], v[150:153], v[206:209], v[70:73]
	v_mfma_f32_16x16x32_bf16 v[66:69], v[158:161], v[206:209], v[66:69]
	s_setprio 0
	s_barrier
	s_add_i32 s34, s76, s3
	v_lshl_add_u64 v[182:183], s[62:63], 0, v[184:185]
	s_mov_b32 m0, s34
	ds_read_b128 v[162:165], v222 offset:16384
	ds_read_b128 v[166:169], v222 offset:17408
	ds_read_b128 v[170:173], v222 offset:18432
	ds_read_b128 v[174:177], v222 offset:19456
	ds_read_b128 v[178:181], v222 offset:20480
	ds_read_b128 v[198:201], v222 offset:21504
	ds_read_b128 v[202:205], v222 offset:22528
	ds_read_b128 v[206:209], v222 offset:23552
	global_load_lds_dwordx4 v[182:183], off
	s_add_i32 m0, s34, 0x2000
	s_add_u32 s34, s62, 0x40000
	v_lshl_add_u64 v[210:211], s[62:63], 0, v[186:187]
	s_addc_u32 s35, s63, 0
	s_add_i32 s81, s77, s3
	global_load_lds_dwordx4 v[210:211], off
	v_lshl_add_u64 v[212:213], s[34:35], 0, v[184:185]
	s_mov_b32 m0, s81
	v_lshl_add_u64 v[214:215], s[64:65], 0, v[186:187]
	global_load_lds_dwordx4 v[212:213], off
	v_lshl_add_u64 v[212:213], s[34:35], 0, v[186:187]
	s_add_i32 m0, s81, 0x2000
	s_nop 0
	global_load_lds_dwordx4 v[212:213], off
	v_lshl_add_u64 v[212:213], s[64:65], 0, v[184:185]
	s_mov_b32 m0, s19
	s_nop 0
	global_load_lds_dwordx4 v[212:213], off
	s_mov_b32 m0, s66
	s_nop 0
	global_load_lds_dwordx4 v[214:215], off
	s_waitcnt vmcnt(8)
	s_waitcnt lgkmcnt(0)
	s_barrier
; #define PG8_STAGE(bufoff, gbase, voff) do { _Pragma("unroll") for (int _i = 0; _i < 2; ++_i) \
;         __builtin_amdgcn_global_load_lds((const unsigned*)((const char*)(gbase) + (voff)[_i]), (PG8_LAS unsigned*)(lds + (bufoff) + ldsw + _i * 8192), 16, 0, 0); } while (0)
; #define PG8_LDA(dst, b, h) do { _Pragma("unroll") for (int m = 0; m < 4; ++m) _Pragma("unroll") for (int k = 0; k < 2; ++k) dst[m][k] = *(const PG8_LAS bf16x8*)(lds + PG8_SA(b, h) + aoff + m * 2048 + k * 1024); } while (0)
; #define PG8_LDB(dst, b, h) do { _Pragma("unroll") for (int n = 0; n < 2; ++n) _Pragma("unroll") for (int k = 0; k < 2; ++k) dst[n][k] = *(const PG8_LAS bf16x8*)(lds + PG8_SB(b, h) + boff + n * 2048 + k * 1024); } while (0)
; #define PG8_MMA(ai, bj, At, Bt) do { __builtin_amdgcn_s_setprio(1); _Pragma("unroll") for (int m = 0; m < 4; ++m) _Pragma("unroll") for (int n = 0; n < 2; ++n) _Pragma("unroll") for (int k = 0; k < 2; ++k) \
;         acc[ai][bj][m][n] = __builtin_amdgcn_mfma_f32_16x16x32_bf16(Bt[n][k], At[m][k], acc[ai][bj][m][n], 0, 0, 0); __builtin_amdgcn_s_setprio(0); } while (0)
; #define PG8_WAIT_V(n) asm volatile("s_waitcnt vmcnt(" #n ")" ::: "memory")
; #define PG8_WAIT_L(n) asm volatile("s_waitcnt lgkmcnt(" #n ")" ::: "memory")
; #define PG8_BAR __builtin_amdgcn_s_barrier()
; #define PG8_SCHED __builtin_amdgcn_sched_barrier(0)
; template <class Epi, class Sched, bool ALIGN_EPI = false, bool SP2 = false>
; __device__ __forceinline__ void gemm_phase(PG8_LAS unsigned char* lds, const Gemm g, const Sched& S, const Epi& E) {
;     ...
;             PG8_WAIT_V(8); PG8_WAIT_L(0); PG8_BAR; PG8_MMA(1, 0, At, B0); PG8_MMA(1, 1, At, B1); PG8_BAR; PG8_SCHED;
;             PG8_LDB(B0, 1, 0); PG8_LDB(B1, 1, 1); PG8_SCHED; PG8_LDA(At, 1, 0); PG8_STAGE(PG8_SA(0, 1), a2 + hstep, voffA);
;             PG8_WAIT_V(8); PG8_WAIT_L(0); PG8_BAR; PG8_MMA(0, 0, At, B0); PG8_MMA(0, 1, At, B1); PG8_BAR; PG8_SCHED;
	s_setprio 1
	s_waitcnt lgkmcnt(0)
	v_mfma_f32_16x16x32_bf16 v[62:65], v[74:77], v[162:165], v[62:65]
	v_mfma_f32_16x16x32_bf16 v[58:61], v[86:89], v[162:165], v[58:61]
	v_mfma_f32_16x16x32_bf16 v[54:57], v[74:77], v[170:173], v[54:57]
	v_mfma_f32_16x16x32_bf16 v[42:45], v[86:89], v[170:173], v[42:45]
	v_mfma_f32_16x16x32_bf16 v[30:33], v[74:77], v[178:181], v[30:33]
	v_mfma_f32_16x16x32_bf16 v[26:29], v[86:89], v[178:181], v[26:29]
	v_mfma_f32_16x16x32_bf16 v[22:25], v[74:77], v[202:205], v[22:25]
	v_mfma_f32_16x16x32_bf16 v[10:13], v[86:89], v[202:205], v[10:13]
	v_mfma_f32_16x16x32_bf16 v[62:65], v[82:85], v[166:169], v[62:65]
	v_mfma_f32_16x16x32_bf16 v[58:61], v[90:93], v[166:169], v[58:61]
	v_mfma_f32_16x16x32_bf16 v[54:57], v[82:85], v[174:177], v[54:57]
	v_mfma_f32_16x16x32_bf16 v[42:45], v[90:93], v[174:177], v[42:45]
	v_mfma_f32_16x16x32_bf16 v[30:33], v[82:85], v[198:201], v[30:33]
	v_mfma_f32_16x16x32_bf16 v[26:29], v[90:93], v[198:201], v[26:29]
	v_mfma_f32_16x16x32_bf16 v[22:25], v[82:85], v[206:209], v[22:25]
	v_mfma_f32_16x16x32_bf16 v[10:13], v[90:93], v[206:209], v[10:13]
	v_mfma_f32_16x16x32_bf16 v[50:53], v[146:149], v[162:165], v[50:53]
	v_mfma_f32_16x16x32_bf16 v[46:49], v[154:157], v[162:165], v[46:49]
	v_mfma_f32_16x16x32_bf16 v[38:41], v[146:149], v[170:173], v[38:41]
	v_mfma_f32_16x16x32_bf16 v[34:37], v[154:157], v[170:173], v[34:37]
	v_mfma_f32_16x16x32_bf16 v[18:21], v[146:149], v[178:181], v[18:21]
	v_mfma_f32_16x16x32_bf16 v[14:17], v[154:157], v[178:181], v[14:17]
	v_mfma_f32_16x16x32_bf16 v[6:9], v[146:149], v[202:205], v[6:9]
	v_mfma_f32_16x16x32_bf16 v[2:5], v[154:157], v[202:205], v[2:5]
	v_mfma_f32_16x16x32_bf16 v[50:53], v[150:153], v[166:169], v[50:53]
	v_mfma_f32_16x16x32_bf16 v[46:49], v[158:161], v[166:169], v[46:49]
	v_mfma_f32_16x16x32_bf16 v[38:41], v[150:153], v[174:177], v[38:41]
	v_mfma_f32_16x16x32_bf16 v[34:37], v[158:161], v[174:177], v[34:37]
	v_mfma_f32_16x16x32_bf16 v[18:21], v[150:153], v[198:201], v[18:21]
	v_mfma_f32_16x16x32_bf16 v[14:17], v[158:161], v[198:201], v[14:17]
	v_mfma_f32_16x16x32_bf16 v[6:9], v[150:153], v[206:209], v[6:9]
	v_mfma_f32_16x16x32_bf16 v[2:5], v[158:161], v[206:209], v[2:5]
	s_setprio 0
	s_barrier
	s_add_i32 s81, 0, 0x18000
	s_add_i32 s82, 0, 0x1c000
	v_add_u32_e32 v90, s81, v216
	v_add_u32_e32 v158, s82, v216
	ds_read_b128 v[74:77], v90
	ds_read_b128 v[82:85], v90 offset:1024
	ds_read_b128 v[86:89], v90 offset:2048
	ds_read_b128 v[90:93], v90 offset:3072
	ds_read_b128 v[146:149], v158
	ds_read_b128 v[150:153], v158 offset:1024
	ds_read_b128 v[154:157], v158 offset:2048
	ds_read_b128 v[158:161], v158 offset:3072
	s_add_u32 s34, s64, 0x40000
	s_addc_u32 s35, s65, 0
	s_mov_b32 m0, s67
	v_lshl_add_u64 v[224:225], s[34:35], 0, v[184:185]
	ds_read_b128 v[162:165], v222 offset:32768
	ds_read_b128 v[166:169], v222 offset:33792
	ds_read_b128 v[170:173], v222 offset:34816
	ds_read_b128 v[174:177], v222 offset:35840
	ds_read_b128 v[178:181], v222 offset:36864
	ds_read_b128 v[198:201], v222 offset:37888
	ds_read_b128 v[202:205], v222 offset:38912
	ds_read_b128 v[206:209], v222 offset:39936
	global_load_lds_dwordx4 v[224:225], off
	v_lshl_add_u64 v[224:225], s[34:35], 0, v[186:187]
	s_mov_b32 m0, s68
	s_nop 0
	global_load_lds_dwordx4 v[224:225], off
	s_waitcnt vmcnt(8)
	s_waitcnt lgkmcnt(0)
	s_barrier
	s_setprio 1
	s_waitcnt lgkmcnt(0)
	v_mfma_f32_16x16x32_bf16 v[142:145], v[74:77], v[162:165], v[142:145]
	v_mfma_f32_16x16x32_bf16 v[138:141], v[86:89], v[162:165], v[138:141]
	v_mfma_f32_16x16x32_bf16 v[134:137], v[74:77], v[170:173], v[134:137]
	v_mfma_f32_16x16x32_bf16 v[122:125], v[86:89], v[170:173], v[122:125]
	v_mfma_f32_16x16x32_bf16 v[110:113], v[74:77], v[178:181], v[110:113]
	v_mfma_f32_16x16x32_bf16 v[106:109], v[86:89], v[178:181], v[106:109]
	v_mfma_f32_16x16x32_bf16 v[102:105], v[74:77], v[202:205], v[102:105]
	v_mfma_f32_16x16x32_bf16 v[78:81], v[86:89], v[202:205], v[78:81]
	v_mfma_f32_16x16x32_bf16 v[142:145], v[82:85], v[166:169], v[142:145]
	v_mfma_f32_16x16x32_bf16 v[138:141], v[90:93], v[166:169], v[138:141]
	v_mfma_f32_16x16x32_bf16 v[134:137], v[82:85], v[174:177], v[134:137]
	v_mfma_f32_16x16x32_bf16 v[122:125], v[90:93], v[174:177], v[122:125]
	v_mfma_f32_16x16x32_bf16 v[110:113], v[82:85], v[198:201], v[110:113]
	v_mfma_f32_16x16x32_bf16 v[106:109], v[90:93], v[198:201], v[106:109]
	v_mfma_f32_16x16x32_bf16 v[102:105], v[82:85], v[206:209], v[102:105]
	v_mfma_f32_16x16x32_bf16 v[78:81], v[90:93], v[206:209], v[78:81]
	v_mfma_f32_16x16x32_bf16 v[130:133], v[146:149], v[162:165], v[130:133]
	v_mfma_f32_16x16x32_bf16 v[126:129], v[154:157], v[162:165], v[126:129]
	v_mfma_f32_16x16x32_bf16 v[118:121], v[146:149], v[170:173], v[118:121]
	v_mfma_f32_16x16x32_bf16 v[114:117], v[154:157], v[170:173], v[114:117]
	v_mfma_f32_16x16x32_bf16 v[98:101], v[146:149], v[178:181], v[98:101]
	v_mfma_f32_16x16x32_bf16 v[94:97], v[154:157], v[178:181], v[94:97]
	v_mfma_f32_16x16x32_bf16 v[70:73], v[146:149], v[202:205], v[70:73]
	v_mfma_f32_16x16x32_bf16 v[66:69], v[154:157], v[202:205], v[66:69]
	v_mfma_f32_16x16x32_bf16 v[130:133], v[150:153], v[166:169], v[130:133]
	v_mfma_f32_16x16x32_bf16 v[126:129], v[158:161], v[166:169], v[126:129]
	v_mfma_f32_16x16x32_bf16 v[118:121], v[150:153], v[174:177], v[118:121]
	v_mfma_f32_16x16x32_bf16 v[114:117], v[158:161], v[174:177], v[114:117]
	v_mfma_f32_16x16x32_bf16 v[98:101], v[150:153], v[198:201], v[98:101]
	v_mfma_f32_16x16x32_bf16 v[94:97], v[158:161], v[198:201], v[94:97]
	v_mfma_f32_16x16x32_bf16 v[70:73], v[150:153], v[206:209], v[70:73]
	v_mfma_f32_16x16x32_bf16 v[66:69], v[158:161], v[206:209], v[66:69]
	s_setprio 0
	s_barrier
; #define PG8_STAGE(bufoff, gbase, voff) do { _Pragma("unroll") for (int _i = 0; _i < 2; ++_i) \
;         __builtin_amdgcn_global_load_lds((const unsigned*)((const char*)(gbase) + (voff)[_i]), (PG8_LAS unsigned*)(lds + (bufoff) + ldsw + _i * 8192), 16, 0, 0); } while (0)
; #define PG8_LDA(dst, b, h) do { _Pragma("unroll") for (int m = 0; m < 4; ++m) _Pragma("unroll") for (int k = 0; k < 2; ++k) dst[m][k] = *(const PG8_LAS bf16x8*)(lds + PG8_SA(b, h) + aoff + m * 2048 + k * 1024); } while (0)
; #define PG8_MMA(ai, bj, At, Bt) do { __builtin_amdgcn_s_setprio(1); _Pragma("unroll") for (int m = 0; m < 4; ++m) _Pragma("unroll") for (int n = 0; n < 2; ++n) _Pragma("unroll") for (int k = 0; k < 2; ++k) \
;         acc[ai][bj][m][n] = __builtin_amdgcn_mfma_f32_16x16x32_bf16(Bt[n][k], At[m][k], acc[ai][bj][m][n], 0, 0, 0); __builtin_amdgcn_s_setprio(0); } while (0)
; #define PG8_WAIT_V(n) asm volatile("s_waitcnt vmcnt(" #n ")" ::: "memory")
; #define PG8_WAIT_L(n) asm volatile("s_waitcnt lgkmcnt(" #n ")" ::: "memory")
; #define PG8_BAR __builtin_amdgcn_s_barrier()
; #define PG8_SCHED __builtin_amdgcn_sched_barrier(0)
; template <class Epi, class Sched, bool ALIGN_EPI = false, bool SP2 = false>
; __device__ __forceinline__ void gemm_phase(PG8_LAS unsigned char* lds, const Gemm g, const Sched& S, const Epi& E) {
;     ...
;             PG8_LDA(At, 1, 1); PG8_STAGE(PG8_SB(1, 0), b3, voffB); PG8_STAGE(PG8_SB(1, 1), b3 + hstep, voffB); PG8_STAGE(PG8_SA(1, 0), a3, voffA);
;             PG8_WAIT_V(8); PG8_WAIT_L(0); PG8_BAR; PG8_MMA(1, 0, At, B0); PG8_MMA(1, 1, At, B1); PG8_BAR; PG8_SCHED;
;     ...
;         if constexpr (ALIGN_EPI) { if (wr == 0) PG8_BAR; }
	s_add_i32 s34, s81, s3
	v_lshl_add_u64 v[182:183], v[182:183], 0, s[46:47]
	s_mov_b32 m0, s34
	ds_read_b128 v[162:165], v222 offset:49152
	ds_read_b128 v[166:169], v222 offset:50176
	ds_read_b128 v[170:173], v222 offset:51200
	ds_read_b128 v[174:177], v222 offset:52224
	ds_read_b128 v[178:181], v222 offset:53248
	ds_read_b128 v[198:201], v222 offset:54272
	ds_read_b128 v[202:205], v222 offset:55296
	ds_read_b128 v[206:209], v222 offset:56320
	global_load_lds_dwordx4 v[182:183], off
	s_add_i32 m0, s34, 0x2000
	s_add_u32 s34, s62, 0x40080
	v_lshl_add_u64 v[182:183], v[210:211], 0, s[46:47]
	s_addc_u32 s35, s63, 0
	s_add_i32 s62, s82, s3
	global_load_lds_dwordx4 v[182:183], off
	v_lshl_add_u64 v[182:183], s[34:35], 0, v[184:185]
	s_mov_b32 m0, s62
	s_nop 0
	global_load_lds_dwordx4 v[182:183], off
	v_lshl_add_u64 v[182:183], s[34:35], 0, v[186:187]
	s_add_i32 m0, s62, 0x2000
	s_nop 0
	global_load_lds_dwordx4 v[182:183], off
	v_lshl_add_u64 v[182:183], v[212:213], 0, s[46:47]
	s_mov_b32 m0, s70
	s_nop 0
	global_load_lds_dwordx4 v[182:183], off
	v_lshl_add_u64 v[182:183], v[214:215], 0, s[46:47]
	s_mov_b32 m0, s71
	s_nop 0
	global_load_lds_dwordx4 v[182:183], off
	s_waitcnt vmcnt(8)
	s_waitcnt lgkmcnt(0)
	s_barrier
	s_setprio 1
	s_waitcnt lgkmcnt(0)
	v_mfma_f32_16x16x32_bf16 v[62:65], v[74:77], v[162:165], v[62:65]
	v_mfma_f32_16x16x32_bf16 v[58:61], v[86:89], v[162:165], v[58:61]
	v_mfma_f32_16x16x32_bf16 v[54:57], v[74:77], v[170:173], v[54:57]
	v_mfma_f32_16x16x32_bf16 v[42:45], v[86:89], v[170:173], v[42:45]
	v_mfma_f32_16x16x32_bf16 v[30:33], v[74:77], v[178:181], v[30:33]
	v_mfma_f32_16x16x32_bf16 v[26:29], v[86:89], v[178:181], v[26:29]
	v_mfma_f32_16x16x32_bf16 v[22:25], v[74:77], v[202:205], v[22:25]
	v_mfma_f32_16x16x32_bf16 v[10:13], v[86:89], v[202:205], v[10:13]
	v_mfma_f32_16x16x32_bf16 v[62:65], v[82:85], v[166:169], v[62:65]
	v_mfma_f32_16x16x32_bf16 v[58:61], v[90:93], v[166:169], v[58:61]
	v_mfma_f32_16x16x32_bf16 v[54:57], v[82:85], v[174:177], v[54:57]
	v_mfma_f32_16x16x32_bf16 v[42:45], v[90:93], v[174:177], v[42:45]
	v_mfma_f32_16x16x32_bf16 v[30:33], v[82:85], v[198:201], v[30:33]
	v_mfma_f32_16x16x32_bf16 v[26:29], v[90:93], v[198:201], v[26:29]
	v_mfma_f32_16x16x32_bf16 v[22:25], v[82:85], v[206:209], v[22:25]
	v_mfma_f32_16x16x32_bf16 v[10:13], v[90:93], v[206:209], v[10:13]
	v_mfma_f32_16x16x32_bf16 v[50:53], v[146:149], v[162:165], v[50:53]
	v_mfma_f32_16x16x32_bf16 v[46:49], v[154:157], v[162:165], v[46:49]
	v_mfma_f32_16x16x32_bf16 v[38:41], v[146:149], v[170:173], v[38:41]
	v_mfma_f32_16x16x32_bf16 v[34:37], v[154:157], v[170:173], v[34:37]
	v_mfma_f32_16x16x32_bf16 v[18:21], v[146:149], v[178:181], v[18:21]
	v_mfma_f32_16x16x32_bf16 v[14:17], v[154:157], v[178:181], v[14:17]
	v_mfma_f32_16x16x32_bf16 v[6:9], v[146:149], v[202:205], v[6:9]
	v_mfma_f32_16x16x32_bf16 v[2:5], v[154:157], v[202:205], v[2:5]
	v_mfma_f32_16x16x32_bf16 v[50:53], v[150:153], v[166:169], v[50:53]
	v_mfma_f32_16x16x32_bf16 v[46:49], v[158:161], v[166:169], v[46:49]
	v_mfma_f32_16x16x32_bf16 v[38:41], v[150:153], v[174:177], v[38:41]
	v_mfma_f32_16x16x32_bf16 v[34:37], v[158:161], v[174:177], v[34:37]
	v_mfma_f32_16x16x32_bf16 v[18:21], v[150:153], v[198:201], v[18:21]
	v_mfma_f32_16x16x32_bf16 v[14:17], v[158:161], v[198:201], v[14:17]
	v_mfma_f32_16x16x32_bf16 v[6:9], v[150:153], v[206:209], v[6:9]
	v_mfma_f32_16x16x32_bf16 v[2:5], v[158:161], v[206:209], v[2:5]
	s_setprio 0
	s_barrier
	s_add_i32 s80, s80, 2
	s_add_u32 s12, s12, 0x100
	s_addc_u32 s13, s13, 0
	s_add_u32 s78, s78, 0x100
	s_addc_u32 s79, s79, 0
	s_cmp_gt_u32 s80, 13
	s_cbranch_scc0 .LBB0_1331
	s_and_b64 vcc, exec, s[48:49]
	s_cbranch_vccz .LBB0_1334
	s_barrier

; #define PG8_STAGE(bufoff, gbase, voff) do { _Pragma("unroll") for (int _i = 0; _i < 2; ++_i) \
;         __builtin_amdgcn_global_load_lds((const unsigned*)((const char*)(gbase) + (voff)[_i]), (PG8_LAS unsigned*)(lds + (bufoff) + ldsw + _i * 8192), 16, 0, 0); } while (0)
; #define PG8_LDA(dst, b, h) do { _Pragma("unroll") for (int m = 0; m < 4; ++m) _Pragma("unroll") for (int k = 0; k < 2; ++k) dst[m][k] = *(const PG8_LAS bf16x8*)(lds + PG8_SA(b, h) + aoff + m * 2048 + k * 1024); } while (0)
; #define PG8_LDB(dst, b, h) do { _Pragma("unroll") for (int n = 0; n < 2; ++n) _Pragma("unroll") for (int k = 0; k < 2; ++k) dst[n][k] = *(const PG8_LAS bf16x8*)(lds + PG8_SB(b, h) + boff + n * 2048 + k * 1024); } while (0)
; #define PG8_MMA(ai, bj, At, Bt) do { __builtin_amdgcn_s_setprio(1); _Pragma("unroll") for (int m = 0; m < 4; ++m) _Pragma("unroll") for (int n = 0; n < 2; ++n) _Pragma("unroll") for (int k = 0; k < 2; ++k) \
;         acc[ai][bj][m][n] = __builtin_amdgcn_mfma_f32_16x16x32_bf16(Bt[n][k], At[m][k], acc[ai][bj][m][n], 0, 0, 0); __builtin_amdgcn_s_setprio(0); } while (0)
; #define PG8_WAIT_V(n) asm volatile("s_waitcnt vmcnt(" #n ")" ::: "memory")
; #define PG8_WAIT_L(n) asm volatile("s_waitcnt lgkmcnt(" #n ")" ::: "memory")
; #define PG8_BAR __builtin_amdgcn_s_barrier()
; #define PG8_SCHED __builtin_amdgcn_sched_barrier(0)
; template <class Epi, class Sched, bool ALIGN_EPI = false, bool SP2 = false>
; __device__ __forceinline__ void gemm_phase(PG8_LAS unsigned char* lds, const Gemm g, const Sched& S, const Epi& E) {
;     ...
;         for (int t = 0; t < nt; t += 2) {
;             const bool last = (t == nt - 2);
;             const char* a1 = cA + (size_t)(t + 1) * kstep;
;             const char* a2 = last ? nA : cA + (size_t)(t + 2) * kstep; const char* b2 = last ? nB : cB + (size_t)(t + 2) * kstep;
;             const char* a3 = a2 + kstep; const char* b3 = b2 + kstep;
;             if (last && has_next) S.a_ready(nxt);
;             if constexpr (SP2) {
;             PG8_LDB(B0, 0, 0); PG8_LDB(B1, 0, 1); PG8_SCHED; PG8_LDA(At, 0, 0); PG8_STAGE(PG8_SA(1, 1), a1 + hstep, voffA);
;             PG8_WAIT_V(8); PG8_WAIT_L(0); PG8_BAR; PG8_MMA(0, 0, At, B0); PG8_MMA(0, 1, At, B1); PG8_BAR; PG8_SCHED;
;             PG8_LDA(At, 0, 1); PG8_STAGE(PG8_SB(0, 0), b2, voffB); PG8_STAGE(PG8_SB(0, 1), b2 + hstep, voffB); PG8_STAGE(PG8_SA(0, 0), a2, voffA);
.LBB0_1577:
	ds_read_b128 v[142:145], v160
	ds_read_b128 v[146:149], v160 offset:1024
	ds_read_b128 v[164:167], v160 offset:2048
	ds_read_b128 v[168:171], v160 offset:3072
	ds_read_b128 v[172:175], v161
	ds_read_b128 v[176:179], v161 offset:1024
	ds_read_b128 v[180:183], v161 offset:2048
	ds_read_b128 v[184:187], v161 offset:3072
	s_add_u32 s34, s60, 0xfffe0080
	s_addc_u32 s35, s61, -1
	s_cmp_eq_u32 s82, 4
	s_cselect_b32 s65, s53, s35
	s_cselect_b32 s64, s78, s34
	s_cselect_b32 s63, s51, s81
	s_cselect_b32 s62, s79, s80
	v_lshl_add_u64 v[220:221], s[60:61], 0, v[134:135]
	s_add_i32 m0, s59, 0xc000
	ds_read_b128 v[188:191], v162
	ds_read_b128 v[192:195], v162 offset:1024
	ds_read_b128 v[196:199], v162 offset:2048
	ds_read_b128 v[200:203], v162 offset:3072
	ds_read_b128 v[204:207], v162 offset:4096
	ds_read_b128 v[208:211], v162 offset:5120
	ds_read_b128 v[212:215], v162 offset:6144
	ds_read_b128 v[216:219], v162 offset:7168
	global_load_lds_dwordx4 v[220:221], off
	v_lshl_add_u64 v[220:221], s[60:61], 0, v[136:137]
	s_add_i32 m0, s59, 0xe000
	s_nop 0
	global_load_lds_dwordx4 v[220:221], off
	s_waitcnt vmcnt(8)
	s_waitcnt lgkmcnt(0)
	s_barrier
	s_setprio 1
	s_waitcnt lgkmcnt(0)
	v_mfma_f32_16x16x32_bf16 v[126:129], v[142:145], v[188:191], v[126:129]
	v_mfma_f32_16x16x32_bf16 v[122:125], v[164:167], v[188:191], v[122:125]
	v_mfma_f32_16x16x32_bf16 v[118:121], v[142:145], v[196:199], v[118:121]
	v_mfma_f32_16x16x32_bf16 v[106:109], v[164:167], v[196:199], v[106:109]
	v_mfma_f32_16x16x32_bf16 v[98:101], v[142:145], v[204:207], v[98:101]
	v_mfma_f32_16x16x32_bf16 v[90:93], v[164:167], v[204:207], v[90:93]
	v_mfma_f32_16x16x32_bf16 v[86:89], v[142:145], v[212:215], v[86:89]
	v_mfma_f32_16x16x32_bf16 v[74:77], v[164:167], v[212:215], v[74:77]
	v_mfma_f32_16x16x32_bf16 v[126:129], v[146:149], v[192:195], v[126:129]
	v_mfma_f32_16x16x32_bf16 v[122:125], v[168:171], v[192:195], v[122:125]
	v_mfma_f32_16x16x32_bf16 v[118:121], v[146:149], v[200:203], v[118:121]
	v_mfma_f32_16x16x32_bf16 v[106:109], v[168:171], v[200:203], v[106:109]
	v_mfma_f32_16x16x32_bf16 v[98:101], v[146:149], v[208:211], v[98:101]
	v_mfma_f32_16x16x32_bf16 v[90:93], v[168:171], v[208:211], v[90:93]
	v_mfma_f32_16x16x32_bf16 v[86:89], v[146:149], v[216:219], v[86:89]
	v_mfma_f32_16x16x32_bf16 v[74:77], v[168:171], v[216:219], v[74:77]
	v_mfma_f32_16x16x32_bf16 v[114:117], v[172:175], v[188:191], v[114:117]
	v_mfma_f32_16x16x32_bf16 v[110:113], v[180:183], v[188:191], v[110:113]
	v_mfma_f32_16x16x32_bf16 v[102:105], v[172:175], v[196:199], v[102:105]
	v_mfma_f32_16x16x32_bf16 v[94:97], v[180:183], v[196:199], v[94:97]
	v_mfma_f32_16x16x32_bf16 v[82:85], v[172:175], v[204:207], v[82:85]
	v_mfma_f32_16x16x32_bf16 v[78:81], v[180:183], v[204:207], v[78:81]
	v_mfma_f32_16x16x32_bf16 v[70:73], v[172:175], v[212:215], v[70:73]
	v_mfma_f32_16x16x32_bf16 v[66:69], v[180:183], v[212:215], v[66:69]
	v_mfma_f32_16x16x32_bf16 v[114:117], v[176:179], v[192:195], v[114:117]
	v_mfma_f32_16x16x32_bf16 v[110:113], v[184:187], v[192:195], v[110:113]
	v_mfma_f32_16x16x32_bf16 v[102:105], v[176:179], v[200:203], v[102:105]
	v_mfma_f32_16x16x32_bf16 v[94:97], v[184:187], v[200:203], v[94:97]
	v_mfma_f32_16x16x32_bf16 v[82:85], v[176:179], v[208:211], v[82:85]
	v_mfma_f32_16x16x32_bf16 v[78:81], v[184:187], v[208:211], v[78:81]
	v_mfma_f32_16x16x32_bf16 v[70:73], v[176:179], v[216:219], v[70:73]
	v_mfma_f32_16x16x32_bf16 v[66:69], v[184:187], v[216:219], v[66:69]
	s_setprio 0
	s_barrier
	s_add_i32 s34, s73, s19
	v_lshl_add_u64 v[220:221], s[62:63], 0, v[130:131]
	s_mov_b32 m0, s34
	ds_read_b128 v[188:191], v162 offset:16384
	ds_read_b128 v[192:195], v162 offset:17408
	ds_read_b128 v[196:199], v162 offset:18432
	ds_read_b128 v[200:203], v162 offset:19456
	ds_read_b128 v[204:207], v162 offset:20480
	ds_read_b128 v[208:211], v162 offset:21504
	ds_read_b128 v[212:215], v162 offset:22528
	ds_read_b128 v[216:219], v162 offset:23552
	global_load_lds_dwordx4 v[220:221], off
	s_add_i32 m0, s34, 0x2000
	s_add_u32 s34, s62, 0x20000
	v_lshl_add_u64 v[222:223], s[62:63], 0, v[132:133]
	s_addc_u32 s35, s63, 0
	s_add_i32 s83, s76, s19
	global_load_lds_dwordx4 v[222:223], off
	v_lshl_add_u64 v[224:225], s[34:35], 0, v[130:131]
	s_mov_b32 m0, s83
	v_lshl_add_u64 v[226:227], s[64:65], 0, v[132:133]
	global_load_lds_dwordx4 v[224:225], off
	v_lshl_add_u64 v[224:225], s[34:35], 0, v[132:133]
	s_add_i32 m0, s83, 0x2000
	s_nop 0
	global_load_lds_dwordx4 v[224:225], off
	v_lshl_add_u64 v[224:225], s[64:65], 0, v[130:131]
	s_mov_b32 m0, s59
	s_nop 0
	global_load_lds_dwordx4 v[224:225], off
	s_mov_b32 m0, s66
	s_nop 0
	global_load_lds_dwordx4 v[226:227], off
	s_waitcnt vmcnt(8)
	s_waitcnt lgkmcnt(0)
	s_barrier
; #define PG8_STAGE(bufoff, gbase, voff) do { _Pragma("unroll") for (int _i = 0; _i < 2; ++_i) \
;         __builtin_amdgcn_global_load_lds((const unsigned*)((const char*)(gbase) + (voff)[_i]), (PG8_LAS unsigned*)(lds + (bufoff) + ldsw + _i * 8192), 16, 0, 0); } while (0)
; #define PG8_LDA(dst, b, h) do { _Pragma("unroll") for (int m = 0; m < 4; ++m) _Pragma("unroll") for (int k = 0; k < 2; ++k) dst[m][k] = *(const PG8_LAS bf16x8*)(lds + PG8_SA(b, h) + aoff + m * 2048 + k * 1024); } while (0)
; #define PG8_LDB(dst, b, h) do { _Pragma("unroll") for (int n = 0; n < 2; ++n) _Pragma("unroll") for (int k = 0; k < 2; ++k) dst[n][k] = *(const PG8_LAS bf16x8*)(lds + PG8_SB(b, h) + boff + n * 2048 + k * 1024); } while (0)
; #define PG8_MMA(ai, bj, At, Bt) do { __builtin_amdgcn_s_setprio(1); _Pragma("unroll") for (int m = 0; m < 4; ++m) _Pragma("unroll") for (int n = 0; n < 2; ++n) _Pragma("unroll") for (int k = 0; k < 2; ++k) \
;         acc[ai][bj][m][n] = __builtin_amdgcn_mfma_f32_16x16x32_bf16(Bt[n][k], At[m][k], acc[ai][bj][m][n], 0, 0, 0); __builtin_amdgcn_s_setprio(0); } while (0)
; #define PG8_WAIT_V(n) asm volatile("s_waitcnt vmcnt(" #n ")" ::: "memory")
; #define PG8_WAIT_L(n) asm volatile("s_waitcnt lgkmcnt(" #n ")" ::: "memory")
; #define PG8_BAR __builtin_amdgcn_s_barrier()
; #define PG8_SCHED __builtin_amdgcn_sched_barrier(0)
; template <class Epi, class Sched, bool ALIGN_EPI = false, bool SP2 = false>
; __device__ __forceinline__ void gemm_phase(PG8_LAS unsigned char* lds, const Gemm g, const Sched& S, const Epi& E) {
;     ...
;             PG8_WAIT_V(8); PG8_WAIT_L(0); PG8_BAR; PG8_MMA(1, 0, At, B0); PG8_MMA(1, 1, At, B1); PG8_BAR; PG8_SCHED;
;             PG8_LDB(B0, 1, 0); PG8_LDB(B1, 1, 1); PG8_SCHED; PG8_LDA(At, 1, 0); PG8_STAGE(PG8_SA(0, 1), a2 + hstep, voffA);
;             PG8_WAIT_V(8); PG8_WAIT_L(0); PG8_BAR; PG8_MMA(0, 0, At, B0); PG8_MMA(0, 1, At, B1); PG8_BAR; PG8_SCHED;
	s_setprio 1
	s_waitcnt lgkmcnt(0)
	v_mfma_f32_16x16x32_bf16 v[62:65], v[142:145], v[188:191], v[62:65]
	v_mfma_f32_16x16x32_bf16 v[58:61], v[164:167], v[188:191], v[58:61]
	v_mfma_f32_16x16x32_bf16 v[54:57], v[142:145], v[196:199], v[54:57]
	v_mfma_f32_16x16x32_bf16 v[42:45], v[164:167], v[196:199], v[42:45]
	v_mfma_f32_16x16x32_bf16 v[34:37], v[142:145], v[204:207], v[34:37]
	v_mfma_f32_16x16x32_bf16 v[26:29], v[164:167], v[204:207], v[26:29]
	v_mfma_f32_16x16x32_bf16 v[18:21], v[142:145], v[212:215], v[18:21]
	v_mfma_f32_16x16x32_bf16 v[10:13], v[164:167], v[212:215], v[10:13]
	v_mfma_f32_16x16x32_bf16 v[62:65], v[146:149], v[192:195], v[62:65]
	v_mfma_f32_16x16x32_bf16 v[58:61], v[168:171], v[192:195], v[58:61]
	v_mfma_f32_16x16x32_bf16 v[54:57], v[146:149], v[200:203], v[54:57]
	v_mfma_f32_16x16x32_bf16 v[42:45], v[168:171], v[200:203], v[42:45]
	v_mfma_f32_16x16x32_bf16 v[34:37], v[146:149], v[208:211], v[34:37]
	v_mfma_f32_16x16x32_bf16 v[26:29], v[168:171], v[208:211], v[26:29]
	v_mfma_f32_16x16x32_bf16 v[18:21], v[146:149], v[216:219], v[18:21]
	v_mfma_f32_16x16x32_bf16 v[10:13], v[168:171], v[216:219], v[10:13]
	v_mfma_f32_16x16x32_bf16 v[50:53], v[172:175], v[188:191], v[50:53]
	v_mfma_f32_16x16x32_bf16 v[46:49], v[180:183], v[188:191], v[46:49]
	v_mfma_f32_16x16x32_bf16 v[38:41], v[172:175], v[196:199], v[38:41]
	v_mfma_f32_16x16x32_bf16 v[30:33], v[180:183], v[196:199], v[30:33]
	v_mfma_f32_16x16x32_bf16 v[22:25], v[172:175], v[204:207], v[22:25]
	v_mfma_f32_16x16x32_bf16 v[14:17], v[180:183], v[204:207], v[14:17]
	v_mfma_f32_16x16x32_bf16 v[6:9], v[172:175], v[212:215], v[6:9]
	v_mfma_f32_16x16x32_bf16 v[2:5], v[180:183], v[212:215], v[2:5]
	v_mfma_f32_16x16x32_bf16 v[50:53], v[176:179], v[192:195], v[50:53]
	v_mfma_f32_16x16x32_bf16 v[46:49], v[184:187], v[192:195], v[46:49]
	v_mfma_f32_16x16x32_bf16 v[38:41], v[176:179], v[200:203], v[38:41]
	v_mfma_f32_16x16x32_bf16 v[30:33], v[184:187], v[200:203], v[30:33]
	v_mfma_f32_16x16x32_bf16 v[22:25], v[176:179], v[208:211], v[22:25]
	v_mfma_f32_16x16x32_bf16 v[14:17], v[184:187], v[208:211], v[14:17]
	v_mfma_f32_16x16x32_bf16 v[6:9], v[176:179], v[216:219], v[6:9]
	v_mfma_f32_16x16x32_bf16 v[2:5], v[184:187], v[216:219], v[2:5]
	s_setprio 0
	s_barrier
	s_add_i32 s83, 0, 0x18000
	v_add_u32_e32 v163, s83, v158
	s_add_i32 s84, 0, 0x1c000
	ds_read_b128 v[142:145], v163
	ds_read_b128 v[146:149], v163 offset:1024
	ds_read_b128 v[164:167], v163 offset:2048
	ds_read_b128 v[168:171], v163 offset:3072
	v_add_u32_e32 v163, s84, v158
	ds_read_b128 v[172:175], v163
	ds_read_b128 v[176:179], v163 offset:1024
	ds_read_b128 v[180:183], v163 offset:2048
	ds_read_b128 v[184:187], v163 offset:3072
	s_add_u32 s34, s64, 0x20000
	s_addc_u32 s35, s65, 0
	s_mov_b32 m0, s67
	v_lshl_add_u64 v[228:229], s[34:35], 0, v[130:131]
	ds_read_b128 v[188:191], v162 offset:32768
	ds_read_b128 v[192:195], v162 offset:33792
	ds_read_b128 v[196:199], v162 offset:34816
	ds_read_b128 v[200:203], v162 offset:35840
	ds_read_b128 v[204:207], v162 offset:36864
	ds_read_b128 v[208:211], v162 offset:37888
	ds_read_b128 v[212:215], v162 offset:38912
	ds_read_b128 v[216:219], v162 offset:39936
	global_load_lds_dwordx4 v[228:229], off
	v_lshl_add_u64 v[228:229], s[34:35], 0, v[132:133]
	s_mov_b32 m0, s68
	s_nop 0
	global_load_lds_dwordx4 v[228:229], off
	s_waitcnt vmcnt(8)
	s_waitcnt lgkmcnt(0)
	s_barrier
	s_setprio 1
	s_waitcnt lgkmcnt(0)
	v_mfma_f32_16x16x32_bf16 v[126:129], v[142:145], v[188:191], v[126:129]
	v_mfma_f32_16x16x32_bf16 v[122:125], v[164:167], v[188:191], v[122:125]
	v_mfma_f32_16x16x32_bf16 v[118:121], v[142:145], v[196:199], v[118:121]
	v_mfma_f32_16x16x32_bf16 v[106:109], v[164:167], v[196:199], v[106:109]
	v_mfma_f32_16x16x32_bf16 v[98:101], v[142:145], v[204:207], v[98:101]
	v_mfma_f32_16x16x32_bf16 v[90:93], v[164:167], v[204:207], v[90:93]
	v_mfma_f32_16x16x32_bf16 v[86:89], v[142:145], v[212:215], v[86:89]
	v_mfma_f32_16x16x32_bf16 v[74:77], v[164:167], v[212:215], v[74:77]
	v_mfma_f32_16x16x32_bf16 v[126:129], v[146:149], v[192:195], v[126:129]
	v_mfma_f32_16x16x32_bf16 v[122:125], v[168:171], v[192:195], v[122:125]
	v_mfma_f32_16x16x32_bf16 v[118:121], v[146:149], v[200:203], v[118:121]
	v_mfma_f32_16x16x32_bf16 v[106:109], v[168:171], v[200:203], v[106:109]
	v_mfma_f32_16x16x32_bf16 v[98:101], v[146:149], v[208:211], v[98:101]
	v_mfma_f32_16x16x32_bf16 v[90:93], v[168:171], v[208:211], v[90:93]
	v_mfma_f32_16x16x32_bf16 v[86:89], v[146:149], v[216:219], v[86:89]
	v_mfma_f32_16x16x32_bf16 v[74:77], v[168:171], v[216:219], v[74:77]
	v_mfma_f32_16x16x32_bf16 v[114:117], v[172:175], v[188:191], v[114:117]
	v_mfma_f32_16x16x32_bf16 v[110:113], v[180:183], v[188:191], v[110:113]
	v_mfma_f32_16x16x32_bf16 v[102:105], v[172:175], v[196:199], v[102:105]
	v_mfma_f32_16x16x32_bf16 v[94:97], v[180:183], v[196:199], v[94:97]
	v_mfma_f32_16x16x32_bf16 v[82:85], v[172:175], v[204:207], v[82:85]
	v_mfma_f32_16x16x32_bf16 v[78:81], v[180:183], v[204:207], v[78:81]
	v_mfma_f32_16x16x32_bf16 v[70:73], v[172:175], v[212:215], v[70:73]
	v_mfma_f32_16x16x32_bf16 v[66:69], v[180:183], v[212:215], v[66:69]
	v_mfma_f32_16x16x32_bf16 v[114:117], v[176:179], v[192:195], v[114:117]
	v_mfma_f32_16x16x32_bf16 v[110:113], v[184:187], v[192:195], v[110:113]
	v_mfma_f32_16x16x32_bf16 v[102:105], v[176:179], v[200:203], v[102:105]
	v_mfma_f32_16x16x32_bf16 v[94:97], v[184:187], v[200:203], v[94:97]
	v_mfma_f32_16x16x32_bf16 v[82:85], v[176:179], v[208:211], v[82:85]
	v_mfma_f32_16x16x32_bf16 v[78:81], v[184:187], v[208:211], v[78:81]
	v_mfma_f32_16x16x32_bf16 v[70:73], v[176:179], v[216:219], v[70:73]
	v_mfma_f32_16x16x32_bf16 v[66:69], v[184:187], v[216:219], v[66:69]
	s_setprio 0
	s_barrier
; #define PG8_STAGE(bufoff, gbase, voff) do { _Pragma("unroll") for (int _i = 0; _i < 2; ++_i) \
;         __builtin_amdgcn_global_load_lds((const unsigned*)((const char*)(gbase) + (voff)[_i]), (PG8_LAS unsigned*)(lds + (bufoff) + ldsw + _i * 8192), 16, 0, 0); } while (0)
; #define PG8_LDA(dst, b, h) do { _Pragma("unroll") for (int m = 0; m < 4; ++m) _Pragma("unroll") for (int k = 0; k < 2; ++k) dst[m][k] = *(const PG8_LAS bf16x8*)(lds + PG8_SA(b, h) + aoff + m * 2048 + k * 1024); } while (0)
; #define PG8_MMA(ai, bj, At, Bt) do { __builtin_amdgcn_s_setprio(1); _Pragma("unroll") for (int m = 0; m < 4; ++m) _Pragma("unroll") for (int n = 0; n < 2; ++n) _Pragma("unroll") for (int k = 0; k < 2; ++k) \
;         acc[ai][bj][m][n] = __builtin_amdgcn_mfma_f32_16x16x32_bf16(Bt[n][k], At[m][k], acc[ai][bj][m][n], 0, 0, 0); __builtin_amdgcn_s_setprio(0); } while (0)
; #define PG8_WAIT_V(n) asm volatile("s_waitcnt vmcnt(" #n ")" ::: "memory")
; #define PG8_WAIT_L(n) asm volatile("s_waitcnt lgkmcnt(" #n ")" ::: "memory")
; #define PG8_BAR __builtin_amdgcn_s_barrier()
; #define PG8_SCHED __builtin_amdgcn_sched_barrier(0)
; template <class Epi, class Sched, bool ALIGN_EPI = false, bool SP2 = false>
; __device__ __forceinline__ void gemm_phase(PG8_LAS unsigned char* lds, const Gemm g, const Sched& S, const Epi& E) {
;     ...
;             PG8_LDA(At, 1, 1); PG8_STAGE(PG8_SB(1, 0), b3, voffB); PG8_STAGE(PG8_SB(1, 1), b3 + hstep, voffB); PG8_STAGE(PG8_SA(1, 0), a3, voffA);
;             PG8_WAIT_V(8); PG8_WAIT_L(0); PG8_BAR; PG8_MMA(1, 0, At, B0); PG8_MMA(1, 1, At, B1); PG8_BAR; PG8_SCHED;
;     ...
;         if constexpr (ALIGN_EPI) { if (wr == 0) PG8_BAR; }
	s_add_i32 s34, s83, s19
	v_lshl_add_u64 v[220:221], v[220:221], 0, s[36:37]
	s_mov_b32 m0, s34
	ds_read_b128 v[188:191], v162 offset:49152
	ds_read_b128 v[192:195], v162 offset:50176
	ds_read_b128 v[196:199], v162 offset:51200
	ds_read_b128 v[200:203], v162 offset:52224
	ds_read_b128 v[204:207], v162 offset:53248
	ds_read_b128 v[208:211], v162 offset:54272
	ds_read_b128 v[212:215], v162 offset:55296
	ds_read_b128 v[216:219], v162 offset:56320
	global_load_lds_dwordx4 v[220:221], off
	s_add_i32 m0, s34, 0x2000
	s_add_u32 s34, s62, 0x20080
	v_lshl_add_u64 v[220:221], v[222:223], 0, s[36:37]
	s_addc_u32 s35, s63, 0
	s_add_i32 s62, s84, s19
	global_load_lds_dwordx4 v[220:221], off
	v_lshl_add_u64 v[220:221], s[34:35], 0, v[130:131]
	s_mov_b32 m0, s62
	s_nop 0
	global_load_lds_dwordx4 v[220:221], off
	v_lshl_add_u64 v[220:221], s[34:35], 0, v[132:133]
	s_add_i32 m0, s62, 0x2000
	s_nop 0
	global_load_lds_dwordx4 v[220:221], off
	v_lshl_add_u64 v[220:221], v[224:225], 0, s[36:37]
	s_mov_b32 m0, s70
	s_nop 0
	global_load_lds_dwordx4 v[220:221], off
	v_lshl_add_u64 v[220:221], v[226:227], 0, s[36:37]
	s_mov_b32 m0, s71
	s_nop 0
	global_load_lds_dwordx4 v[220:221], off
	s_waitcnt vmcnt(8)
	s_waitcnt lgkmcnt(0)
	s_barrier
	s_setprio 1
	s_waitcnt lgkmcnt(0)
	v_mfma_f32_16x16x32_bf16 v[62:65], v[142:145], v[188:191], v[62:65]
	v_mfma_f32_16x16x32_bf16 v[58:61], v[164:167], v[188:191], v[58:61]
	v_mfma_f32_16x16x32_bf16 v[54:57], v[142:145], v[196:199], v[54:57]
	v_mfma_f32_16x16x32_bf16 v[42:45], v[164:167], v[196:199], v[42:45]
	v_mfma_f32_16x16x32_bf16 v[34:37], v[142:145], v[204:207], v[34:37]
	v_mfma_f32_16x16x32_bf16 v[26:29], v[164:167], v[204:207], v[26:29]
	v_mfma_f32_16x16x32_bf16 v[18:21], v[142:145], v[212:215], v[18:21]
	v_mfma_f32_16x16x32_bf16 v[10:13], v[164:167], v[212:215], v[10:13]
	v_mfma_f32_16x16x32_bf16 v[62:65], v[146:149], v[192:195], v[62:65]
	v_mfma_f32_16x16x32_bf16 v[58:61], v[168:171], v[192:195], v[58:61]
	v_mfma_f32_16x16x32_bf16 v[54:57], v[146:149], v[200:203], v[54:57]
	v_mfma_f32_16x16x32_bf16 v[42:45], v[168:171], v[200:203], v[42:45]
	v_mfma_f32_16x16x32_bf16 v[34:37], v[146:149], v[208:211], v[34:37]
	v_mfma_f32_16x16x32_bf16 v[26:29], v[168:171], v[208:211], v[26:29]
	v_mfma_f32_16x16x32_bf16 v[18:21], v[146:149], v[216:219], v[18:21]
	v_mfma_f32_16x16x32_bf16 v[10:13], v[168:171], v[216:219], v[10:13]
	v_mfma_f32_16x16x32_bf16 v[50:53], v[172:175], v[188:191], v[50:53]
	v_mfma_f32_16x16x32_bf16 v[46:49], v[180:183], v[188:191], v[46:49]
	v_mfma_f32_16x16x32_bf16 v[38:41], v[172:175], v[196:199], v[38:41]
	v_mfma_f32_16x16x32_bf16 v[30:33], v[180:183], v[196:199], v[30:33]
	v_mfma_f32_16x16x32_bf16 v[22:25], v[172:175], v[204:207], v[22:25]
	v_mfma_f32_16x16x32_bf16 v[14:17], v[180:183], v[204:207], v[14:17]
	v_mfma_f32_16x16x32_bf16 v[6:9], v[172:175], v[212:215], v[6:9]
	v_mfma_f32_16x16x32_bf16 v[2:5], v[180:183], v[212:215], v[2:5]
	v_mfma_f32_16x16x32_bf16 v[50:53], v[176:179], v[192:195], v[50:53]
	v_mfma_f32_16x16x32_bf16 v[46:49], v[184:187], v[192:195], v[46:49]
	v_mfma_f32_16x16x32_bf16 v[38:41], v[176:179], v[200:203], v[38:41]
	v_mfma_f32_16x16x32_bf16 v[30:33], v[184:187], v[200:203], v[30:33]
	v_mfma_f32_16x16x32_bf16 v[22:25], v[176:179], v[208:211], v[22:25]
	v_mfma_f32_16x16x32_bf16 v[14:17], v[184:187], v[208:211], v[14:17]
	v_mfma_f32_16x16x32_bf16 v[6:9], v[176:179], v[216:219], v[6:9]
	v_mfma_f32_16x16x32_bf16 v[2:5], v[184:187], v[216:219], v[2:5]
	s_setprio 0
	s_barrier
	s_add_i32 s82, s82, 2
	s_add_u32 s60, s60, 0x100
	s_addc_u32 s61, s61, 0
	s_add_u32 s80, s80, 0x100
	s_addc_u32 s81, s81, 0
	s_cmp_gt_u32 s82, 5
	s_cbranch_scc0 .LBB0_1577
	s_and_b64 vcc, exec, s[38:39]
	s_cbranch_vccz .LBB0_1580
	s_barrier

; #define PG8_STAGE(bufoff, gbase, voff) do { _Pragma("unroll") for (int _i = 0; _i < 2; ++_i) \
;         __builtin_amdgcn_global_load_lds((const unsigned*)((const char*)(gbase) + (voff)[_i]), (PG8_LAS unsigned*)(lds + (bufoff) + ldsw + _i * 8192), 16, 0, 0); } while (0)
; #define PG8_LDA(dst, b, h) do { _Pragma("unroll") for (int m = 0; m < 4; ++m) _Pragma("unroll") for (int k = 0; k < 2; ++k) dst[m][k] = *(const PG8_LAS bf16x8*)(lds + PG8_SA(b, h) + aoff + m * 2048 + k * 1024); } while (0)
; #define PG8_LDB(dst, b, h) do { _Pragma("unroll") for (int n = 0; n < 2; ++n) _Pragma("unroll") for (int k = 0; k < 2; ++k) dst[n][k] = *(const PG8_LAS bf16x8*)(lds + PG8_SB(b, h) + boff + n * 2048 + k * 1024); } while (0)
; #define PG8_MMA(ai, bj, At, Bt) do { __builtin_amdgcn_s_setprio(1); _Pragma("unroll") for (int m = 0; m < 4; ++m) _Pragma("unroll") for (int n = 0; n < 2; ++n) _Pragma("unroll") for (int k = 0; k < 2; ++k) \
;         acc[ai][bj][m][n] = __builtin_amdgcn_mfma_f32_16x16x32_bf16(Bt[n][k], At[m][k], acc[ai][bj][m][n], 0, 0, 0); __builtin_amdgcn_s_setprio(0); } while (0)
; #define PG8_WAIT_V(n) asm volatile("s_waitcnt vmcnt(" #n ")" ::: "memory")
; #define PG8_WAIT_L(n) asm volatile("s_waitcnt lgkmcnt(" #n ")" ::: "memory")
; #define PG8_BAR __builtin_amdgcn_s_barrier()
; #define PG8_SCHED __builtin_amdgcn_sched_barrier(0)
; template <class Epi, class Sched, bool ALIGN_EPI = false, bool SP2 = false>
; __device__ __forceinline__ void gemm_phase(PG8_LAS unsigned char* lds, const Gemm g, const Sched& S, const Epi& E) {
;     ...
;         for (int t = 0; t < nt; t += 2) {
;             const bool last = (t == nt - 2);
;             const char* a1 = cA + (size_t)(t + 1) * kstep;
;             const char* a2 = last ? nA : cA + (size_t)(t + 2) * kstep; const char* b2 = last ? nB : cB + (size_t)(t + 2) * kstep;
;             const char* a3 = a2 + kstep; const char* b3 = b2 + kstep;
;             if (last && has_next) S.a_ready(nxt);
;             if constexpr (SP2) {
;             PG8_LDB(B0, 0, 0); PG8_LDB(B1, 0, 1); PG8_SCHED; PG8_LDA(At, 0, 0); PG8_STAGE(PG8_SA(1, 1), a1 + hstep, voffA);
;             PG8_WAIT_V(8); PG8_WAIT_L(0); PG8_BAR; PG8_MMA(0, 0, At, B0); PG8_MMA(0, 1, At, B1); PG8_BAR; PG8_SCHED;
;             PG8_LDA(At, 0, 1); PG8_STAGE(PG8_SB(0, 0), b2, voffB); PG8_STAGE(PG8_SB(0, 1), b2 + hstep, voffB); PG8_STAGE(PG8_SA(0, 0), a2, voffA);
.LBB0_1601:
	ds_read_b128 v[142:145], v1
	ds_read_b128 v[146:149], v1 offset:1024
	ds_read_b128 v[150:153], v1 offset:2048
	ds_read_b128 v[160:163], v1 offset:3072
	ds_read_b128 v[164:167], v156
	ds_read_b128 v[168:171], v156 offset:1024
	ds_read_b128 v[172:175], v156 offset:2048
	ds_read_b128 v[176:179], v156 offset:3072
	s_add_u32 s34, s56, 0xfffe0080
	s_addc_u32 s35, s57, -1
	s_cmp_eq_u32 s78, 4
	s_cselect_b32 s61, s49, s35
	s_cselect_b32 s60, s72, s34
	s_cselect_b32 s59, s47, s77
	s_cselect_b32 s58, s73, s76
	v_lshl_add_u64 v[212:213], s[56:57], 0, v[134:135]
	s_add_i32 m0, s55, 0xc000
	ds_read_b128 v[180:183], v158
	ds_read_b128 v[184:187], v158 offset:1024
	ds_read_b128 v[188:191], v158 offset:2048
	ds_read_b128 v[192:195], v158 offset:3072
	ds_read_b128 v[196:199], v158 offset:4096
	ds_read_b128 v[200:203], v158 offset:5120
	ds_read_b128 v[204:207], v158 offset:6144
	ds_read_b128 v[208:211], v158 offset:7168
	global_load_lds_dwordx4 v[212:213], off
	v_lshl_add_u64 v[212:213], s[56:57], 0, v[136:137]
	s_add_i32 m0, s55, 0xe000
	s_nop 0
	global_load_lds_dwordx4 v[212:213], off
	s_waitcnt vmcnt(8)
	s_waitcnt lgkmcnt(0)
	s_barrier
	s_setprio 1
	s_waitcnt lgkmcnt(0)
	v_mfma_f32_16x16x32_bf16 v[126:129], v[142:145], v[180:183], v[126:129]
	v_mfma_f32_16x16x32_bf16 v[122:125], v[150:153], v[180:183], v[122:125]
	v_mfma_f32_16x16x32_bf16 v[114:117], v[142:145], v[188:191], v[114:117]
	v_mfma_f32_16x16x32_bf16 v[106:109], v[150:153], v[188:191], v[106:109]
	v_mfma_f32_16x16x32_bf16 v[94:97], v[142:145], v[196:199], v[94:97]
	v_mfma_f32_16x16x32_bf16 v[90:93], v[150:153], v[196:199], v[90:93]
	v_mfma_f32_16x16x32_bf16 v[82:85], v[142:145], v[204:207], v[82:85]
	v_mfma_f32_16x16x32_bf16 v[74:77], v[150:153], v[204:207], v[74:77]
	v_mfma_f32_16x16x32_bf16 v[126:129], v[146:149], v[184:187], v[126:129]
	v_mfma_f32_16x16x32_bf16 v[122:125], v[160:163], v[184:187], v[122:125]
	v_mfma_f32_16x16x32_bf16 v[114:117], v[146:149], v[192:195], v[114:117]
	v_mfma_f32_16x16x32_bf16 v[106:109], v[160:163], v[192:195], v[106:109]
	v_mfma_f32_16x16x32_bf16 v[94:97], v[146:149], v[200:203], v[94:97]
	v_mfma_f32_16x16x32_bf16 v[90:93], v[160:163], v[200:203], v[90:93]
	v_mfma_f32_16x16x32_bf16 v[82:85], v[146:149], v[208:211], v[82:85]
	v_mfma_f32_16x16x32_bf16 v[74:77], v[160:163], v[208:211], v[74:77]
	v_mfma_f32_16x16x32_bf16 v[118:121], v[164:167], v[180:183], v[118:121]
	v_mfma_f32_16x16x32_bf16 v[110:113], v[172:175], v[180:183], v[110:113]
	v_mfma_f32_16x16x32_bf16 v[102:105], v[164:167], v[188:191], v[102:105]
	v_mfma_f32_16x16x32_bf16 v[98:101], v[172:175], v[188:191], v[98:101]
	v_mfma_f32_16x16x32_bf16 v[86:89], v[164:167], v[196:199], v[86:89]
	v_mfma_f32_16x16x32_bf16 v[78:81], v[172:175], v[196:199], v[78:81]
	v_mfma_f32_16x16x32_bf16 v[70:73], v[164:167], v[204:207], v[70:73]
	v_mfma_f32_16x16x32_bf16 v[66:69], v[172:175], v[204:207], v[66:69]
	v_mfma_f32_16x16x32_bf16 v[118:121], v[168:171], v[184:187], v[118:121]
	v_mfma_f32_16x16x32_bf16 v[110:113], v[176:179], v[184:187], v[110:113]
	v_mfma_f32_16x16x32_bf16 v[102:105], v[168:171], v[192:195], v[102:105]
	v_mfma_f32_16x16x32_bf16 v[98:101], v[176:179], v[192:195], v[98:101]
	v_mfma_f32_16x16x32_bf16 v[86:89], v[168:171], v[200:203], v[86:89]
	v_mfma_f32_16x16x32_bf16 v[78:81], v[176:179], v[200:203], v[78:81]
	v_mfma_f32_16x16x32_bf16 v[70:73], v[168:171], v[208:211], v[70:73]
	v_mfma_f32_16x16x32_bf16 v[66:69], v[176:179], v[208:211], v[66:69]
	s_setprio 0
	s_barrier
	s_add_i32 s34, s69, s19
	v_lshl_add_u64 v[212:213], s[58:59], 0, v[130:131]
	s_mov_b32 m0, s34
	ds_read_b128 v[180:183], v158 offset:16384
	ds_read_b128 v[184:187], v158 offset:17408
	ds_read_b128 v[188:191], v158 offset:18432
	ds_read_b128 v[192:195], v158 offset:19456
	ds_read_b128 v[196:199], v158 offset:20480
	ds_read_b128 v[200:203], v158 offset:21504
	ds_read_b128 v[204:207], v158 offset:22528
	ds_read_b128 v[208:211], v158 offset:23552
	global_load_lds_dwordx4 v[212:213], off
	s_add_i32 m0, s34, 0x2000
	s_add_u32 s34, s58, 0x20000
	v_lshl_add_u64 v[214:215], s[58:59], 0, v[132:133]
	s_addc_u32 s35, s59, 0
	s_add_i32 s79, s70, s19
	global_load_lds_dwordx4 v[214:215], off
	v_lshl_add_u64 v[216:217], s[34:35], 0, v[130:131]
	s_mov_b32 m0, s79
	v_lshl_add_u64 v[218:219], s[60:61], 0, v[132:133]
	global_load_lds_dwordx4 v[216:217], off
	v_lshl_add_u64 v[216:217], s[34:35], 0, v[132:133]
	s_add_i32 m0, s79, 0x2000
	s_nop 0
	global_load_lds_dwordx4 v[216:217], off
	v_lshl_add_u64 v[216:217], s[60:61], 0, v[130:131]
	s_mov_b32 m0, s55
	s_nop 0
	global_load_lds_dwordx4 v[216:217], off
	s_mov_b32 m0, s62
	s_nop 0
	global_load_lds_dwordx4 v[218:219], off
	s_waitcnt vmcnt(8)
	s_waitcnt lgkmcnt(0)
	s_barrier
; #define PG8_STAGE(bufoff, gbase, voff) do { _Pragma("unroll") for (int _i = 0; _i < 2; ++_i) \
;         __builtin_amdgcn_global_load_lds((const unsigned*)((const char*)(gbase) + (voff)[_i]), (PG8_LAS unsigned*)(lds + (bufoff) + ldsw + _i * 8192), 16, 0, 0); } while (0)
; #define PG8_LDA(dst, b, h) do { _Pragma("unroll") for (int m = 0; m < 4; ++m) _Pragma("unroll") for (int k = 0; k < 2; ++k) dst[m][k] = *(const PG8_LAS bf16x8*)(lds + PG8_SA(b, h) + aoff + m * 2048 + k * 1024); } while (0)
; #define PG8_LDB(dst, b, h) do { _Pragma("unroll") for (int n = 0; n < 2; ++n) _Pragma("unroll") for (int k = 0; k < 2; ++k) dst[n][k] = *(const PG8_LAS bf16x8*)(lds + PG8_SB(b, h) + boff + n * 2048 + k * 1024); } while (0)
; #define PG8_MMA(ai, bj, At, Bt) do { __builtin_amdgcn_s_setprio(1); _Pragma("unroll") for (int m = 0; m < 4; ++m) _Pragma("unroll") for (int n = 0; n < 2; ++n) _Pragma("unroll") for (int k = 0; k < 2; ++k) \
;         acc[ai][bj][m][n] = __builtin_amdgcn_mfma_f32_16x16x32_bf16(Bt[n][k], At[m][k], acc[ai][bj][m][n], 0, 0, 0); __builtin_amdgcn_s_setprio(0); } while (0)
; #define PG8_WAIT_V(n) asm volatile("s_waitcnt vmcnt(" #n ")" ::: "memory")
; #define PG8_WAIT_L(n) asm volatile("s_waitcnt lgkmcnt(" #n ")" ::: "memory")
; #define PG8_BAR __builtin_amdgcn_s_barrier()
; #define PG8_SCHED __builtin_amdgcn_sched_barrier(0)
; template <class Epi, class Sched, bool ALIGN_EPI = false, bool SP2 = false>
; __device__ __forceinline__ void gemm_phase(PG8_LAS unsigned char* lds, const Gemm g, const Sched& S, const Epi& E) {
;     ...
;             PG8_WAIT_V(8); PG8_WAIT_L(0); PG8_BAR; PG8_MMA(1, 0, At, B0); PG8_MMA(1, 1, At, B1); PG8_BAR; PG8_SCHED;
;             PG8_LDB(B0, 1, 0); PG8_LDB(B1, 1, 1); PG8_SCHED; PG8_LDA(At, 1, 0); PG8_STAGE(PG8_SA(0, 1), a2 + hstep, voffA);
;             PG8_WAIT_V(8); PG8_WAIT_L(0); PG8_BAR; PG8_MMA(0, 0, At, B0); PG8_MMA(0, 1, At, B1); PG8_BAR; PG8_SCHED;
	s_setprio 1
	s_waitcnt lgkmcnt(0)
	v_mfma_f32_16x16x32_bf16 v[62:65], v[142:145], v[180:183], v[62:65]
	v_mfma_f32_16x16x32_bf16 v[58:61], v[150:153], v[180:183], v[58:61]
	v_mfma_f32_16x16x32_bf16 v[50:53], v[142:145], v[188:191], v[50:53]
	v_mfma_f32_16x16x32_bf16 v[42:45], v[150:153], v[188:191], v[42:45]
	v_mfma_f32_16x16x32_bf16 v[30:33], v[142:145], v[196:199], v[30:33]
	v_mfma_f32_16x16x32_bf16 v[26:29], v[150:153], v[196:199], v[26:29]
	v_mfma_f32_16x16x32_bf16 v[18:21], v[142:145], v[204:207], v[18:21]
	v_mfma_f32_16x16x32_bf16 v[10:13], v[150:153], v[204:207], v[10:13]
	v_mfma_f32_16x16x32_bf16 v[62:65], v[146:149], v[184:187], v[62:65]
	v_mfma_f32_16x16x32_bf16 v[58:61], v[160:163], v[184:187], v[58:61]
	v_mfma_f32_16x16x32_bf16 v[50:53], v[146:149], v[192:195], v[50:53]
	v_mfma_f32_16x16x32_bf16 v[42:45], v[160:163], v[192:195], v[42:45]
	v_mfma_f32_16x16x32_bf16 v[30:33], v[146:149], v[200:203], v[30:33]
	v_mfma_f32_16x16x32_bf16 v[26:29], v[160:163], v[200:203], v[26:29]
	v_mfma_f32_16x16x32_bf16 v[18:21], v[146:149], v[208:211], v[18:21]
	v_mfma_f32_16x16x32_bf16 v[10:13], v[160:163], v[208:211], v[10:13]
	v_mfma_f32_16x16x32_bf16 v[54:57], v[164:167], v[180:183], v[54:57]
	v_mfma_f32_16x16x32_bf16 v[46:49], v[172:175], v[180:183], v[46:49]
	v_mfma_f32_16x16x32_bf16 v[38:41], v[164:167], v[188:191], v[38:41]
	v_mfma_f32_16x16x32_bf16 v[34:37], v[172:175], v[188:191], v[34:37]
	v_mfma_f32_16x16x32_bf16 v[22:25], v[164:167], v[196:199], v[22:25]
	v_mfma_f32_16x16x32_bf16 v[14:17], v[172:175], v[196:199], v[14:17]
	v_mfma_f32_16x16x32_bf16 v[6:9], v[164:167], v[204:207], v[6:9]
	v_mfma_f32_16x16x32_bf16 v[2:5], v[172:175], v[204:207], v[2:5]
	v_mfma_f32_16x16x32_bf16 v[54:57], v[168:171], v[184:187], v[54:57]
	v_mfma_f32_16x16x32_bf16 v[46:49], v[176:179], v[184:187], v[46:49]
	v_mfma_f32_16x16x32_bf16 v[38:41], v[168:171], v[192:195], v[38:41]
	v_mfma_f32_16x16x32_bf16 v[34:37], v[176:179], v[192:195], v[34:37]
	v_mfma_f32_16x16x32_bf16 v[22:25], v[168:171], v[200:203], v[22:25]
	v_mfma_f32_16x16x32_bf16 v[14:17], v[176:179], v[200:203], v[14:17]
	v_mfma_f32_16x16x32_bf16 v[6:9], v[168:171], v[208:211], v[6:9]
	v_mfma_f32_16x16x32_bf16 v[2:5], v[176:179], v[208:211], v[2:5]
	s_setprio 0
	s_barrier
	s_add_i32 s79, 0, 0x18000
	v_add_u32_e32 v159, s79, v154
	s_add_i32 s80, 0, 0x1c000
	ds_read_b128 v[142:145], v159
	ds_read_b128 v[146:149], v159 offset:1024
	ds_read_b128 v[150:153], v159 offset:2048
	ds_read_b128 v[160:163], v159 offset:3072
	v_add_u32_e32 v159, s80, v154
	ds_read_b128 v[164:167], v159
	ds_read_b128 v[168:171], v159 offset:1024
	ds_read_b128 v[172:175], v159 offset:2048
	ds_read_b128 v[176:179], v159 offset:3072
	s_add_u32 s34, s60, 0x20000
	s_addc_u32 s35, s61, 0
	s_mov_b32 m0, s63
	v_lshl_add_u64 v[220:221], s[34:35], 0, v[130:131]
	ds_read_b128 v[180:183], v158 offset:32768
	ds_read_b128 v[184:187], v158 offset:33792
	ds_read_b128 v[188:191], v158 offset:34816
	ds_read_b128 v[192:195], v158 offset:35840
	ds_read_b128 v[196:199], v158 offset:36864
	ds_read_b128 v[200:203], v158 offset:37888
	ds_read_b128 v[204:207], v158 offset:38912
	ds_read_b128 v[208:211], v158 offset:39936
	global_load_lds_dwordx4 v[220:221], off
	v_lshl_add_u64 v[220:221], s[34:35], 0, v[132:133]
	s_mov_b32 m0, s64
	s_nop 0
	global_load_lds_dwordx4 v[220:221], off
	s_waitcnt vmcnt(8)
	s_waitcnt lgkmcnt(0)
	s_barrier
	s_setprio 1
	s_waitcnt lgkmcnt(0)
	v_mfma_f32_16x16x32_bf16 v[126:129], v[142:145], v[180:183], v[126:129]
	v_mfma_f32_16x16x32_bf16 v[122:125], v[150:153], v[180:183], v[122:125]
	v_mfma_f32_16x16x32_bf16 v[114:117], v[142:145], v[188:191], v[114:117]
	v_mfma_f32_16x16x32_bf16 v[106:109], v[150:153], v[188:191], v[106:109]
	v_mfma_f32_16x16x32_bf16 v[94:97], v[142:145], v[196:199], v[94:97]
	v_mfma_f32_16x16x32_bf16 v[90:93], v[150:153], v[196:199], v[90:93]
	v_mfma_f32_16x16x32_bf16 v[82:85], v[142:145], v[204:207], v[82:85]
	v_mfma_f32_16x16x32_bf16 v[74:77], v[150:153], v[204:207], v[74:77]
	v_mfma_f32_16x16x32_bf16 v[126:129], v[146:149], v[184:187], v[126:129]
	v_mfma_f32_16x16x32_bf16 v[122:125], v[160:163], v[184:187], v[122:125]
	v_mfma_f32_16x16x32_bf16 v[114:117], v[146:149], v[192:195], v[114:117]
	v_mfma_f32_16x16x32_bf16 v[106:109], v[160:163], v[192:195], v[106:109]
	v_mfma_f32_16x16x32_bf16 v[94:97], v[146:149], v[200:203], v[94:97]
	v_mfma_f32_16x16x32_bf16 v[90:93], v[160:163], v[200:203], v[90:93]
	v_mfma_f32_16x16x32_bf16 v[82:85], v[146:149], v[208:211], v[82:85]
	v_mfma_f32_16x16x32_bf16 v[74:77], v[160:163], v[208:211], v[74:77]
	v_mfma_f32_16x16x32_bf16 v[118:121], v[164:167], v[180:183], v[118:121]
	v_mfma_f32_16x16x32_bf16 v[110:113], v[172:175], v[180:183], v[110:113]
	v_mfma_f32_16x16x32_bf16 v[102:105], v[164:167], v[188:191], v[102:105]
	v_mfma_f32_16x16x32_bf16 v[98:101], v[172:175], v[188:191], v[98:101]
	v_mfma_f32_16x16x32_bf16 v[86:89], v[164:167], v[196:199], v[86:89]
	v_mfma_f32_16x16x32_bf16 v[78:81], v[172:175], v[196:199], v[78:81]
	v_mfma_f32_16x16x32_bf16 v[70:73], v[164:167], v[204:207], v[70:73]
	v_mfma_f32_16x16x32_bf16 v[66:69], v[172:175], v[204:207], v[66:69]
	v_mfma_f32_16x16x32_bf16 v[118:121], v[168:171], v[184:187], v[118:121]
	v_mfma_f32_16x16x32_bf16 v[110:113], v[176:179], v[184:187], v[110:113]
	v_mfma_f32_16x16x32_bf16 v[102:105], v[168:171], v[192:195], v[102:105]
	v_mfma_f32_16x16x32_bf16 v[98:101], v[176:179], v[192:195], v[98:101]
	v_mfma_f32_16x16x32_bf16 v[86:89], v[168:171], v[200:203], v[86:89]
	v_mfma_f32_16x16x32_bf16 v[78:81], v[176:179], v[200:203], v[78:81]
	v_mfma_f32_16x16x32_bf16 v[70:73], v[168:171], v[208:211], v[70:73]
	v_mfma_f32_16x16x32_bf16 v[66:69], v[176:179], v[208:211], v[66:69]
	s_setprio 0
	s_barrier
; #define PG8_STAGE(bufoff, gbase, voff) do { _Pragma("unroll") for (int _i = 0; _i < 2; ++_i) \
;         __builtin_amdgcn_global_load_lds((const unsigned*)((const char*)(gbase) + (voff)[_i]), (PG8_LAS unsigned*)(lds + (bufoff) + ldsw + _i * 8192), 16, 0, 0); } while (0)
; #define PG8_LDA(dst, b, h) do { _Pragma("unroll") for (int m = 0; m < 4; ++m) _Pragma("unroll") for (int k = 0; k < 2; ++k) dst[m][k] = *(const PG8_LAS bf16x8*)(lds + PG8_SA(b, h) + aoff + m * 2048 + k * 1024); } while (0)
; #define PG8_MMA(ai, bj, At, Bt) do { __builtin_amdgcn_s_setprio(1); _Pragma("unroll") for (int m = 0; m < 4; ++m) _Pragma("unroll") for (int n = 0; n < 2; ++n) _Pragma("unroll") for (int k = 0; k < 2; ++k) \
;         acc[ai][bj][m][n] = __builtin_amdgcn_mfma_f32_16x16x32_bf16(Bt[n][k], At[m][k], acc[ai][bj][m][n], 0, 0, 0); __builtin_amdgcn_s_setprio(0); } while (0)
; #define PG8_WAIT_V(n) asm volatile("s_waitcnt vmcnt(" #n ")" ::: "memory")
; #define PG8_WAIT_L(n) asm volatile("s_waitcnt lgkmcnt(" #n ")" ::: "memory")
; #define PG8_BAR __builtin_amdgcn_s_barrier()
; #define PG8_SCHED __builtin_amdgcn_sched_barrier(0)
; template <class Epi, class Sched, bool ALIGN_EPI = false, bool SP2 = false>
; __device__ __forceinline__ void gemm_phase(PG8_LAS unsigned char* lds, const Gemm g, const Sched& S, const Epi& E) {
;     ...
;             PG8_LDA(At, 1, 1); PG8_STAGE(PG8_SB(1, 0), b3, voffB); PG8_STAGE(PG8_SB(1, 1), b3 + hstep, voffB); PG8_STAGE(PG8_SA(1, 0), a3, voffA);
;             PG8_WAIT_V(8); PG8_WAIT_L(0); PG8_BAR; PG8_MMA(1, 0, At, B0); PG8_MMA(1, 1, At, B1); PG8_BAR; PG8_SCHED;
;     ...
;         if constexpr (ALIGN_EPI) { if (wr == 0) PG8_BAR; }
	s_add_i32 s34, s79, s19
	v_lshl_add_u64 v[212:213], v[212:213], 0, s[42:43]
	s_mov_b32 m0, s34
	ds_read_b128 v[180:183], v158 offset:49152
	ds_read_b128 v[184:187], v158 offset:50176
	ds_read_b128 v[188:191], v158 offset:51200
	ds_read_b128 v[192:195], v158 offset:52224
	ds_read_b128 v[196:199], v158 offset:53248
	ds_read_b128 v[200:203], v158 offset:54272
	ds_read_b128 v[204:207], v158 offset:55296
	ds_read_b128 v[208:211], v158 offset:56320
	global_load_lds_dwordx4 v[212:213], off
	s_add_i32 m0, s34, 0x2000
	s_add_u32 s34, s58, 0x20080
	v_lshl_add_u64 v[212:213], v[214:215], 0, s[42:43]
	s_addc_u32 s35, s59, 0
	s_add_i32 s58, s80, s19
	global_load_lds_dwordx4 v[212:213], off
	v_lshl_add_u64 v[212:213], s[34:35], 0, v[130:131]
	s_mov_b32 m0, s58
	s_nop 0
	global_load_lds_dwordx4 v[212:213], off
	v_lshl_add_u64 v[212:213], s[34:35], 0, v[132:133]
	s_add_i32 m0, s58, 0x2000
	s_nop 0
	global_load_lds_dwordx4 v[212:213], off
	v_lshl_add_u64 v[212:213], v[216:217], 0, s[42:43]
	s_mov_b32 m0, s66
	s_nop 0
	global_load_lds_dwordx4 v[212:213], off
	v_lshl_add_u64 v[212:213], v[218:219], 0, s[42:43]
	s_mov_b32 m0, s67
	s_nop 0
	global_load_lds_dwordx4 v[212:213], off
	s_waitcnt vmcnt(8)
	s_waitcnt lgkmcnt(0)
	s_barrier
	s_setprio 1
	s_waitcnt lgkmcnt(0)
	v_mfma_f32_16x16x32_bf16 v[62:65], v[142:145], v[180:183], v[62:65]
	v_mfma_f32_16x16x32_bf16 v[58:61], v[150:153], v[180:183], v[58:61]
	v_mfma_f32_16x16x32_bf16 v[50:53], v[142:145], v[188:191], v[50:53]
	v_mfma_f32_16x16x32_bf16 v[42:45], v[150:153], v[188:191], v[42:45]
	v_mfma_f32_16x16x32_bf16 v[30:33], v[142:145], v[196:199], v[30:33]
	v_mfma_f32_16x16x32_bf16 v[26:29], v[150:153], v[196:199], v[26:29]
	v_mfma_f32_16x16x32_bf16 v[18:21], v[142:145], v[204:207], v[18:21]
	v_mfma_f32_16x16x32_bf16 v[10:13], v[150:153], v[204:207], v[10:13]
	v_mfma_f32_16x16x32_bf16 v[62:65], v[146:149], v[184:187], v[62:65]
	v_mfma_f32_16x16x32_bf16 v[58:61], v[160:163], v[184:187], v[58:61]
	v_mfma_f32_16x16x32_bf16 v[50:53], v[146:149], v[192:195], v[50:53]
	v_mfma_f32_16x16x32_bf16 v[42:45], v[160:163], v[192:195], v[42:45]
	v_mfma_f32_16x16x32_bf16 v[30:33], v[146:149], v[200:203], v[30:33]
	v_mfma_f32_16x16x32_bf16 v[26:29], v[160:163], v[200:203], v[26:29]
	v_mfma_f32_16x16x32_bf16 v[18:21], v[146:149], v[208:211], v[18:21]
	v_mfma_f32_16x16x32_bf16 v[10:13], v[160:163], v[208:211], v[10:13]
	v_mfma_f32_16x16x32_bf16 v[54:57], v[164:167], v[180:183], v[54:57]
	v_mfma_f32_16x16x32_bf16 v[46:49], v[172:175], v[180:183], v[46:49]
	v_mfma_f32_16x16x32_bf16 v[38:41], v[164:167], v[188:191], v[38:41]
	v_mfma_f32_16x16x32_bf16 v[34:37], v[172:175], v[188:191], v[34:37]
	v_mfma_f32_16x16x32_bf16 v[22:25], v[164:167], v[196:199], v[22:25]
	v_mfma_f32_16x16x32_bf16 v[14:17], v[172:175], v[196:199], v[14:17]
	v_mfma_f32_16x16x32_bf16 v[6:9], v[164:167], v[204:207], v[6:9]
	v_mfma_f32_16x16x32_bf16 v[2:5], v[172:175], v[204:207], v[2:5]
	v_mfma_f32_16x16x32_bf16 v[54:57], v[168:171], v[184:187], v[54:57]
	v_mfma_f32_16x16x32_bf16 v[46:49], v[176:179], v[184:187], v[46:49]
	v_mfma_f32_16x16x32_bf16 v[38:41], v[168:171], v[192:195], v[38:41]
	v_mfma_f32_16x16x32_bf16 v[34:37], v[176:179], v[192:195], v[34:37]
	v_mfma_f32_16x16x32_bf16 v[22:25], v[168:171], v[200:203], v[22:25]
	v_mfma_f32_16x16x32_bf16 v[14:17], v[176:179], v[200:203], v[14:17]
	v_mfma_f32_16x16x32_bf16 v[6:9], v[168:171], v[208:211], v[6:9]
	v_mfma_f32_16x16x32_bf16 v[2:5], v[176:179], v[208:211], v[2:5]
	s_setprio 0
	s_barrier
	s_add_i32 s78, s78, 2
	s_add_u32 s56, s56, 0x100
	s_addc_u32 s57, s57, 0
	s_add_u32 s76, s76, 0x100
	s_addc_u32 s77, s77, 0
	s_cmp_gt_u32 s78, 5
	s_cbranch_scc0 .LBB0_1601
	s_and_b64 vcc, exec, s[44:45]
	s_cbranch_vccz .LBB0_1604
	s_barrier

; #define PG8_STAGE(bufoff, gbase, voff) do { _Pragma("unroll") for (int _i = 0; _i < 2; ++_i) \
;         __builtin_amdgcn_global_load_lds((const unsigned*)((const char*)(gbase) + (voff)[_i]), (PG8_LAS unsigned*)(lds + (bufoff) + ldsw + _i * 8192), 16, 0, 0); } while (0)
; #define PG8_LDA(dst, b, h) do { _Pragma("unroll") for (int m = 0; m < 4; ++m) _Pragma("unroll") for (int k = 0; k < 2; ++k) dst[m][k] = *(const PG8_LAS bf16x8*)(lds + PG8_SA(b, h) + aoff + m * 2048 + k * 1024); } while (0)
; #define PG8_LDB(dst, b, h) do { _Pragma("unroll") for (int n = 0; n < 2; ++n) _Pragma("unroll") for (int k = 0; k < 2; ++k) dst[n][k] = *(const PG8_LAS bf16x8*)(lds + PG8_SB(b, h) + boff + n * 2048 + k * 1024); } while (0)
; #define PG8_MMA(ai, bj, At, Bt) do { __builtin_amdgcn_s_setprio(1); _Pragma("unroll") for (int m = 0; m < 4; ++m) _Pragma("unroll") for (int n = 0; n < 2; ++n) _Pragma("unroll") for (int k = 0; k < 2; ++k) \
;         acc[ai][bj][m][n] = __builtin_amdgcn_mfma_f32_16x16x32_bf16(Bt[n][k], At[m][k], acc[ai][bj][m][n], 0, 0, 0); __builtin_amdgcn_s_setprio(0); } while (0)
; #define PG8_WAIT_V(n) asm volatile("s_waitcnt vmcnt(" #n ")" ::: "memory")
; #define PG8_WAIT_L(n) asm volatile("s_waitcnt lgkmcnt(" #n ")" ::: "memory")
; #define PG8_BAR __builtin_amdgcn_s_barrier()
; #define PG8_SCHED __builtin_amdgcn_sched_barrier(0)
; template <class Epi, class Sched, bool ALIGN_EPI = false, bool SP2 = false>
; __device__ __forceinline__ void gemm_phase(PG8_LAS unsigned char* lds, const Gemm g, const Sched& S, const Epi& E) {
;     ...
;         for (int t = 0; t < nt; t += 2) {
;             const bool last = (t == nt - 2);
;             const char* a1 = cA + (size_t)(t + 1) * kstep;
;             const char* a2 = last ? nA : cA + (size_t)(t + 2) * kstep; const char* b2 = last ? nB : cB + (size_t)(t + 2) * kstep;
;             const char* a3 = a2 + kstep; const char* b3 = b2 + kstep;
;             if (last && has_next) S.a_ready(nxt);
;             if constexpr (SP2) {
;             PG8_LDB(B0, 0, 0); PG8_LDB(B1, 0, 1); PG8_SCHED; PG8_LDA(At, 0, 0); PG8_STAGE(PG8_SA(1, 1), a1 + hstep, voffA);
;             PG8_WAIT_V(8); PG8_WAIT_L(0); PG8_BAR; PG8_MMA(0, 0, At, B0); PG8_MMA(0, 1, At, B1); PG8_BAR; PG8_SCHED;
;             PG8_LDA(At, 0, 1); PG8_STAGE(PG8_SB(0, 0), b2, voffB); PG8_STAGE(PG8_SB(0, 1), b2 + hstep, voffB); PG8_STAGE(PG8_SA(0, 0), a2, voffA);
.LBB0_1746:
	ds_read_b128 v[130:133], v173
	ds_read_b128 v[148:151], v173 offset:1024
	ds_read_b128 v[178:181], v173 offset:2048
	ds_read_b128 v[182:185], v173 offset:3072
	ds_read_b128 v[186:189], v174
	ds_read_b128 v[190:193], v174 offset:1024
	ds_read_b128 v[194:197], v174 offset:2048
	ds_read_b128 v[198:201], v174 offset:3072
	s_add_u32 s50, s10, 0xfffc0080
	s_addc_u32 s51, s11, -1
	s_cmp_eq_u32 s80, 12
	s_cselect_b32 s53, s9, s51
	s_cselect_b32 s52, s43, s50
	s_cselect_b32 s51, s41, s79
	s_cselect_b32 s50, s77, s78
	v_lshl_add_u64 v[166:167], s[10:11], 0, v[140:141]
	s_add_i32 m0, s49, 0xc000
	ds_read_b128 v[202:205], v175
	ds_read_b128 v[206:209], v175 offset:1024
	ds_read_b128 v[210:213], v175 offset:2048
	ds_read_b128 v[214:217], v175 offset:3072
	ds_read_b128 v[218:221], v175 offset:4096
	ds_read_b128 v[222:225], v175 offset:5120
	ds_read_b128 v[226:229], v175 offset:6144
	ds_read_b128 v[230:233], v175 offset:7168
	global_load_lds_dwordx4 v[166:167], off
	v_lshl_add_u64 v[166:167], s[10:11], 0, v[142:143]
	s_add_i32 m0, s49, 0xe000
	s_nop 0
	global_load_lds_dwordx4 v[166:167], off
	s_waitcnt vmcnt(8)
	s_waitcnt lgkmcnt(0)
	s_barrier
	s_setprio 1
	s_waitcnt lgkmcnt(0)
	v_mfma_f32_16x16x32_bf16 v[126:129], v[130:133], v[202:205], v[126:129]
	v_mfma_f32_16x16x32_bf16 v[122:125], v[178:181], v[202:205], v[122:125]
	v_mfma_f32_16x16x32_bf16 v[110:113], v[130:133], v[210:213], v[110:113]
	v_mfma_f32_16x16x32_bf16 v[106:109], v[178:181], v[210:213], v[106:109]
	v_mfma_f32_16x16x32_bf16 v[94:97], v[130:133], v[218:221], v[94:97]
	v_mfma_f32_16x16x32_bf16 v[90:93], v[178:181], v[218:221], v[90:93]
	v_mfma_f32_16x16x32_bf16 v[78:81], v[130:133], v[226:229], v[78:81]
	v_mfma_f32_16x16x32_bf16 v[74:77], v[178:181], v[226:229], v[74:77]
	v_mfma_f32_16x16x32_bf16 v[126:129], v[148:151], v[206:209], v[126:129]
	v_mfma_f32_16x16x32_bf16 v[122:125], v[182:185], v[206:209], v[122:125]
	v_mfma_f32_16x16x32_bf16 v[110:113], v[148:151], v[214:217], v[110:113]
	v_mfma_f32_16x16x32_bf16 v[106:109], v[182:185], v[214:217], v[106:109]
	v_mfma_f32_16x16x32_bf16 v[94:97], v[148:151], v[222:225], v[94:97]
	v_mfma_f32_16x16x32_bf16 v[90:93], v[182:185], v[222:225], v[90:93]
	v_mfma_f32_16x16x32_bf16 v[78:81], v[148:151], v[230:233], v[78:81]
	v_mfma_f32_16x16x32_bf16 v[74:77], v[182:185], v[230:233], v[74:77]
	v_mfma_f32_16x16x32_bf16 v[118:121], v[186:189], v[202:205], v[118:121]
	v_mfma_f32_16x16x32_bf16 v[114:117], v[194:197], v[202:205], v[114:117]
	v_mfma_f32_16x16x32_bf16 v[102:105], v[186:189], v[210:213], v[102:105]
	v_mfma_f32_16x16x32_bf16 v[98:101], v[194:197], v[210:213], v[98:101]
	v_mfma_f32_16x16x32_bf16 v[86:89], v[186:189], v[218:221], v[86:89]
	v_mfma_f32_16x16x32_bf16 v[82:85], v[194:197], v[218:221], v[82:85]
	v_mfma_f32_16x16x32_bf16 v[70:73], v[186:189], v[226:229], v[70:73]
	v_mfma_f32_16x16x32_bf16 v[66:69], v[194:197], v[226:229], v[66:69]
	v_mfma_f32_16x16x32_bf16 v[118:121], v[190:193], v[206:209], v[118:121]
	v_mfma_f32_16x16x32_bf16 v[114:117], v[198:201], v[206:209], v[114:117]
	v_mfma_f32_16x16x32_bf16 v[102:105], v[190:193], v[214:217], v[102:105]
	v_mfma_f32_16x16x32_bf16 v[98:101], v[198:201], v[214:217], v[98:101]
	v_mfma_f32_16x16x32_bf16 v[86:89], v[190:193], v[222:225], v[86:89]
	v_mfma_f32_16x16x32_bf16 v[82:85], v[198:201], v[222:225], v[82:85]
	v_mfma_f32_16x16x32_bf16 v[70:73], v[190:193], v[230:233], v[70:73]
	v_mfma_f32_16x16x32_bf16 v[66:69], v[198:201], v[230:233], v[66:69]
	s_setprio 0
	s_barrier
	s_add_i32 s81, s64, s54
	v_lshl_add_u64 v[166:167], s[50:51], 0, v[134:135]
	s_mov_b32 m0, s81
	ds_read_b128 v[202:205], v175 offset:16384
	ds_read_b128 v[206:209], v175 offset:17408
	ds_read_b128 v[210:213], v175 offset:18432
	ds_read_b128 v[214:217], v175 offset:19456
	ds_read_b128 v[218:221], v175 offset:20480
	ds_read_b128 v[222:225], v175 offset:21504
	ds_read_b128 v[226:229], v175 offset:22528
	ds_read_b128 v[230:233], v175 offset:23552
	global_load_lds_dwordx4 v[166:167], off
	s_add_i32 m0, s81, 0x2000
	s_add_u32 s82, s50, 0x40000
	v_lshl_add_u64 v[234:235], s[50:51], 0, v[136:137]
	s_addc_u32 s83, s51, 0
	s_add_i32 s81, s65, s54
	global_load_lds_dwordx4 v[234:235], off
	v_lshl_add_u64 v[236:237], s[82:83], 0, v[134:135]
	s_mov_b32 m0, s81
	v_lshl_add_u64 v[238:239], s[52:53], 0, v[136:137]
	global_load_lds_dwordx4 v[236:237], off
	v_lshl_add_u64 v[236:237], s[82:83], 0, v[136:137]
	s_add_i32 m0, s81, 0x2000
	s_nop 0
	global_load_lds_dwordx4 v[236:237], off
	v_lshl_add_u64 v[236:237], s[52:53], 0, v[134:135]
	s_mov_b32 m0, s49
	s_nop 0
	global_load_lds_dwordx4 v[236:237], off
	s_mov_b32 m0, s55
	s_nop 0
	global_load_lds_dwordx4 v[238:239], off
	s_waitcnt vmcnt(8)
	s_waitcnt lgkmcnt(0)
	s_barrier
; #define PG8_STAGE(bufoff, gbase, voff) do { _Pragma("unroll") for (int _i = 0; _i < 2; ++_i) \
;         __builtin_amdgcn_global_load_lds((const unsigned*)((const char*)(gbase) + (voff)[_i]), (PG8_LAS unsigned*)(lds + (bufoff) + ldsw + _i * 8192), 16, 0, 0); } while (0)
; #define PG8_LDA(dst, b, h) do { _Pragma("unroll") for (int m = 0; m < 4; ++m) _Pragma("unroll") for (int k = 0; k < 2; ++k) dst[m][k] = *(const PG8_LAS bf16x8*)(lds + PG8_SA(b, h) + aoff + m * 2048 + k * 1024); } while (0)
; #define PG8_LDB(dst, b, h) do { _Pragma("unroll") for (int n = 0; n < 2; ++n) _Pragma("unroll") for (int k = 0; k < 2; ++k) dst[n][k] = *(const PG8_LAS bf16x8*)(lds + PG8_SB(b, h) + boff + n * 2048 + k * 1024); } while (0)
; #define PG8_MMA(ai, bj, At, Bt) do { __builtin_amdgcn_s_setprio(1); _Pragma("unroll") for (int m = 0; m < 4; ++m) _Pragma("unroll") for (int n = 0; n < 2; ++n) _Pragma("unroll") for (int k = 0; k < 2; ++k) \
;         acc[ai][bj][m][n] = __builtin_amdgcn_mfma_f32_16x16x32_bf16(Bt[n][k], At[m][k], acc[ai][bj][m][n], 0, 0, 0); __builtin_amdgcn_s_setprio(0); } while (0)
; #define PG8_WAIT_V(n) asm volatile("s_waitcnt vmcnt(" #n ")" ::: "memory")
; #define PG8_WAIT_L(n) asm volatile("s_waitcnt lgkmcnt(" #n ")" ::: "memory")
; #define PG8_BAR __builtin_amdgcn_s_barrier()
; #define PG8_SCHED __builtin_amdgcn_sched_barrier(0)
; template <class Epi, class Sched, bool ALIGN_EPI = false, bool SP2 = false>
; __device__ __forceinline__ void gemm_phase(PG8_LAS unsigned char* lds, const Gemm g, const Sched& S, const Epi& E) {
;     ...
;             PG8_WAIT_V(8); PG8_WAIT_L(0); PG8_BAR; PG8_MMA(1, 0, At, B0); PG8_MMA(1, 1, At, B1); PG8_BAR; PG8_SCHED;
;             PG8_LDB(B0, 1, 0); PG8_LDB(B1, 1, 1); PG8_SCHED; PG8_LDA(At, 1, 0); PG8_STAGE(PG8_SA(0, 1), a2 + hstep, voffA);
;             PG8_WAIT_V(8); PG8_WAIT_L(0); PG8_BAR; PG8_MMA(0, 0, At, B0); PG8_MMA(0, 1, At, B1); PG8_BAR; PG8_SCHED;
	s_setprio 1
	s_waitcnt lgkmcnt(0)
	v_mfma_f32_16x16x32_bf16 v[62:65], v[130:133], v[202:205], v[62:65]
	v_mfma_f32_16x16x32_bf16 v[58:61], v[178:181], v[202:205], v[58:61]
	v_mfma_f32_16x16x32_bf16 v[46:49], v[130:133], v[210:213], v[46:49]
	v_mfma_f32_16x16x32_bf16 v[42:45], v[178:181], v[210:213], v[42:45]
	v_mfma_f32_16x16x32_bf16 v[30:33], v[130:133], v[218:221], v[30:33]
	v_mfma_f32_16x16x32_bf16 v[26:29], v[178:181], v[218:221], v[26:29]
	v_mfma_f32_16x16x32_bf16 v[14:17], v[130:133], v[226:229], v[14:17]
	v_mfma_f32_16x16x32_bf16 v[10:13], v[178:181], v[226:229], v[10:13]
	v_mfma_f32_16x16x32_bf16 v[62:65], v[148:151], v[206:209], v[62:65]
	v_mfma_f32_16x16x32_bf16 v[58:61], v[182:185], v[206:209], v[58:61]
	v_mfma_f32_16x16x32_bf16 v[46:49], v[148:151], v[214:217], v[46:49]
	v_mfma_f32_16x16x32_bf16 v[42:45], v[182:185], v[214:217], v[42:45]
	v_mfma_f32_16x16x32_bf16 v[30:33], v[148:151], v[222:225], v[30:33]
	v_mfma_f32_16x16x32_bf16 v[26:29], v[182:185], v[222:225], v[26:29]
	v_mfma_f32_16x16x32_bf16 v[14:17], v[148:151], v[230:233], v[14:17]
	v_mfma_f32_16x16x32_bf16 v[10:13], v[182:185], v[230:233], v[10:13]
	v_mfma_f32_16x16x32_bf16 v[54:57], v[186:189], v[202:205], v[54:57]
	v_mfma_f32_16x16x32_bf16 v[50:53], v[194:197], v[202:205], v[50:53]
	v_mfma_f32_16x16x32_bf16 v[38:41], v[186:189], v[210:213], v[38:41]
	v_mfma_f32_16x16x32_bf16 v[34:37], v[194:197], v[210:213], v[34:37]
	v_mfma_f32_16x16x32_bf16 v[22:25], v[186:189], v[218:221], v[22:25]
	v_mfma_f32_16x16x32_bf16 v[18:21], v[194:197], v[218:221], v[18:21]
	v_mfma_f32_16x16x32_bf16 v[6:9], v[186:189], v[226:229], v[6:9]
	v_mfma_f32_16x16x32_bf16 v[2:5], v[194:197], v[226:229], v[2:5]
	v_mfma_f32_16x16x32_bf16 v[54:57], v[190:193], v[206:209], v[54:57]
	v_mfma_f32_16x16x32_bf16 v[50:53], v[198:201], v[206:209], v[50:53]
	v_mfma_f32_16x16x32_bf16 v[38:41], v[190:193], v[214:217], v[38:41]
	v_mfma_f32_16x16x32_bf16 v[34:37], v[198:201], v[214:217], v[34:37]
	v_mfma_f32_16x16x32_bf16 v[22:25], v[190:193], v[222:225], v[22:25]
	v_mfma_f32_16x16x32_bf16 v[18:21], v[198:201], v[222:225], v[18:21]
	v_mfma_f32_16x16x32_bf16 v[6:9], v[190:193], v[230:233], v[6:9]
	v_mfma_f32_16x16x32_bf16 v[2:5], v[198:201], v[230:233], v[2:5]
	s_setprio 0
	s_barrier
	s_add_i32 s81, 0, 0x18000
	v_add_u32_e32 v138, s81, v170
	s_add_i32 s82, 0, 0x1c000
	ds_read_b128 v[130:133], v138
	ds_read_b128 v[148:151], v138 offset:1024
	ds_read_b128 v[178:181], v138 offset:2048
	ds_read_b128 v[182:185], v138 offset:3072
	v_add_u32_e32 v138, s82, v170
	ds_read_b128 v[186:189], v138
	ds_read_b128 v[190:193], v138 offset:1024
	ds_read_b128 v[194:197], v138 offset:2048
	ds_read_b128 v[198:201], v138 offset:3072
	s_add_u32 s52, s52, 0x40000
	s_addc_u32 s53, s53, 0
	s_mov_b32 m0, s56
	v_lshl_add_u64 v[240:241], s[52:53], 0, v[134:135]
	ds_read_b128 v[202:205], v175 offset:32768
	ds_read_b128 v[206:209], v175 offset:33792
	ds_read_b128 v[210:213], v175 offset:34816
	ds_read_b128 v[214:217], v175 offset:35840
	ds_read_b128 v[218:221], v175 offset:36864
	ds_read_b128 v[222:225], v175 offset:37888
	ds_read_b128 v[226:229], v175 offset:38912
	ds_read_b128 v[230:233], v175 offset:39936
	global_load_lds_dwordx4 v[240:241], off
	v_lshl_add_u64 v[240:241], s[52:53], 0, v[136:137]
	s_mov_b32 m0, s57
	s_nop 0
	global_load_lds_dwordx4 v[240:241], off
	s_waitcnt vmcnt(8)
	s_waitcnt lgkmcnt(0)
	s_barrier
	s_setprio 1
	s_waitcnt lgkmcnt(0)
	v_mfma_f32_16x16x32_bf16 v[126:129], v[130:133], v[202:205], v[126:129]
	v_mfma_f32_16x16x32_bf16 v[122:125], v[178:181], v[202:205], v[122:125]
	v_mfma_f32_16x16x32_bf16 v[110:113], v[130:133], v[210:213], v[110:113]
	v_mfma_f32_16x16x32_bf16 v[106:109], v[178:181], v[210:213], v[106:109]
	v_mfma_f32_16x16x32_bf16 v[94:97], v[130:133], v[218:221], v[94:97]
	v_mfma_f32_16x16x32_bf16 v[90:93], v[178:181], v[218:221], v[90:93]
	v_mfma_f32_16x16x32_bf16 v[78:81], v[130:133], v[226:229], v[78:81]
	v_mfma_f32_16x16x32_bf16 v[74:77], v[178:181], v[226:229], v[74:77]
	v_mfma_f32_16x16x32_bf16 v[126:129], v[148:151], v[206:209], v[126:129]
	v_mfma_f32_16x16x32_bf16 v[122:125], v[182:185], v[206:209], v[122:125]
	v_mfma_f32_16x16x32_bf16 v[110:113], v[148:151], v[214:217], v[110:113]
	v_mfma_f32_16x16x32_bf16 v[106:109], v[182:185], v[214:217], v[106:109]
	v_mfma_f32_16x16x32_bf16 v[94:97], v[148:151], v[222:225], v[94:97]
	v_mfma_f32_16x16x32_bf16 v[90:93], v[182:185], v[222:225], v[90:93]
	v_mfma_f32_16x16x32_bf16 v[78:81], v[148:151], v[230:233], v[78:81]
	v_mfma_f32_16x16x32_bf16 v[74:77], v[182:185], v[230:233], v[74:77]
	v_mfma_f32_16x16x32_bf16 v[118:121], v[186:189], v[202:205], v[118:121]
	v_mfma_f32_16x16x32_bf16 v[114:117], v[194:197], v[202:205], v[114:117]
	v_mfma_f32_16x16x32_bf16 v[102:105], v[186:189], v[210:213], v[102:105]
	v_mfma_f32_16x16x32_bf16 v[98:101], v[194:197], v[210:213], v[98:101]
	v_mfma_f32_16x16x32_bf16 v[86:89], v[186:189], v[218:221], v[86:89]
	v_mfma_f32_16x16x32_bf16 v[82:85], v[194:197], v[218:221], v[82:85]
	v_mfma_f32_16x16x32_bf16 v[70:73], v[186:189], v[226:229], v[70:73]
	v_mfma_f32_16x16x32_bf16 v[66:69], v[194:197], v[226:229], v[66:69]
	v_mfma_f32_16x16x32_bf16 v[118:121], v[190:193], v[206:209], v[118:121]
	v_mfma_f32_16x16x32_bf16 v[114:117], v[198:201], v[206:209], v[114:117]
	v_mfma_f32_16x16x32_bf16 v[102:105], v[190:193], v[214:217], v[102:105]
	v_mfma_f32_16x16x32_bf16 v[98:101], v[198:201], v[214:217], v[98:101]
	v_mfma_f32_16x16x32_bf16 v[86:89], v[190:193], v[222:225], v[86:89]
	v_mfma_f32_16x16x32_bf16 v[82:85], v[198:201], v[222:225], v[82:85]
	v_mfma_f32_16x16x32_bf16 v[70:73], v[190:193], v[230:233], v[70:73]
	v_mfma_f32_16x16x32_bf16 v[66:69], v[198:201], v[230:233], v[66:69]
	s_setprio 0
	s_barrier
; #define PG8_STAGE(bufoff, gbase, voff) do { _Pragma("unroll") for (int _i = 0; _i < 2; ++_i) \
;         __builtin_amdgcn_global_load_lds((const unsigned*)((const char*)(gbase) + (voff)[_i]), (PG8_LAS unsigned*)(lds + (bufoff) + ldsw + _i * 8192), 16, 0, 0); } while (0)
; #define PG8_LDA(dst, b, h) do { _Pragma("unroll") for (int m = 0; m < 4; ++m) _Pragma("unroll") for (int k = 0; k < 2; ++k) dst[m][k] = *(const PG8_LAS bf16x8*)(lds + PG8_SA(b, h) + aoff + m * 2048 + k * 1024); } while (0)
; #define PG8_MMA(ai, bj, At, Bt) do { __builtin_amdgcn_s_setprio(1); _Pragma("unroll") for (int m = 0; m < 4; ++m) _Pragma("unroll") for (int n = 0; n < 2; ++n) _Pragma("unroll") for (int k = 0; k < 2; ++k) \
;         acc[ai][bj][m][n] = __builtin_amdgcn_mfma_f32_16x16x32_bf16(Bt[n][k], At[m][k], acc[ai][bj][m][n], 0, 0, 0); __builtin_amdgcn_s_setprio(0); } while (0)
; #define PG8_WAIT_V(n) asm volatile("s_waitcnt vmcnt(" #n ")" ::: "memory")
; #define PG8_WAIT_L(n) asm volatile("s_waitcnt lgkmcnt(" #n ")" ::: "memory")
; #define PG8_BAR __builtin_amdgcn_s_barrier()
; #define PG8_SCHED __builtin_amdgcn_sched_barrier(0)
; template <class Epi, class Sched, bool ALIGN_EPI = false, bool SP2 = false>
; __device__ __forceinline__ void gemm_phase(PG8_LAS unsigned char* lds, const Gemm g, const Sched& S, const Epi& E) {
;     ...
;             PG8_LDA(At, 1, 1); PG8_STAGE(PG8_SB(1, 0), b3, voffB); PG8_STAGE(PG8_SB(1, 1), b3 + hstep, voffB); PG8_STAGE(PG8_SA(1, 0), a3, voffA);
;             PG8_WAIT_V(8); PG8_WAIT_L(0); PG8_BAR; PG8_MMA(1, 0, At, B0); PG8_MMA(1, 1, At, B1); PG8_BAR; PG8_SCHED;
;     ...
;         if constexpr (ALIGN_EPI) { if (wr == 0) PG8_BAR; }
	s_add_i32 s52, s81, s54
	v_lshl_add_u64 v[166:167], v[166:167], 0, s[34:35]
	s_mov_b32 m0, s52
	ds_read_b128 v[202:205], v175 offset:49152
	ds_read_b128 v[206:209], v175 offset:50176
	ds_read_b128 v[210:213], v175 offset:51200
	ds_read_b128 v[214:217], v175 offset:52224
	ds_read_b128 v[218:221], v175 offset:53248
	ds_read_b128 v[222:225], v175 offset:54272
	ds_read_b128 v[226:229], v175 offset:55296
	ds_read_b128 v[230:233], v175 offset:56320
	global_load_lds_dwordx4 v[166:167], off
	s_add_i32 m0, s52, 0x2000
	s_add_u32 s50, s50, 0x40080
	v_lshl_add_u64 v[166:167], v[234:235], 0, s[34:35]
	s_addc_u32 s51, s51, 0
	s_add_i32 s52, s82, s54
	global_load_lds_dwordx4 v[166:167], off
	v_lshl_add_u64 v[166:167], s[50:51], 0, v[134:135]
	s_mov_b32 m0, s52
	s_nop 0
	global_load_lds_dwordx4 v[166:167], off
	v_lshl_add_u64 v[166:167], s[50:51], 0, v[136:137]
	s_add_i32 m0, s52, 0x2000
	s_nop 0
	global_load_lds_dwordx4 v[166:167], off
	v_lshl_add_u64 v[166:167], v[236:237], 0, s[34:35]
	s_mov_b32 m0, s59
	s_nop 0
	global_load_lds_dwordx4 v[166:167], off
	v_lshl_add_u64 v[166:167], v[238:239], 0, s[34:35]
	s_mov_b32 m0, s60
	s_nop 0
	global_load_lds_dwordx4 v[166:167], off
	s_waitcnt vmcnt(8)
	s_waitcnt lgkmcnt(0)
	s_barrier
	s_setprio 1
	s_waitcnt lgkmcnt(0)
	v_mfma_f32_16x16x32_bf16 v[62:65], v[130:133], v[202:205], v[62:65]
	v_mfma_f32_16x16x32_bf16 v[58:61], v[178:181], v[202:205], v[58:61]
	v_mfma_f32_16x16x32_bf16 v[46:49], v[130:133], v[210:213], v[46:49]
	v_mfma_f32_16x16x32_bf16 v[42:45], v[178:181], v[210:213], v[42:45]
	v_mfma_f32_16x16x32_bf16 v[30:33], v[130:133], v[218:221], v[30:33]
	v_mfma_f32_16x16x32_bf16 v[26:29], v[178:181], v[218:221], v[26:29]
	v_mfma_f32_16x16x32_bf16 v[14:17], v[130:133], v[226:229], v[14:17]
	v_mfma_f32_16x16x32_bf16 v[10:13], v[178:181], v[226:229], v[10:13]
	v_mfma_f32_16x16x32_bf16 v[62:65], v[148:151], v[206:209], v[62:65]
	v_mfma_f32_16x16x32_bf16 v[58:61], v[182:185], v[206:209], v[58:61]
	v_mfma_f32_16x16x32_bf16 v[46:49], v[148:151], v[214:217], v[46:49]
	v_mfma_f32_16x16x32_bf16 v[42:45], v[182:185], v[214:217], v[42:45]
	v_mfma_f32_16x16x32_bf16 v[30:33], v[148:151], v[222:225], v[30:33]
	v_mfma_f32_16x16x32_bf16 v[26:29], v[182:185], v[222:225], v[26:29]
	v_mfma_f32_16x16x32_bf16 v[14:17], v[148:151], v[230:233], v[14:17]
	v_mfma_f32_16x16x32_bf16 v[10:13], v[182:185], v[230:233], v[10:13]
	v_mfma_f32_16x16x32_bf16 v[54:57], v[186:189], v[202:205], v[54:57]
	v_mfma_f32_16x16x32_bf16 v[50:53], v[194:197], v[202:205], v[50:53]
	v_mfma_f32_16x16x32_bf16 v[38:41], v[186:189], v[210:213], v[38:41]
	v_mfma_f32_16x16x32_bf16 v[34:37], v[194:197], v[210:213], v[34:37]
	v_mfma_f32_16x16x32_bf16 v[22:25], v[186:189], v[218:221], v[22:25]
	v_mfma_f32_16x16x32_bf16 v[18:21], v[194:197], v[218:221], v[18:21]
	v_mfma_f32_16x16x32_bf16 v[6:9], v[186:189], v[226:229], v[6:9]
	v_mfma_f32_16x16x32_bf16 v[2:5], v[194:197], v[226:229], v[2:5]
	v_mfma_f32_16x16x32_bf16 v[54:57], v[190:193], v[206:209], v[54:57]
	v_mfma_f32_16x16x32_bf16 v[50:53], v[198:201], v[206:209], v[50:53]
	v_mfma_f32_16x16x32_bf16 v[38:41], v[190:193], v[214:217], v[38:41]
	v_mfma_f32_16x16x32_bf16 v[34:37], v[198:201], v[214:217], v[34:37]
	v_mfma_f32_16x16x32_bf16 v[22:25], v[190:193], v[222:225], v[22:25]
	v_mfma_f32_16x16x32_bf16 v[18:21], v[198:201], v[222:225], v[18:21]
	v_mfma_f32_16x16x32_bf16 v[6:9], v[190:193], v[230:233], v[6:9]
	v_mfma_f32_16x16x32_bf16 v[2:5], v[198:201], v[230:233], v[2:5]
	s_setprio 0
	s_barrier
	s_add_i32 s80, s80, 2
	s_add_u32 s10, s10, 0x100
	s_addc_u32 s11, s11, 0
	s_add_u32 s78, s78, 0x100
	s_addc_u32 s79, s79, 0
	s_cmp_gt_u32 s80, 13
	s_cbranch_scc0 .LBB0_1746
	s_and_b64 vcc, exec, s[36:37]
	s_cbranch_vccz .LBB0_1749
	s_barrier

; #define PG8_STAGE(bufoff, gbase, voff) do { _Pragma("unroll") for (int _i = 0; _i < 2; ++_i) \
;         __builtin_amdgcn_global_load_lds((const unsigned*)((const char*)(gbase) + (voff)[_i]), (PG8_LAS unsigned*)(lds + (bufoff) + ldsw + _i * 8192), 16, 0, 0); } while (0)
; #define PG8_LDA(dst, b, h) do { _Pragma("unroll") for (int m = 0; m < 4; ++m) _Pragma("unroll") for (int k = 0; k < 2; ++k) dst[m][k] = *(const PG8_LAS bf16x8*)(lds + PG8_SA(b, h) + aoff + m * 2048 + k * 1024); } while (0)
; #define PG8_LDB(dst, b, h) do { _Pragma("unroll") for (int n = 0; n < 2; ++n) _Pragma("unroll") for (int k = 0; k < 2; ++k) dst[n][k] = *(const PG8_LAS bf16x8*)(lds + PG8_SB(b, h) + boff + n * 2048 + k * 1024); } while (0)
; #define PG8_MMA(ai, bj, At, Bt) do { __builtin_amdgcn_s_setprio(1); _Pragma("unroll") for (int m = 0; m < 4; ++m) _Pragma("unroll") for (int n = 0; n < 2; ++n) _Pragma("unroll") for (int k = 0; k < 2; ++k) \
;         acc[ai][bj][m][n] = __builtin_amdgcn_mfma_f32_16x16x32_bf16(Bt[n][k], At[m][k], acc[ai][bj][m][n], 0, 0, 0); __builtin_amdgcn_s_setprio(0); } while (0)
; #define PG8_WAIT_V(n) asm volatile("s_waitcnt vmcnt(" #n ")" ::: "memory")
; #define PG8_WAIT_L(n) asm volatile("s_waitcnt lgkmcnt(" #n ")" ::: "memory")
; #define PG8_BAR __builtin_amdgcn_s_barrier()
; #define PG8_SCHED __builtin_amdgcn_sched_barrier(0)
; template <class Epi, class Sched, bool ALIGN_EPI = false, bool SP2 = false>
; __device__ __forceinline__ void gemm_phase(PG8_LAS unsigned char* lds, const Gemm g, const Sched& S, const Epi& E) {
;     ...
;         for (int t = 0; t < nt; t += 2) {
;             const bool last = (t == nt - 2);
;             const char* a1 = cA + (size_t)(t + 1) * kstep;
;             const char* a2 = last ? nA : cA + (size_t)(t + 2) * kstep; const char* b2 = last ? nB : cB + (size_t)(t + 2) * kstep;
;             const char* a3 = a2 + kstep; const char* b3 = b2 + kstep;
;             if (last && has_next) S.a_ready(nxt);
;             if constexpr (SP2) {
;             PG8_LDB(B0, 0, 0); PG8_LDB(B1, 0, 1); PG8_SCHED; PG8_LDA(At, 0, 0); PG8_STAGE(PG8_SA(1, 1), a1 + hstep, voffA);
;             PG8_WAIT_V(8); PG8_WAIT_L(0); PG8_BAR; PG8_MMA(0, 0, At, B0); PG8_MMA(0, 1, At, B1); PG8_BAR; PG8_SCHED;
;             PG8_LDA(At, 0, 1); PG8_STAGE(PG8_SB(0, 0), b2, voffB); PG8_STAGE(PG8_SB(0, 1), b2 + hstep, voffB); PG8_STAGE(PG8_SA(0, 0), a2, voffA);
.LBB0_1898:
	ds_read_b128 v[170:173], v147
	ds_read_b128 v[174:177], v147 offset:1024
	ds_read_b128 v[178:181], v147 offset:2048
	ds_read_b128 v[182:185], v147 offset:3072
	ds_read_b128 v[186:189], v148
	ds_read_b128 v[190:193], v148 offset:1024
	ds_read_b128 v[194:197], v148 offset:2048
	ds_read_b128 v[198:201], v148 offset:3072
	s_add_u32 s44, s42, 0xfff50080
	s_addc_u32 s45, s43, -1
	s_cmp_eq_u32 s68, 40
	s_cselect_b32 s47, s9, s45
	s_cselect_b32 s46, s8, s44
	s_cselect_b32 s45, s41, s67
	s_cselect_b32 s44, s40, s66
	v_lshl_add_u64 v[142:143], s[42:43], 0, v[134:135]
	s_add_i32 m0, s48, 0xc000
	ds_read_b128 v[202:205], v149
	ds_read_b128 v[206:209], v149 offset:1024
	ds_read_b128 v[210:213], v149 offset:2048
	ds_read_b128 v[214:217], v149 offset:3072
	ds_read_b128 v[218:221], v149 offset:4096
	ds_read_b128 v[222:225], v149 offset:5120
	ds_read_b128 v[226:229], v149 offset:6144
	ds_read_b128 v[230:233], v149 offset:7168
	global_load_lds_dwordx4 v[142:143], off
	v_lshl_add_u64 v[142:143], s[42:43], 0, v[136:137]
	s_add_i32 m0, s48, 0xe000
	s_nop 0
	global_load_lds_dwordx4 v[142:143], off
	s_waitcnt vmcnt(8)
	s_waitcnt lgkmcnt(0)
	s_barrier
	s_setprio 1
	s_waitcnt lgkmcnt(0)
	v_mfma_f32_16x16x32_bf16 v[126:129], v[170:173], v[202:205], v[126:129]
	v_mfma_f32_16x16x32_bf16 v[122:125], v[178:181], v[202:205], v[122:125]
	v_mfma_f32_16x16x32_bf16 v[118:121], v[170:173], v[210:213], v[118:121]
	v_mfma_f32_16x16x32_bf16 v[114:117], v[178:181], v[210:213], v[114:117]
	v_mfma_f32_16x16x32_bf16 v[94:97], v[170:173], v[218:221], v[94:97]
	v_mfma_f32_16x16x32_bf16 v[90:93], v[178:181], v[218:221], v[90:93]
	v_mfma_f32_16x16x32_bf16 v[86:89], v[170:173], v[226:229], v[86:89]
	v_mfma_f32_16x16x32_bf16 v[82:85], v[178:181], v[226:229], v[82:85]
	v_mfma_f32_16x16x32_bf16 v[126:129], v[174:177], v[206:209], v[126:129]
	v_mfma_f32_16x16x32_bf16 v[122:125], v[182:185], v[206:209], v[122:125]
	v_mfma_f32_16x16x32_bf16 v[118:121], v[174:177], v[214:217], v[118:121]
	v_mfma_f32_16x16x32_bf16 v[114:117], v[182:185], v[214:217], v[114:117]
	v_mfma_f32_16x16x32_bf16 v[94:97], v[174:177], v[222:225], v[94:97]
	v_mfma_f32_16x16x32_bf16 v[90:93], v[182:185], v[222:225], v[90:93]
	v_mfma_f32_16x16x32_bf16 v[86:89], v[174:177], v[230:233], v[86:89]
	v_mfma_f32_16x16x32_bf16 v[82:85], v[182:185], v[230:233], v[82:85]
	v_mfma_f32_16x16x32_bf16 v[110:113], v[186:189], v[202:205], v[110:113]
	v_mfma_f32_16x16x32_bf16 v[106:109], v[194:197], v[202:205], v[106:109]
	v_mfma_f32_16x16x32_bf16 v[102:105], v[186:189], v[210:213], v[102:105]
	v_mfma_f32_16x16x32_bf16 v[98:101], v[194:197], v[210:213], v[98:101]
	v_mfma_f32_16x16x32_bf16 v[78:81], v[186:189], v[218:221], v[78:81]
	v_mfma_f32_16x16x32_bf16 v[74:77], v[194:197], v[218:221], v[74:77]
	v_mfma_f32_16x16x32_bf16 v[70:73], v[186:189], v[226:229], v[70:73]
	v_mfma_f32_16x16x32_bf16 v[66:69], v[194:197], v[226:229], v[66:69]
	v_mfma_f32_16x16x32_bf16 v[110:113], v[190:193], v[206:209], v[110:113]
	v_mfma_f32_16x16x32_bf16 v[106:109], v[198:201], v[206:209], v[106:109]
	v_mfma_f32_16x16x32_bf16 v[102:105], v[190:193], v[214:217], v[102:105]
	v_mfma_f32_16x16x32_bf16 v[98:101], v[198:201], v[214:217], v[98:101]
	v_mfma_f32_16x16x32_bf16 v[78:81], v[190:193], v[222:225], v[78:81]
	v_mfma_f32_16x16x32_bf16 v[74:77], v[198:201], v[222:225], v[74:77]
	v_mfma_f32_16x16x32_bf16 v[70:73], v[190:193], v[230:233], v[70:73]
	v_mfma_f32_16x16x32_bf16 v[66:69], v[198:201], v[230:233], v[66:69]
	s_setprio 0
	s_barrier
	s_add_i32 s69, s56, s19
	v_lshl_add_u64 v[142:143], s[44:45], 0, v[130:131]
	s_mov_b32 m0, s69
	ds_read_b128 v[202:205], v149 offset:16384
	ds_read_b128 v[206:209], v149 offset:17408
	ds_read_b128 v[210:213], v149 offset:18432
	ds_read_b128 v[214:217], v149 offset:19456
	ds_read_b128 v[218:221], v149 offset:20480
	ds_read_b128 v[222:225], v149 offset:21504
	ds_read_b128 v[226:229], v149 offset:22528
	ds_read_b128 v[230:233], v149 offset:23552
	global_load_lds_dwordx4 v[142:143], off
	s_add_i32 m0, s69, 0x2000
	s_add_u32 s70, s44, 0xb0000
	v_lshl_add_u64 v[150:151], s[44:45], 0, v[132:133]
	s_addc_u32 s71, s45, 0
	s_add_i32 s69, s57, s19
	global_load_lds_dwordx4 v[150:151], off
	v_lshl_add_u64 v[166:167], s[70:71], 0, v[130:131]
	s_mov_b32 m0, s69
	v_lshl_add_u64 v[234:235], s[46:47], 0, v[132:133]
	global_load_lds_dwordx4 v[166:167], off
	v_lshl_add_u64 v[166:167], s[70:71], 0, v[132:133]
	s_add_i32 m0, s69, 0x2000
	s_nop 0
	global_load_lds_dwordx4 v[166:167], off
	v_lshl_add_u64 v[166:167], s[46:47], 0, v[130:131]
	s_mov_b32 m0, s48
	s_nop 0
	global_load_lds_dwordx4 v[166:167], off
	s_mov_b32 m0, s49
	s_nop 0
	global_load_lds_dwordx4 v[234:235], off
	s_waitcnt vmcnt(8)
	s_waitcnt lgkmcnt(0)
	s_barrier
; #define PG8_STAGE(bufoff, gbase, voff) do { _Pragma("unroll") for (int _i = 0; _i < 2; ++_i) \
;         __builtin_amdgcn_global_load_lds((const unsigned*)((const char*)(gbase) + (voff)[_i]), (PG8_LAS unsigned*)(lds + (bufoff) + ldsw + _i * 8192), 16, 0, 0); } while (0)
; #define PG8_LDA(dst, b, h) do { _Pragma("unroll") for (int m = 0; m < 4; ++m) _Pragma("unroll") for (int k = 0; k < 2; ++k) dst[m][k] = *(const PG8_LAS bf16x8*)(lds + PG8_SA(b, h) + aoff + m * 2048 + k * 1024); } while (0)
; #define PG8_LDB(dst, b, h) do { _Pragma("unroll") for (int n = 0; n < 2; ++n) _Pragma("unroll") for (int k = 0; k < 2; ++k) dst[n][k] = *(const PG8_LAS bf16x8*)(lds + PG8_SB(b, h) + boff + n * 2048 + k * 1024); } while (0)
; #define PG8_MMA(ai, bj, At, Bt) do { __builtin_amdgcn_s_setprio(1); _Pragma("unroll") for (int m = 0; m < 4; ++m) _Pragma("unroll") for (int n = 0; n < 2; ++n) _Pragma("unroll") for (int k = 0; k < 2; ++k) \
;         acc[ai][bj][m][n] = __builtin_amdgcn_mfma_f32_16x16x32_bf16(Bt[n][k], At[m][k], acc[ai][bj][m][n], 0, 0, 0); __builtin_amdgcn_s_setprio(0); } while (0)
; #define PG8_WAIT_V(n) asm volatile("s_waitcnt vmcnt(" #n ")" ::: "memory")
; #define PG8_WAIT_L(n) asm volatile("s_waitcnt lgkmcnt(" #n ")" ::: "memory")
; #define PG8_BAR __builtin_amdgcn_s_barrier()
; #define PG8_SCHED __builtin_amdgcn_sched_barrier(0)
; template <class Epi, class Sched, bool ALIGN_EPI = false, bool SP2 = false>
; __device__ __forceinline__ void gemm_phase(PG8_LAS unsigned char* lds, const Gemm g, const Sched& S, const Epi& E) {
;     ...
;             PG8_WAIT_V(8); PG8_WAIT_L(0); PG8_BAR; PG8_MMA(1, 0, At, B0); PG8_MMA(1, 1, At, B1); PG8_BAR; PG8_SCHED;
;             PG8_LDB(B0, 1, 0); PG8_LDB(B1, 1, 1); PG8_SCHED; PG8_LDA(At, 1, 0); PG8_STAGE(PG8_SA(0, 1), a2 + hstep, voffA);
;             PG8_WAIT_V(8); PG8_WAIT_L(0); PG8_BAR; PG8_MMA(0, 0, At, B0); PG8_MMA(0, 1, At, B1); PG8_BAR; PG8_SCHED;
	s_setprio 1
	s_waitcnt lgkmcnt(0)
	v_mfma_f32_16x16x32_bf16 v[62:65], v[170:173], v[202:205], v[62:65]
	v_mfma_f32_16x16x32_bf16 v[58:61], v[178:181], v[202:205], v[58:61]
	v_mfma_f32_16x16x32_bf16 v[54:57], v[170:173], v[210:213], v[54:57]
	v_mfma_f32_16x16x32_bf16 v[50:53], v[178:181], v[210:213], v[50:53]
	v_mfma_f32_16x16x32_bf16 v[30:33], v[170:173], v[218:221], v[30:33]
	v_mfma_f32_16x16x32_bf16 v[26:29], v[178:181], v[218:221], v[26:29]
	v_mfma_f32_16x16x32_bf16 v[22:25], v[170:173], v[226:229], v[22:25]
	v_mfma_f32_16x16x32_bf16 v[14:17], v[178:181], v[226:229], v[14:17]
	v_mfma_f32_16x16x32_bf16 v[62:65], v[174:177], v[206:209], v[62:65]
	v_mfma_f32_16x16x32_bf16 v[58:61], v[182:185], v[206:209], v[58:61]
	v_mfma_f32_16x16x32_bf16 v[54:57], v[174:177], v[214:217], v[54:57]
	v_mfma_f32_16x16x32_bf16 v[50:53], v[182:185], v[214:217], v[50:53]
	v_mfma_f32_16x16x32_bf16 v[30:33], v[174:177], v[222:225], v[30:33]
	v_mfma_f32_16x16x32_bf16 v[26:29], v[182:185], v[222:225], v[26:29]
	v_mfma_f32_16x16x32_bf16 v[22:25], v[174:177], v[230:233], v[22:25]
	v_mfma_f32_16x16x32_bf16 v[14:17], v[182:185], v[230:233], v[14:17]
	v_mfma_f32_16x16x32_bf16 v[46:49], v[186:189], v[202:205], v[46:49]
	v_mfma_f32_16x16x32_bf16 v[42:45], v[194:197], v[202:205], v[42:45]
	v_mfma_f32_16x16x32_bf16 v[38:41], v[186:189], v[210:213], v[38:41]
	v_mfma_f32_16x16x32_bf16 v[34:37], v[194:197], v[210:213], v[34:37]
	v_mfma_f32_16x16x32_bf16 v[18:21], v[186:189], v[218:221], v[18:21]
	v_mfma_f32_16x16x32_bf16 v[10:13], v[194:197], v[218:221], v[10:13]
	v_mfma_f32_16x16x32_bf16 v[6:9], v[186:189], v[226:229], v[6:9]
	v_mfma_f32_16x16x32_bf16 v[2:5], v[194:197], v[226:229], v[2:5]
	v_mfma_f32_16x16x32_bf16 v[46:49], v[190:193], v[206:209], v[46:49]
	v_mfma_f32_16x16x32_bf16 v[42:45], v[198:201], v[206:209], v[42:45]
	v_mfma_f32_16x16x32_bf16 v[38:41], v[190:193], v[214:217], v[38:41]
	v_mfma_f32_16x16x32_bf16 v[34:37], v[198:201], v[214:217], v[34:37]
	v_mfma_f32_16x16x32_bf16 v[18:21], v[190:193], v[222:225], v[18:21]
	v_mfma_f32_16x16x32_bf16 v[10:13], v[198:201], v[222:225], v[10:13]
	v_mfma_f32_16x16x32_bf16 v[6:9], v[190:193], v[230:233], v[6:9]
	v_mfma_f32_16x16x32_bf16 v[2:5], v[198:201], v[230:233], v[2:5]
	s_setprio 0
	s_barrier
	s_add_i32 s69, 0, 0x18000
	v_add_u32_e32 v152, s69, v145
	s_add_i32 s70, 0, 0x1c000
	ds_read_b128 v[170:173], v152
	ds_read_b128 v[174:177], v152 offset:1024
	ds_read_b128 v[178:181], v152 offset:2048
	ds_read_b128 v[182:185], v152 offset:3072
	v_add_u32_e32 v152, s70, v145
	ds_read_b128 v[186:189], v152
	ds_read_b128 v[190:193], v152 offset:1024
	ds_read_b128 v[194:197], v152 offset:2048
	ds_read_b128 v[198:201], v152 offset:3072
	s_add_u32 s46, s46, 0xb0000
	s_addc_u32 s47, s47, 0
	s_mov_b32 m0, s50
	v_lshl_add_u64 v[236:237], s[46:47], 0, v[130:131]
	ds_read_b128 v[202:205], v149 offset:32768
	ds_read_b128 v[206:209], v149 offset:33792
	ds_read_b128 v[210:213], v149 offset:34816
	ds_read_b128 v[214:217], v149 offset:35840
	ds_read_b128 v[218:221], v149 offset:36864
	ds_read_b128 v[222:225], v149 offset:37888
	ds_read_b128 v[226:229], v149 offset:38912
	ds_read_b128 v[230:233], v149 offset:39936
	global_load_lds_dwordx4 v[236:237], off
	v_lshl_add_u64 v[236:237], s[46:47], 0, v[132:133]
	s_mov_b32 m0, s51
	s_nop 0
	global_load_lds_dwordx4 v[236:237], off
	s_waitcnt vmcnt(8)
	s_waitcnt lgkmcnt(0)
	s_barrier
	s_setprio 1
	s_waitcnt lgkmcnt(0)
	v_mfma_f32_16x16x32_bf16 v[126:129], v[170:173], v[202:205], v[126:129]
	v_mfma_f32_16x16x32_bf16 v[122:125], v[178:181], v[202:205], v[122:125]
	v_mfma_f32_16x16x32_bf16 v[118:121], v[170:173], v[210:213], v[118:121]
	v_mfma_f32_16x16x32_bf16 v[114:117], v[178:181], v[210:213], v[114:117]
	v_mfma_f32_16x16x32_bf16 v[94:97], v[170:173], v[218:221], v[94:97]
	v_mfma_f32_16x16x32_bf16 v[90:93], v[178:181], v[218:221], v[90:93]
	v_mfma_f32_16x16x32_bf16 v[86:89], v[170:173], v[226:229], v[86:89]
	v_mfma_f32_16x16x32_bf16 v[82:85], v[178:181], v[226:229], v[82:85]
	v_mfma_f32_16x16x32_bf16 v[126:129], v[174:177], v[206:209], v[126:129]
	v_mfma_f32_16x16x32_bf16 v[122:125], v[182:185], v[206:209], v[122:125]
	v_mfma_f32_16x16x32_bf16 v[118:121], v[174:177], v[214:217], v[118:121]
	v_mfma_f32_16x16x32_bf16 v[114:117], v[182:185], v[214:217], v[114:117]
	v_mfma_f32_16x16x32_bf16 v[94:97], v[174:177], v[222:225], v[94:97]
	v_mfma_f32_16x16x32_bf16 v[90:93], v[182:185], v[222:225], v[90:93]
	v_mfma_f32_16x16x32_bf16 v[86:89], v[174:177], v[230:233], v[86:89]
	v_mfma_f32_16x16x32_bf16 v[82:85], v[182:185], v[230:233], v[82:85]
	v_mfma_f32_16x16x32_bf16 v[110:113], v[186:189], v[202:205], v[110:113]
	v_mfma_f32_16x16x32_bf16 v[106:109], v[194:197], v[202:205], v[106:109]
	v_mfma_f32_16x16x32_bf16 v[102:105], v[186:189], v[210:213], v[102:105]
	v_mfma_f32_16x16x32_bf16 v[98:101], v[194:197], v[210:213], v[98:101]
	v_mfma_f32_16x16x32_bf16 v[78:81], v[186:189], v[218:221], v[78:81]
	v_mfma_f32_16x16x32_bf16 v[74:77], v[194:197], v[218:221], v[74:77]
	v_mfma_f32_16x16x32_bf16 v[70:73], v[186:189], v[226:229], v[70:73]
	v_mfma_f32_16x16x32_bf16 v[66:69], v[194:197], v[226:229], v[66:69]
	v_mfma_f32_16x16x32_bf16 v[110:113], v[190:193], v[206:209], v[110:113]
	v_mfma_f32_16x16x32_bf16 v[106:109], v[198:201], v[206:209], v[106:109]
	v_mfma_f32_16x16x32_bf16 v[102:105], v[190:193], v[214:217], v[102:105]
	v_mfma_f32_16x16x32_bf16 v[98:101], v[198:201], v[214:217], v[98:101]
	v_mfma_f32_16x16x32_bf16 v[78:81], v[190:193], v[222:225], v[78:81]
	v_mfma_f32_16x16x32_bf16 v[74:77], v[198:201], v[222:225], v[74:77]
	v_mfma_f32_16x16x32_bf16 v[70:73], v[190:193], v[230:233], v[70:73]
	v_mfma_f32_16x16x32_bf16 v[66:69], v[198:201], v[230:233], v[66:69]
	s_setprio 0
	s_barrier
; #define PG8_STAGE(bufoff, gbase, voff) do { _Pragma("unroll") for (int _i = 0; _i < 2; ++_i) \
;         __builtin_amdgcn_global_load_lds((const unsigned*)((const char*)(gbase) + (voff)[_i]), (PG8_LAS unsigned*)(lds + (bufoff) + ldsw + _i * 8192), 16, 0, 0); } while (0)
; #define PG8_LDA(dst, b, h) do { _Pragma("unroll") for (int m = 0; m < 4; ++m) _Pragma("unroll") for (int k = 0; k < 2; ++k) dst[m][k] = *(const PG8_LAS bf16x8*)(lds + PG8_SA(b, h) + aoff + m * 2048 + k * 1024); } while (0)
; #define PG8_MMA(ai, bj, At, Bt) do { __builtin_amdgcn_s_setprio(1); _Pragma("unroll") for (int m = 0; m < 4; ++m) _Pragma("unroll") for (int n = 0; n < 2; ++n) _Pragma("unroll") for (int k = 0; k < 2; ++k) \
;         acc[ai][bj][m][n] = __builtin_amdgcn_mfma_f32_16x16x32_bf16(Bt[n][k], At[m][k], acc[ai][bj][m][n], 0, 0, 0); __builtin_amdgcn_s_setprio(0); } while (0)
; #define PG8_WAIT_V(n) asm volatile("s_waitcnt vmcnt(" #n ")" ::: "memory")
; #define PG8_WAIT_L(n) asm volatile("s_waitcnt lgkmcnt(" #n ")" ::: "memory")
; #define PG8_BAR __builtin_amdgcn_s_barrier()
; #define PG8_SCHED __builtin_amdgcn_sched_barrier(0)
; template <class Epi, class Sched, bool ALIGN_EPI = false, bool SP2 = false>
; __device__ __forceinline__ void gemm_phase(PG8_LAS unsigned char* lds, const Gemm g, const Sched& S, const Epi& E) {
;     ...
;             PG8_LDA(At, 1, 1); PG8_STAGE(PG8_SB(1, 0), b3, voffB); PG8_STAGE(PG8_SB(1, 1), b3 + hstep, voffB); PG8_STAGE(PG8_SA(1, 0), a3, voffA);
;             PG8_WAIT_V(8); PG8_WAIT_L(0); PG8_BAR; PG8_MMA(1, 0, At, B0); PG8_MMA(1, 1, At, B1); PG8_BAR; PG8_SCHED;
	s_add_i32 s46, s69, s19
	v_lshl_add_u64 v[142:143], v[142:143], 0, s[16:17]
	s_mov_b32 m0, s46
	ds_read_b128 v[202:205], v149 offset:49152
	ds_read_b128 v[206:209], v149 offset:50176
	ds_read_b128 v[210:213], v149 offset:51200
	ds_read_b128 v[214:217], v149 offset:52224
	ds_read_b128 v[218:221], v149 offset:53248
	ds_read_b128 v[222:225], v149 offset:54272
	ds_read_b128 v[226:229], v149 offset:55296
	ds_read_b128 v[230:233], v149 offset:56320
	global_load_lds_dwordx4 v[142:143], off
	s_add_i32 m0, s46, 0x2000
	s_add_u32 s44, s44, 0xb0080
	v_lshl_add_u64 v[142:143], v[150:151], 0, s[16:17]
	s_addc_u32 s45, s45, 0
	s_add_i32 s46, s70, s19
	global_load_lds_dwordx4 v[142:143], off
	v_lshl_add_u64 v[142:143], s[44:45], 0, v[130:131]
	s_mov_b32 m0, s46
	s_nop 0
	global_load_lds_dwordx4 v[142:143], off
	v_lshl_add_u64 v[142:143], s[44:45], 0, v[132:133]
	s_add_i32 m0, s46, 0x2000
	s_nop 0
	global_load_lds_dwordx4 v[142:143], off
	v_lshl_add_u64 v[142:143], v[166:167], 0, s[16:17]
	s_mov_b32 m0, s53
	s_nop 0
	global_load_lds_dwordx4 v[142:143], off
	v_lshl_add_u64 v[142:143], v[234:235], 0, s[16:17]
	s_mov_b32 m0, s54
	s_nop 0
	global_load_lds_dwordx4 v[142:143], off
	s_waitcnt vmcnt(8)
	s_waitcnt lgkmcnt(0)
	s_barrier
	s_setprio 1
	s_waitcnt lgkmcnt(0)
	v_mfma_f32_16x16x32_bf16 v[62:65], v[170:173], v[202:205], v[62:65]
	v_mfma_f32_16x16x32_bf16 v[58:61], v[178:181], v[202:205], v[58:61]
	v_mfma_f32_16x16x32_bf16 v[54:57], v[170:173], v[210:213], v[54:57]
	v_mfma_f32_16x16x32_bf16 v[50:53], v[178:181], v[210:213], v[50:53]
	v_mfma_f32_16x16x32_bf16 v[30:33], v[170:173], v[218:221], v[30:33]
	v_mfma_f32_16x16x32_bf16 v[26:29], v[178:181], v[218:221], v[26:29]
	v_mfma_f32_16x16x32_bf16 v[22:25], v[170:173], v[226:229], v[22:25]
	v_mfma_f32_16x16x32_bf16 v[14:17], v[178:181], v[226:229], v[14:17]
	v_mfma_f32_16x16x32_bf16 v[62:65], v[174:177], v[206:209], v[62:65]
	v_mfma_f32_16x16x32_bf16 v[58:61], v[182:185], v[206:209], v[58:61]
	v_mfma_f32_16x16x32_bf16 v[54:57], v[174:177], v[214:217], v[54:57]
	v_mfma_f32_16x16x32_bf16 v[50:53], v[182:185], v[214:217], v[50:53]
	v_mfma_f32_16x16x32_bf16 v[30:33], v[174:177], v[222:225], v[30:33]
	v_mfma_f32_16x16x32_bf16 v[26:29], v[182:185], v[222:225], v[26:29]
	v_mfma_f32_16x16x32_bf16 v[22:25], v[174:177], v[230:233], v[22:25]
	v_mfma_f32_16x16x32_bf16 v[14:17], v[182:185], v[230:233], v[14:17]
	v_mfma_f32_16x16x32_bf16 v[46:49], v[186:189], v[202:205], v[46:49]
	v_mfma_f32_16x16x32_bf16 v[42:45], v[194:197], v[202:205], v[42:45]
	v_mfma_f32_16x16x32_bf16 v[38:41], v[186:189], v[210:213], v[38:41]
	v_mfma_f32_16x16x32_bf16 v[34:37], v[194:197], v[210:213], v[34:37]
	v_mfma_f32_16x16x32_bf16 v[18:21], v[186:189], v[218:221], v[18:21]
	v_mfma_f32_16x16x32_bf16 v[10:13], v[194:197], v[218:221], v[10:13]
	v_mfma_f32_16x16x32_bf16 v[6:9], v[186:189], v[226:229], v[6:9]
	v_mfma_f32_16x16x32_bf16 v[2:5], v[194:197], v[226:229], v[2:5]
	v_mfma_f32_16x16x32_bf16 v[46:49], v[190:193], v[206:209], v[46:49]
	v_mfma_f32_16x16x32_bf16 v[42:45], v[198:201], v[206:209], v[42:45]
	v_mfma_f32_16x16x32_bf16 v[38:41], v[190:193], v[214:217], v[38:41]
	v_mfma_f32_16x16x32_bf16 v[34:37], v[198:201], v[214:217], v[34:37]
	v_mfma_f32_16x16x32_bf16 v[18:21], v[190:193], v[222:225], v[18:21]
	v_mfma_f32_16x16x32_bf16 v[10:13], v[198:201], v[222:225], v[10:13]
	v_mfma_f32_16x16x32_bf16 v[6:9], v[190:193], v[230:233], v[6:9]
	v_mfma_f32_16x16x32_bf16 v[2:5], v[198:201], v[230:233], v[2:5]
	s_setprio 0
	s_barrier
	s_add_i32 s68, s68, 2
	s_add_u32 s42, s42, 0x100
	s_addc_u32 s43, s43, 0
	s_add_u32 s66, s66, 0x100
	s_addc_u32 s67, s67, 0
	s_cmp_gt_u32 s68, 41
	s_cbranch_scc0 .LBB0_1898
	s_and_b64 vcc, exec, s[30:31]
	s_cbranch_vccz .LBB0_1901
	s_barrier

; #define PG8_STAGE(bufoff, gbase, voff) do { _Pragma("unroll") for (int _i = 0; _i < 2; ++_i) \
;         __builtin_amdgcn_global_load_lds((const unsigned*)((const char*)(gbase) + (voff)[_i]), (PG8_LAS unsigned*)(lds + (bufoff) + ldsw + _i * 8192), 16, 0, 0); } while (0)
; #define PG8_LDA(dst, b, h) do { _Pragma("unroll") for (int m = 0; m < 4; ++m) _Pragma("unroll") for (int k = 0; k < 2; ++k) dst[m][k] = *(const PG8_LAS bf16x8*)(lds + PG8_SA(b, h) + aoff + m * 2048 + k * 1024); } while (0)
; #define PG8_LDB(dst, b, h) do { _Pragma("unroll") for (int n = 0; n < 2; ++n) _Pragma("unroll") for (int k = 0; k < 2; ++k) dst[n][k] = *(const PG8_LAS bf16x8*)(lds + PG8_SB(b, h) + boff + n * 2048 + k * 1024); } while (0)
; #define PG8_MMA(ai, bj, At, Bt) do { __builtin_amdgcn_s_setprio(1); _Pragma("unroll") for (int m = 0; m < 4; ++m) _Pragma("unroll") for (int n = 0; n < 2; ++n) _Pragma("unroll") for (int k = 0; k < 2; ++k) \
;         acc[ai][bj][m][n] = __builtin_amdgcn_mfma_f32_16x16x32_bf16(Bt[n][k], At[m][k], acc[ai][bj][m][n], 0, 0, 0); __builtin_amdgcn_s_setprio(0); } while (0)
; #define PG8_WAIT_V(n) asm volatile("s_waitcnt vmcnt(" #n ")" ::: "memory")
; #define PG8_WAIT_L(n) asm volatile("s_waitcnt lgkmcnt(" #n ")" ::: "memory")
; #define PG8_BAR __builtin_amdgcn_s_barrier()
; #define PG8_SCHED __builtin_amdgcn_sched_barrier(0)
; template <class Epi, class Sched, bool ALIGN_EPI = false, bool SP2 = false>
; __device__ __forceinline__ void gemm_phase(PG8_LAS unsigned char* lds, const Gemm g, const Sched& S, const Epi& E) {
;     ...
;             PG8_LDB(B0, 0, 0); PG8_LDB(B1, 0, 1); PG8_SCHED; PG8_LDA(At, 0, 0); PG8_STAGE(PG8_SA(1, 1), a1 + hstep, voffA);
;             PG8_WAIT_V(8); PG8_WAIT_L(0); PG8_BAR; PG8_MMA(0, 0, At, B0); PG8_MMA(0, 1, At, B1); PG8_BAR; PG8_SCHED;
;             PG8_LDA(At, 0, 1); PG8_STAGE(PG8_SB(0, 0), b2, voffB); PG8_STAGE(PG8_SB(0, 1), b2 + hstep, voffB); PG8_STAGE(PG8_SA(0, 0), a2, voffA);
;             PG8_WAIT_V(8); PG8_WAIT_L(0); PG8_BAR; PG8_MMA(1, 0, At, B0); PG8_MMA(1, 1, At, B1); PG8_BAR; PG8_SCHED;
.LBB0_1928:
	ds_read_b128 v[150:153], v1
	ds_read_b128 v[154:157], v1 offset:1024
	ds_read_b128 v[158:161], v1 offset:2048
	ds_read_b128 v[162:165], v1 offset:3072
	ds_read_b128 v[166:169], v147
	ds_read_b128 v[170:173], v147 offset:1024
	ds_read_b128 v[174:177], v147 offset:2048
	ds_read_b128 v[178:181], v147 offset:3072
	s_add_u32 s44, s42, 0xfff50080
	s_addc_u32 s45, s43, -1
	s_cmp_eq_u32 s68, 40
	s_cselect_b32 s47, s9, s45
	s_cselect_b32 s46, s8, s44
	s_cselect_b32 s45, s41, s67
	s_cselect_b32 s44, s40, s66
	v_lshl_add_u64 v[142:143], s[42:43], 0, v[134:135]
	s_add_i32 m0, s48, 0xc000
	ds_read_b128 v[182:185], v148
	ds_read_b128 v[186:189], v148 offset:1024
	ds_read_b128 v[190:193], v148 offset:2048
	ds_read_b128 v[194:197], v148 offset:3072
	ds_read_b128 v[198:201], v148 offset:4096
	ds_read_b128 v[202:205], v148 offset:5120
	ds_read_b128 v[206:209], v148 offset:6144
	ds_read_b128 v[210:213], v148 offset:7168
	global_load_lds_dwordx4 v[142:143], off
	v_lshl_add_u64 v[142:143], s[42:43], 0, v[136:137]
	s_add_i32 m0, s48, 0xe000
	s_nop 0
	global_load_lds_dwordx4 v[142:143], off
	s_waitcnt vmcnt(8)
	s_waitcnt lgkmcnt(0)
	s_barrier
	s_setprio 1
	s_waitcnt lgkmcnt(0)
	v_mfma_f32_16x16x32_bf16 v[126:129], v[150:153], v[182:185], v[126:129]
	v_mfma_f32_16x16x32_bf16 v[122:125], v[158:161], v[182:185], v[122:125]
	v_mfma_f32_16x16x32_bf16 v[118:121], v[150:153], v[190:193], v[118:121]
	v_mfma_f32_16x16x32_bf16 v[114:117], v[158:161], v[190:193], v[114:117]
	v_mfma_f32_16x16x32_bf16 v[94:97], v[150:153], v[198:201], v[94:97]
	v_mfma_f32_16x16x32_bf16 v[90:93], v[158:161], v[198:201], v[90:93]
	v_mfma_f32_16x16x32_bf16 v[86:89], v[150:153], v[206:209], v[86:89]
	v_mfma_f32_16x16x32_bf16 v[82:85], v[158:161], v[206:209], v[82:85]
	v_mfma_f32_16x16x32_bf16 v[126:129], v[154:157], v[186:189], v[126:129]
	v_mfma_f32_16x16x32_bf16 v[122:125], v[162:165], v[186:189], v[122:125]
	v_mfma_f32_16x16x32_bf16 v[118:121], v[154:157], v[194:197], v[118:121]
	v_mfma_f32_16x16x32_bf16 v[114:117], v[162:165], v[194:197], v[114:117]
	v_mfma_f32_16x16x32_bf16 v[94:97], v[154:157], v[202:205], v[94:97]
	v_mfma_f32_16x16x32_bf16 v[90:93], v[162:165], v[202:205], v[90:93]
	v_mfma_f32_16x16x32_bf16 v[86:89], v[154:157], v[210:213], v[86:89]
	v_mfma_f32_16x16x32_bf16 v[82:85], v[162:165], v[210:213], v[82:85]
	v_mfma_f32_16x16x32_bf16 v[110:113], v[166:169], v[182:185], v[110:113]
	v_mfma_f32_16x16x32_bf16 v[106:109], v[174:177], v[182:185], v[106:109]
	v_mfma_f32_16x16x32_bf16 v[102:105], v[166:169], v[190:193], v[102:105]
	v_mfma_f32_16x16x32_bf16 v[98:101], v[174:177], v[190:193], v[98:101]
	v_mfma_f32_16x16x32_bf16 v[78:81], v[166:169], v[198:201], v[78:81]
	v_mfma_f32_16x16x32_bf16 v[74:77], v[174:177], v[198:201], v[74:77]
	v_mfma_f32_16x16x32_bf16 v[70:73], v[166:169], v[206:209], v[70:73]
	v_mfma_f32_16x16x32_bf16 v[66:69], v[174:177], v[206:209], v[66:69]
	v_mfma_f32_16x16x32_bf16 v[110:113], v[170:173], v[186:189], v[110:113]
	v_mfma_f32_16x16x32_bf16 v[106:109], v[178:181], v[186:189], v[106:109]
	v_mfma_f32_16x16x32_bf16 v[102:105], v[170:173], v[194:197], v[102:105]
	v_mfma_f32_16x16x32_bf16 v[98:101], v[178:181], v[194:197], v[98:101]
	v_mfma_f32_16x16x32_bf16 v[78:81], v[170:173], v[202:205], v[78:81]
	v_mfma_f32_16x16x32_bf16 v[74:77], v[178:181], v[202:205], v[74:77]
	v_mfma_f32_16x16x32_bf16 v[70:73], v[170:173], v[210:213], v[70:73]
	v_mfma_f32_16x16x32_bf16 v[66:69], v[178:181], v[210:213], v[66:69]
	s_setprio 0
	s_barrier
	s_add_i32 s69, s56, s19
	v_lshl_add_u64 v[142:143], s[44:45], 0, v[130:131]
	s_mov_b32 m0, s69
	ds_read_b128 v[182:185], v148 offset:16384
	ds_read_b128 v[186:189], v148 offset:17408
	ds_read_b128 v[190:193], v148 offset:18432
	ds_read_b128 v[194:197], v148 offset:19456
	ds_read_b128 v[198:201], v148 offset:20480
	ds_read_b128 v[202:205], v148 offset:21504
	ds_read_b128 v[206:209], v148 offset:22528
	ds_read_b128 v[210:213], v148 offset:23552
	global_load_lds_dwordx4 v[142:143], off
	s_add_i32 m0, s69, 0x2000
	s_add_u32 s70, s44, 0xb0000
	v_lshl_add_u64 v[214:215], s[44:45], 0, v[132:133]
	s_addc_u32 s71, s45, 0
	s_add_i32 s69, s57, s19
	global_load_lds_dwordx4 v[214:215], off
	v_lshl_add_u64 v[216:217], s[70:71], 0, v[130:131]
	s_mov_b32 m0, s69
	v_lshl_add_u64 v[218:219], s[46:47], 0, v[132:133]
	global_load_lds_dwordx4 v[216:217], off
	v_lshl_add_u64 v[216:217], s[70:71], 0, v[132:133]
	s_add_i32 m0, s69, 0x2000
	s_nop 0
	global_load_lds_dwordx4 v[216:217], off
	v_lshl_add_u64 v[216:217], s[46:47], 0, v[130:131]
	s_mov_b32 m0, s48
	s_nop 0
	global_load_lds_dwordx4 v[216:217], off
	s_mov_b32 m0, s49
	s_nop 0
	global_load_lds_dwordx4 v[218:219], off
	s_waitcnt vmcnt(8)
	s_waitcnt lgkmcnt(0)
	s_barrier
; #define PG8_STAGE(bufoff, gbase, voff) do { _Pragma("unroll") for (int _i = 0; _i < 2; ++_i) \
;         __builtin_amdgcn_global_load_lds((const unsigned*)((const char*)(gbase) + (voff)[_i]), (PG8_LAS unsigned*)(lds + (bufoff) + ldsw + _i * 8192), 16, 0, 0); } while (0)
; #define PG8_LDA(dst, b, h) do { _Pragma("unroll") for (int m = 0; m < 4; ++m) _Pragma("unroll") for (int k = 0; k < 2; ++k) dst[m][k] = *(const PG8_LAS bf16x8*)(lds + PG8_SA(b, h) + aoff + m * 2048 + k * 1024); } while (0)
; #define PG8_LDB(dst, b, h) do { _Pragma("unroll") for (int n = 0; n < 2; ++n) _Pragma("unroll") for (int k = 0; k < 2; ++k) dst[n][k] = *(const PG8_LAS bf16x8*)(lds + PG8_SB(b, h) + boff + n * 2048 + k * 1024); } while (0)
; #define PG8_MMA(ai, bj, At, Bt) do { __builtin_amdgcn_s_setprio(1); _Pragma("unroll") for (int m = 0; m < 4; ++m) _Pragma("unroll") for (int n = 0; n < 2; ++n) _Pragma("unroll") for (int k = 0; k < 2; ++k) \
;         acc[ai][bj][m][n] = __builtin_amdgcn_mfma_f32_16x16x32_bf16(Bt[n][k], At[m][k], acc[ai][bj][m][n], 0, 0, 0); __builtin_amdgcn_s_setprio(0); } while (0)
; #define PG8_WAIT_V(n) asm volatile("s_waitcnt vmcnt(" #n ")" ::: "memory")
; #define PG8_WAIT_L(n) asm volatile("s_waitcnt lgkmcnt(" #n ")" ::: "memory")
; #define PG8_BAR __builtin_amdgcn_s_barrier()
; #define PG8_SCHED __builtin_amdgcn_sched_barrier(0)
; template <class Epi, class Sched, bool ALIGN_EPI = false, bool SP2 = false>
; __device__ __forceinline__ void gemm_phase(PG8_LAS unsigned char* lds, const Gemm g, const Sched& S, const Epi& E) {
;     ...
;             PG8_WAIT_V(8); PG8_WAIT_L(0); PG8_BAR; PG8_MMA(1, 0, At, B0); PG8_MMA(1, 1, At, B1); PG8_BAR; PG8_SCHED;
;             PG8_LDB(B0, 1, 0); PG8_LDB(B1, 1, 1); PG8_SCHED; PG8_LDA(At, 1, 0); PG8_STAGE(PG8_SA(0, 1), a2 + hstep, voffA);
;             PG8_WAIT_V(8); PG8_WAIT_L(0); PG8_BAR; PG8_MMA(0, 0, At, B0); PG8_MMA(0, 1, At, B1); PG8_BAR; PG8_SCHED;
	s_setprio 1
	s_waitcnt lgkmcnt(0)
	v_mfma_f32_16x16x32_bf16 v[62:65], v[150:153], v[182:185], v[62:65]
	v_mfma_f32_16x16x32_bf16 v[58:61], v[158:161], v[182:185], v[58:61]
	v_mfma_f32_16x16x32_bf16 v[54:57], v[150:153], v[190:193], v[54:57]
	v_mfma_f32_16x16x32_bf16 v[50:53], v[158:161], v[190:193], v[50:53]
	v_mfma_f32_16x16x32_bf16 v[30:33], v[150:153], v[198:201], v[30:33]
	v_mfma_f32_16x16x32_bf16 v[26:29], v[158:161], v[198:201], v[26:29]
	v_mfma_f32_16x16x32_bf16 v[22:25], v[150:153], v[206:209], v[22:25]
	v_mfma_f32_16x16x32_bf16 v[14:17], v[158:161], v[206:209], v[14:17]
	v_mfma_f32_16x16x32_bf16 v[62:65], v[154:157], v[186:189], v[62:65]
	v_mfma_f32_16x16x32_bf16 v[58:61], v[162:165], v[186:189], v[58:61]
	v_mfma_f32_16x16x32_bf16 v[54:57], v[154:157], v[194:197], v[54:57]
	v_mfma_f32_16x16x32_bf16 v[50:53], v[162:165], v[194:197], v[50:53]
	v_mfma_f32_16x16x32_bf16 v[30:33], v[154:157], v[202:205], v[30:33]
	v_mfma_f32_16x16x32_bf16 v[26:29], v[162:165], v[202:205], v[26:29]
	v_mfma_f32_16x16x32_bf16 v[22:25], v[154:157], v[210:213], v[22:25]
	v_mfma_f32_16x16x32_bf16 v[14:17], v[162:165], v[210:213], v[14:17]
	v_mfma_f32_16x16x32_bf16 v[46:49], v[166:169], v[182:185], v[46:49]
	v_mfma_f32_16x16x32_bf16 v[42:45], v[174:177], v[182:185], v[42:45]
	v_mfma_f32_16x16x32_bf16 v[38:41], v[166:169], v[190:193], v[38:41]
	v_mfma_f32_16x16x32_bf16 v[34:37], v[174:177], v[190:193], v[34:37]
	v_mfma_f32_16x16x32_bf16 v[18:21], v[166:169], v[198:201], v[18:21]
	v_mfma_f32_16x16x32_bf16 v[10:13], v[174:177], v[198:201], v[10:13]
	v_mfma_f32_16x16x32_bf16 v[6:9], v[166:169], v[206:209], v[6:9]
	v_mfma_f32_16x16x32_bf16 v[2:5], v[174:177], v[206:209], v[2:5]
	v_mfma_f32_16x16x32_bf16 v[46:49], v[170:173], v[186:189], v[46:49]
	v_mfma_f32_16x16x32_bf16 v[42:45], v[178:181], v[186:189], v[42:45]
	v_mfma_f32_16x16x32_bf16 v[38:41], v[170:173], v[194:197], v[38:41]
	v_mfma_f32_16x16x32_bf16 v[34:37], v[178:181], v[194:197], v[34:37]
	v_mfma_f32_16x16x32_bf16 v[18:21], v[170:173], v[202:205], v[18:21]
	v_mfma_f32_16x16x32_bf16 v[10:13], v[178:181], v[202:205], v[10:13]
	v_mfma_f32_16x16x32_bf16 v[6:9], v[170:173], v[210:213], v[6:9]
	v_mfma_f32_16x16x32_bf16 v[2:5], v[178:181], v[210:213], v[2:5]
	s_setprio 0
	s_barrier
	s_add_i32 s69, 0, 0x18000
	v_add_u32_e32 v149, s69, v145
	s_add_i32 s70, 0, 0x1c000
	ds_read_b128 v[150:153], v149
	ds_read_b128 v[154:157], v149 offset:1024
	ds_read_b128 v[158:161], v149 offset:2048
	ds_read_b128 v[162:165], v149 offset:3072
	v_add_u32_e32 v149, s70, v145
	ds_read_b128 v[166:169], v149
	ds_read_b128 v[170:173], v149 offset:1024
	ds_read_b128 v[174:177], v149 offset:2048
	ds_read_b128 v[178:181], v149 offset:3072
	s_add_u32 s46, s46, 0xb0000
	s_addc_u32 s47, s47, 0
	s_mov_b32 m0, s50
	v_lshl_add_u64 v[220:221], s[46:47], 0, v[130:131]
	ds_read_b128 v[182:185], v148 offset:32768
	ds_read_b128 v[186:189], v148 offset:33792
	ds_read_b128 v[190:193], v148 offset:34816
	ds_read_b128 v[194:197], v148 offset:35840
	ds_read_b128 v[198:201], v148 offset:36864
	ds_read_b128 v[202:205], v148 offset:37888
	ds_read_b128 v[206:209], v148 offset:38912
	ds_read_b128 v[210:213], v148 offset:39936
	global_load_lds_dwordx4 v[220:221], off
	v_lshl_add_u64 v[220:221], s[46:47], 0, v[132:133]
	s_mov_b32 m0, s51
	s_nop 0
	global_load_lds_dwordx4 v[220:221], off
	s_waitcnt vmcnt(8)
	s_waitcnt lgkmcnt(0)
	s_barrier
	s_setprio 1
	s_waitcnt lgkmcnt(0)
	v_mfma_f32_16x16x32_bf16 v[126:129], v[150:153], v[182:185], v[126:129]
	v_mfma_f32_16x16x32_bf16 v[122:125], v[158:161], v[182:185], v[122:125]
	v_mfma_f32_16x16x32_bf16 v[118:121], v[150:153], v[190:193], v[118:121]
	v_mfma_f32_16x16x32_bf16 v[114:117], v[158:161], v[190:193], v[114:117]
	v_mfma_f32_16x16x32_bf16 v[94:97], v[150:153], v[198:201], v[94:97]
	v_mfma_f32_16x16x32_bf16 v[90:93], v[158:161], v[198:201], v[90:93]
	v_mfma_f32_16x16x32_bf16 v[86:89], v[150:153], v[206:209], v[86:89]
	v_mfma_f32_16x16x32_bf16 v[82:85], v[158:161], v[206:209], v[82:85]
	v_mfma_f32_16x16x32_bf16 v[126:129], v[154:157], v[186:189], v[126:129]
	v_mfma_f32_16x16x32_bf16 v[122:125], v[162:165], v[186:189], v[122:125]
	v_mfma_f32_16x16x32_bf16 v[118:121], v[154:157], v[194:197], v[118:121]
	v_mfma_f32_16x16x32_bf16 v[114:117], v[162:165], v[194:197], v[114:117]
	v_mfma_f32_16x16x32_bf16 v[94:97], v[154:157], v[202:205], v[94:97]
	v_mfma_f32_16x16x32_bf16 v[90:93], v[162:165], v[202:205], v[90:93]
	v_mfma_f32_16x16x32_bf16 v[86:89], v[154:157], v[210:213], v[86:89]
	v_mfma_f32_16x16x32_bf16 v[82:85], v[162:165], v[210:213], v[82:85]
	v_mfma_f32_16x16x32_bf16 v[110:113], v[166:169], v[182:185], v[110:113]
	v_mfma_f32_16x16x32_bf16 v[106:109], v[174:177], v[182:185], v[106:109]
	v_mfma_f32_16x16x32_bf16 v[102:105], v[166:169], v[190:193], v[102:105]
	v_mfma_f32_16x16x32_bf16 v[98:101], v[174:177], v[190:193], v[98:101]
	v_mfma_f32_16x16x32_bf16 v[78:81], v[166:169], v[198:201], v[78:81]
	v_mfma_f32_16x16x32_bf16 v[74:77], v[174:177], v[198:201], v[74:77]
	v_mfma_f32_16x16x32_bf16 v[70:73], v[166:169], v[206:209], v[70:73]
	v_mfma_f32_16x16x32_bf16 v[66:69], v[174:177], v[206:209], v[66:69]
	v_mfma_f32_16x16x32_bf16 v[110:113], v[170:173], v[186:189], v[110:113]
	v_mfma_f32_16x16x32_bf16 v[106:109], v[178:181], v[186:189], v[106:109]
	v_mfma_f32_16x16x32_bf16 v[102:105], v[170:173], v[194:197], v[102:105]
	v_mfma_f32_16x16x32_bf16 v[98:101], v[178:181], v[194:197], v[98:101]
	v_mfma_f32_16x16x32_bf16 v[78:81], v[170:173], v[202:205], v[78:81]
	v_mfma_f32_16x16x32_bf16 v[74:77], v[178:181], v[202:205], v[74:77]
	v_mfma_f32_16x16x32_bf16 v[70:73], v[170:173], v[210:213], v[70:73]
	v_mfma_f32_16x16x32_bf16 v[66:69], v[178:181], v[210:213], v[66:69]
	s_setprio 0
	s_barrier
; #define PG8_STAGE(bufoff, gbase, voff) do { _Pragma("unroll") for (int _i = 0; _i < 2; ++_i) \
;         __builtin_amdgcn_global_load_lds((const unsigned*)((const char*)(gbase) + (voff)[_i]), (PG8_LAS unsigned*)(lds + (bufoff) + ldsw + _i * 8192), 16, 0, 0); } while (0)
; #define PG8_LDA(dst, b, h) do { _Pragma("unroll") for (int m = 0; m < 4; ++m) _Pragma("unroll") for (int k = 0; k < 2; ++k) dst[m][k] = *(const PG8_LAS bf16x8*)(lds + PG8_SA(b, h) + aoff + m * 2048 + k * 1024); } while (0)
; #define PG8_MMA(ai, bj, At, Bt) do { __builtin_amdgcn_s_setprio(1); _Pragma("unroll") for (int m = 0; m < 4; ++m) _Pragma("unroll") for (int n = 0; n < 2; ++n) _Pragma("unroll") for (int k = 0; k < 2; ++k) \
;         acc[ai][bj][m][n] = __builtin_amdgcn_mfma_f32_16x16x32_bf16(Bt[n][k], At[m][k], acc[ai][bj][m][n], 0, 0, 0); __builtin_amdgcn_s_setprio(0); } while (0)
; #define PG8_WAIT_V(n) asm volatile("s_waitcnt vmcnt(" #n ")" ::: "memory")
; #define PG8_WAIT_L(n) asm volatile("s_waitcnt lgkmcnt(" #n ")" ::: "memory")
; #define PG8_BAR __builtin_amdgcn_s_barrier()
; #define PG8_SCHED __builtin_amdgcn_sched_barrier(0)
; template <class Epi, class Sched, bool ALIGN_EPI = false, bool SP2 = false>
; __device__ __forceinline__ void gemm_phase(PG8_LAS unsigned char* lds, const Gemm g, const Sched& S, const Epi& E) {
;     ...
;             PG8_LDA(At, 1, 1); PG8_STAGE(PG8_SB(1, 0), b3, voffB); PG8_STAGE(PG8_SB(1, 1), b3 + hstep, voffB); PG8_STAGE(PG8_SA(1, 0), a3, voffA);
;             PG8_WAIT_V(8); PG8_WAIT_L(0); PG8_BAR; PG8_MMA(1, 0, At, B0); PG8_MMA(1, 1, At, B1); PG8_BAR; PG8_SCHED;
	s_add_i32 s46, s69, s19
	v_lshl_add_u64 v[142:143], v[142:143], 0, s[16:17]
	s_mov_b32 m0, s46
	ds_read_b128 v[182:185], v148 offset:49152
	ds_read_b128 v[186:189], v148 offset:50176
	ds_read_b128 v[190:193], v148 offset:51200
	ds_read_b128 v[194:197], v148 offset:52224
	ds_read_b128 v[198:201], v148 offset:53248
	ds_read_b128 v[202:205], v148 offset:54272
	ds_read_b128 v[206:209], v148 offset:55296
	ds_read_b128 v[210:213], v148 offset:56320
	global_load_lds_dwordx4 v[142:143], off
	s_add_i32 m0, s46, 0x2000
	s_add_u32 s44, s44, 0xb0080
	v_lshl_add_u64 v[142:143], v[214:215], 0, s[16:17]
	s_addc_u32 s45, s45, 0
	s_add_i32 s46, s70, s19
	global_load_lds_dwordx4 v[142:143], off
	v_lshl_add_u64 v[142:143], s[44:45], 0, v[130:131]
	s_mov_b32 m0, s46
	s_nop 0
	global_load_lds_dwordx4 v[142:143], off
	v_lshl_add_u64 v[142:143], s[44:45], 0, v[132:133]
	s_add_i32 m0, s46, 0x2000
	s_nop 0
	global_load_lds_dwordx4 v[142:143], off
	v_lshl_add_u64 v[142:143], v[216:217], 0, s[16:17]
	s_mov_b32 m0, s53
	s_nop 0
	global_load_lds_dwordx4 v[142:143], off
	v_lshl_add_u64 v[142:143], v[218:219], 0, s[16:17]
	s_mov_b32 m0, s54
	s_nop 0
	global_load_lds_dwordx4 v[142:143], off
	s_waitcnt vmcnt(8)
	s_waitcnt lgkmcnt(0)
	s_barrier
	s_setprio 1
	s_waitcnt lgkmcnt(0)
	v_mfma_f32_16x16x32_bf16 v[62:65], v[150:153], v[182:185], v[62:65]
	v_mfma_f32_16x16x32_bf16 v[58:61], v[158:161], v[182:185], v[58:61]
	v_mfma_f32_16x16x32_bf16 v[54:57], v[150:153], v[190:193], v[54:57]
	v_mfma_f32_16x16x32_bf16 v[50:53], v[158:161], v[190:193], v[50:53]
	v_mfma_f32_16x16x32_bf16 v[30:33], v[150:153], v[198:201], v[30:33]
	v_mfma_f32_16x16x32_bf16 v[26:29], v[158:161], v[198:201], v[26:29]
	v_mfma_f32_16x16x32_bf16 v[22:25], v[150:153], v[206:209], v[22:25]
	v_mfma_f32_16x16x32_bf16 v[14:17], v[158:161], v[206:209], v[14:17]
	v_mfma_f32_16x16x32_bf16 v[62:65], v[154:157], v[186:189], v[62:65]
	v_mfma_f32_16x16x32_bf16 v[58:61], v[162:165], v[186:189], v[58:61]
	v_mfma_f32_16x16x32_bf16 v[54:57], v[154:157], v[194:197], v[54:57]
	v_mfma_f32_16x16x32_bf16 v[50:53], v[162:165], v[194:197], v[50:53]
	v_mfma_f32_16x16x32_bf16 v[30:33], v[154:157], v[202:205], v[30:33]
	v_mfma_f32_16x16x32_bf16 v[26:29], v[162:165], v[202:205], v[26:29]
	v_mfma_f32_16x16x32_bf16 v[22:25], v[154:157], v[210:213], v[22:25]
	v_mfma_f32_16x16x32_bf16 v[14:17], v[162:165], v[210:213], v[14:17]
	v_mfma_f32_16x16x32_bf16 v[46:49], v[166:169], v[182:185], v[46:49]
	v_mfma_f32_16x16x32_bf16 v[42:45], v[174:177], v[182:185], v[42:45]
	v_mfma_f32_16x16x32_bf16 v[38:41], v[166:169], v[190:193], v[38:41]
	v_mfma_f32_16x16x32_bf16 v[34:37], v[174:177], v[190:193], v[34:37]
	v_mfma_f32_16x16x32_bf16 v[18:21], v[166:169], v[198:201], v[18:21]
	v_mfma_f32_16x16x32_bf16 v[10:13], v[174:177], v[198:201], v[10:13]
	v_mfma_f32_16x16x32_bf16 v[6:9], v[166:169], v[206:209], v[6:9]
	v_mfma_f32_16x16x32_bf16 v[2:5], v[174:177], v[206:209], v[2:5]
	v_mfma_f32_16x16x32_bf16 v[46:49], v[170:173], v[186:189], v[46:49]
	v_mfma_f32_16x16x32_bf16 v[42:45], v[178:181], v[186:189], v[42:45]
	v_mfma_f32_16x16x32_bf16 v[38:41], v[170:173], v[194:197], v[38:41]
	v_mfma_f32_16x16x32_bf16 v[34:37], v[178:181], v[194:197], v[34:37]
	v_mfma_f32_16x16x32_bf16 v[18:21], v[170:173], v[202:205], v[18:21]
	v_mfma_f32_16x16x32_bf16 v[10:13], v[178:181], v[202:205], v[10:13]
	v_mfma_f32_16x16x32_bf16 v[6:9], v[170:173], v[210:213], v[6:9]
	v_mfma_f32_16x16x32_bf16 v[2:5], v[178:181], v[210:213], v[2:5]
	s_setprio 0
	s_barrier
	s_add_i32 s68, s68, 2
	s_add_u32 s42, s42, 0x100
	s_addc_u32 s43, s43, 0
	s_add_u32 s66, s66, 0x100
	s_addc_u32 s67, s67, 0
	s_cmp_gt_u32 s68, 41
	s_cbranch_scc0 .LBB0_1928
	s_and_b64 vcc, exec, s[30:31]
	s_cbranch_vccz .LBB0_1931
	s_barrier
